# uniform 4-piece LDS-DMA issue per load segment: As[1][0] staging pair moved from SP2(t+1) to the next iteration's first segment (+ loop-exit staging for the next unit), SP2(t+1) wait vmcnt(6)
# speedup vs baseline: 1.0022x; 1.0022x over previous
.LBB0_249:
	ds_read_b128 v[152:155], v146
	ds_read_b128 v[156:159], v146 offset:1024
	ds_read_b128 v[160:163], v146 offset:2048
	ds_read_b128 v[164:167], v146 offset:3072
	ds_read_b128 v[168:171], v147
	ds_read_b128 v[172:175], v147 offset:1024
	ds_read_b128 v[176:179], v147 offset:2048
	ds_read_b128 v[180:183], v147 offset:3072
	s_add_u32 s16, s70, 0xfff00080
	s_addc_u32 s17, s71, -1
	s_cmp_eq_u32 s15, 60
	s_cselect_b32 s75, s47, s17
	s_cselect_b32 s74, s93, s16
	s_cselect_b32 s67, s4, s14
	s_cselect_b32 s66, s94, s57
	s_cmp_eq_u32 s15, 0
	s_cbranch_scc1 .Lrb2_skip_7701
	s_mov_b32 m0, s65
	s_nop 0
	global_load_lds_dwordx4 v136, s[100:101]
	s_mov_b32 m0, s76
	s_nop 0
	global_load_lds_dwordx4 v132, s[100:101]
.Lrb2_skip_7701:
	s_mov_b32 m0, s78
	ds_read_b128 v[184:187], v148
	ds_read_b128 v[188:191], v148 offset:1024
	ds_read_b128 v[192:195], v148 offset:2048
	ds_read_b128 v[196:199], v148 offset:3072
	ds_read_b128 v[200:203], v148 offset:4096
	ds_read_b128 v[204:207], v148 offset:5120
	ds_read_b128 v[208:211], v148 offset:6144
	ds_read_b128 v[212:215], v148 offset:7168
	global_load_lds_dwordx4 v138, s[70:71]
	s_mov_b32 m0, s79
	s_nop 0
	global_load_lds_dwordx4 v140, s[70:71]
	s_waitcnt vmcnt(8)
	s_waitcnt lgkmcnt(0)
	s_setprio 1
	s_barrier
	v_mfma_f32_16x16x32_bf16 v[122:125], v[152:155], v[184:187], v[122:125]
	v_mfma_f32_16x16x32_bf16 v[114:117], v[160:163], v[184:187], v[114:117]
	v_mfma_f32_16x16x32_bf16 v[106:109], v[152:155], v[192:195], v[106:109]
	v_mfma_f32_16x16x32_bf16 v[98:101], v[160:163], v[192:195], v[98:101]
	v_mfma_f32_16x16x32_bf16 v[90:93], v[152:155], v[200:203], v[90:93]
	v_mfma_f32_16x16x32_bf16 v[82:85], v[160:163], v[200:203], v[82:85]
	v_mfma_f32_16x16x32_bf16 v[74:77], v[152:155], v[208:211], v[74:77]
	v_mfma_f32_16x16x32_bf16 v[58:61], v[160:163], v[208:211], v[58:61]
	v_mfma_f32_16x16x32_bf16 v[122:125], v[156:159], v[188:191], v[122:125]
	v_mfma_f32_16x16x32_bf16 v[114:117], v[164:167], v[188:191], v[114:117]
	v_mfma_f32_16x16x32_bf16 v[106:109], v[156:159], v[196:199], v[106:109]
	v_mfma_f32_16x16x32_bf16 v[98:101], v[164:167], v[196:199], v[98:101]
	v_mfma_f32_16x16x32_bf16 v[90:93], v[156:159], v[204:207], v[90:93]
	v_mfma_f32_16x16x32_bf16 v[82:85], v[164:167], v[204:207], v[82:85]
	v_mfma_f32_16x16x32_bf16 v[74:77], v[156:159], v[212:215], v[74:77]
	v_mfma_f32_16x16x32_bf16 v[58:61], v[164:167], v[212:215], v[58:61]
	s_setprio 0
	s_setprio 1
	v_mfma_f32_16x16x32_bf16 v[126:129], v[168:171], v[184:187], v[126:129]
	v_mfma_f32_16x16x32_bf16 v[118:121], v[176:179], v[184:187], v[118:121]
	v_mfma_f32_16x16x32_bf16 v[110:113], v[168:171], v[192:195], v[110:113]
	v_mfma_f32_16x16x32_bf16 v[102:105], v[176:179], v[192:195], v[102:105]
	v_mfma_f32_16x16x32_bf16 v[94:97], v[168:171], v[200:203], v[94:97]
	v_mfma_f32_16x16x32_bf16 v[86:89], v[176:179], v[200:203], v[86:89]
	v_mfma_f32_16x16x32_bf16 v[78:81], v[168:171], v[208:211], v[78:81]
	v_mfma_f32_16x16x32_bf16 v[66:69], v[176:179], v[208:211], v[66:69]
	v_mfma_f32_16x16x32_bf16 v[126:129], v[172:175], v[188:191], v[126:129]
	v_mfma_f32_16x16x32_bf16 v[118:121], v[180:183], v[188:191], v[118:121]
	v_mfma_f32_16x16x32_bf16 v[110:113], v[172:175], v[196:199], v[110:113]
	v_mfma_f32_16x16x32_bf16 v[102:105], v[180:183], v[196:199], v[102:105]
	v_mfma_f32_16x16x32_bf16 v[94:97], v[172:175], v[204:207], v[94:97]
	v_mfma_f32_16x16x32_bf16 v[86:89], v[180:183], v[204:207], v[86:89]
	v_mfma_f32_16x16x32_bf16 v[78:81], v[172:175], v[212:215], v[78:81]
	v_mfma_f32_16x16x32_bf16 v[66:69], v[180:183], v[212:215], v[66:69]
	s_barrier
	s_setprio 0
	s_mov_b32 m0, s81
	s_mov_b64 s[98:99], s[66:67]
	s_add_u32 s16, s66, 0x100000
	ds_read_b128 v[184:187], v148 offset:16384
	ds_read_b128 v[188:191], v148 offset:17408
	ds_read_b128 v[192:195], v148 offset:18432
	ds_read_b128 v[196:199], v148 offset:19456
	ds_read_b128 v[200:203], v148 offset:20480
	ds_read_b128 v[204:207], v148 offset:21504
	ds_read_b128 v[208:211], v148 offset:22528
	ds_read_b128 v[212:215], v148 offset:23552
	global_load_lds_dwordx4 v134, s[66:67]
	s_mov_b32 m0, s82
	s_addc_u32 s17, s67, 0
	global_load_lds_dwordx4 v130, s[66:67]
	s_mov_b32 m0, s83
	s_mov_b64 s[100:101], s[74:75]
	global_load_lds_dwordx4 v134, s[16:17]
	s_mov_b32 m0, s86
	s_nop 0
	global_load_lds_dwordx4 v130, s[16:17]
	s_waitcnt vmcnt(6)
	s_waitcnt lgkmcnt(0)
	s_setprio 1
	s_barrier
	v_mfma_f32_16x16x32_bf16 v[62:65], v[152:155], v[184:187], v[62:65]
	v_mfma_f32_16x16x32_bf16 v[50:53], v[160:163], v[184:187], v[50:53]
	v_mfma_f32_16x16x32_bf16 v[42:45], v[152:155], v[192:195], v[42:45]
	v_mfma_f32_16x16x32_bf16 v[34:37], v[160:163], v[192:195], v[34:37]
	v_mfma_f32_16x16x32_bf16 v[26:29], v[152:155], v[200:203], v[26:29]
	v_mfma_f32_16x16x32_bf16 v[18:21], v[160:163], v[200:203], v[18:21]
	v_mfma_f32_16x16x32_bf16 v[10:13], v[152:155], v[208:211], v[10:13]
	v_mfma_f32_16x16x32_bf16 v[2:5], v[160:163], v[208:211], v[2:5]
	v_mfma_f32_16x16x32_bf16 v[62:65], v[156:159], v[188:191], v[62:65]
	v_mfma_f32_16x16x32_bf16 v[50:53], v[164:167], v[188:191], v[50:53]
	v_mfma_f32_16x16x32_bf16 v[42:45], v[156:159], v[196:199], v[42:45]
	v_mfma_f32_16x16x32_bf16 v[34:37], v[164:167], v[196:199], v[34:37]
	v_mfma_f32_16x16x32_bf16 v[26:29], v[156:159], v[204:207], v[26:29]
	v_mfma_f32_16x16x32_bf16 v[18:21], v[164:167], v[204:207], v[18:21]
	v_mfma_f32_16x16x32_bf16 v[10:13], v[156:159], v[212:215], v[10:13]
	v_mfma_f32_16x16x32_bf16 v[2:5], v[164:167], v[212:215], v[2:5]
	s_setprio 0
	s_setprio 1
	v_mfma_f32_16x16x32_bf16 v[70:73], v[168:171], v[184:187], v[70:73]
	v_mfma_f32_16x16x32_bf16 v[54:57], v[176:179], v[184:187], v[54:57]
	v_mfma_f32_16x16x32_bf16 v[46:49], v[168:171], v[192:195], v[46:49]
	v_mfma_f32_16x16x32_bf16 v[38:41], v[176:179], v[192:195], v[38:41]
	v_mfma_f32_16x16x32_bf16 v[30:33], v[168:171], v[200:203], v[30:33]
	v_mfma_f32_16x16x32_bf16 v[22:25], v[176:179], v[200:203], v[22:25]
	v_mfma_f32_16x16x32_bf16 v[14:17], v[168:171], v[208:211], v[14:17]
	v_mfma_f32_16x16x32_bf16 v[6:9], v[176:179], v[208:211], v[6:9]
	v_mfma_f32_16x16x32_bf16 v[70:73], v[172:175], v[188:191], v[70:73]
	v_mfma_f32_16x16x32_bf16 v[54:57], v[180:183], v[188:191], v[54:57]
	v_mfma_f32_16x16x32_bf16 v[46:49], v[172:175], v[196:199], v[46:49]
	v_mfma_f32_16x16x32_bf16 v[38:41], v[180:183], v[196:199], v[38:41]
	v_mfma_f32_16x16x32_bf16 v[30:33], v[172:175], v[204:207], v[30:33]
	v_mfma_f32_16x16x32_bf16 v[22:25], v[180:183], v[204:207], v[22:25]
	v_mfma_f32_16x16x32_bf16 v[14:17], v[172:175], v[212:215], v[14:17]
	v_mfma_f32_16x16x32_bf16 v[6:9], v[180:183], v[212:215], v[6:9]
	s_barrier
; #define PG8_BAR __builtin_amdgcn_s_barrier()
;     ...
;         for (int t = 2; t < nt; t += 2) PG8_KITER(t);
;         if constexpr (ALIGN_EPI) { if (wr == 0) PG8_BAR; }
	s_setprio 0
	ds_read_b128 v[152:155], v149
	ds_read_b128 v[156:159], v149 offset:1024
	ds_read_b128 v[160:163], v149 offset:2048
	ds_read_b128 v[164:167], v149 offset:3072
	ds_read_b128 v[168:171], v150
	ds_read_b128 v[172:175], v150 offset:1024
	ds_read_b128 v[176:179], v150 offset:2048
	ds_read_b128 v[180:183], v150 offset:3072
	s_add_u32 s16, s74, 0x100000
	s_addc_u32 s17, s75, 0
	s_mov_b32 m0, s29
	s_nop 0
	global_load_lds_dwordx4 v136, s[100:101]
	s_mov_b32 m0, s33
	s_nop 0
	global_load_lds_dwordx4 v132, s[100:101]
	s_mov_b32 m0, s58
	ds_read_b128 v[184:187], v148 offset:32768
	ds_read_b128 v[188:191], v148 offset:33792
	ds_read_b128 v[192:195], v148 offset:34816
	ds_read_b128 v[196:199], v148 offset:35840
	ds_read_b128 v[200:203], v148 offset:36864
	ds_read_b128 v[204:207], v148 offset:37888
	ds_read_b128 v[208:211], v148 offset:38912
	ds_read_b128 v[212:215], v148 offset:39936
	global_load_lds_dwordx4 v136, s[16:17]
	s_mov_b32 m0, s59
	s_nop 0
	global_load_lds_dwordx4 v132, s[16:17]
	s_waitcnt vmcnt(8)
	s_waitcnt lgkmcnt(0)
	s_setprio 1
	s_barrier
	v_mfma_f32_16x16x32_bf16 v[122:125], v[152:155], v[184:187], v[122:125]
	v_mfma_f32_16x16x32_bf16 v[114:117], v[160:163], v[184:187], v[114:117]
	v_mfma_f32_16x16x32_bf16 v[106:109], v[152:155], v[192:195], v[106:109]
	v_mfma_f32_16x16x32_bf16 v[98:101], v[160:163], v[192:195], v[98:101]
	v_mfma_f32_16x16x32_bf16 v[90:93], v[152:155], v[200:203], v[90:93]
	v_mfma_f32_16x16x32_bf16 v[82:85], v[160:163], v[200:203], v[82:85]
	v_mfma_f32_16x16x32_bf16 v[74:77], v[152:155], v[208:211], v[74:77]
	v_mfma_f32_16x16x32_bf16 v[58:61], v[160:163], v[208:211], v[58:61]
	v_mfma_f32_16x16x32_bf16 v[122:125], v[156:159], v[188:191], v[122:125]
	v_mfma_f32_16x16x32_bf16 v[114:117], v[164:167], v[188:191], v[114:117]
	v_mfma_f32_16x16x32_bf16 v[106:109], v[156:159], v[196:199], v[106:109]
	v_mfma_f32_16x16x32_bf16 v[98:101], v[164:167], v[196:199], v[98:101]
	v_mfma_f32_16x16x32_bf16 v[90:93], v[156:159], v[204:207], v[90:93]
	v_mfma_f32_16x16x32_bf16 v[82:85], v[164:167], v[204:207], v[82:85]
	v_mfma_f32_16x16x32_bf16 v[74:77], v[156:159], v[212:215], v[74:77]
	v_mfma_f32_16x16x32_bf16 v[58:61], v[164:167], v[212:215], v[58:61]
	s_setprio 0
	s_setprio 1
	v_mfma_f32_16x16x32_bf16 v[126:129], v[168:171], v[184:187], v[126:129]
	v_mfma_f32_16x16x32_bf16 v[118:121], v[176:179], v[184:187], v[118:121]
	v_mfma_f32_16x16x32_bf16 v[110:113], v[168:171], v[192:195], v[110:113]
	v_mfma_f32_16x16x32_bf16 v[102:105], v[176:179], v[192:195], v[102:105]
	v_mfma_f32_16x16x32_bf16 v[94:97], v[168:171], v[200:203], v[94:97]
	v_mfma_f32_16x16x32_bf16 v[86:89], v[176:179], v[200:203], v[86:89]
	v_mfma_f32_16x16x32_bf16 v[78:81], v[168:171], v[208:211], v[78:81]
	v_mfma_f32_16x16x32_bf16 v[66:69], v[176:179], v[208:211], v[66:69]
	v_mfma_f32_16x16x32_bf16 v[126:129], v[172:175], v[188:191], v[126:129]
	v_mfma_f32_16x16x32_bf16 v[118:121], v[180:183], v[188:191], v[118:121]
	v_mfma_f32_16x16x32_bf16 v[110:113], v[172:175], v[196:199], v[110:113]
	v_mfma_f32_16x16x32_bf16 v[102:105], v[180:183], v[196:199], v[102:105]
	v_mfma_f32_16x16x32_bf16 v[94:97], v[172:175], v[204:207], v[94:97]
	v_mfma_f32_16x16x32_bf16 v[86:89], v[180:183], v[204:207], v[86:89]
	v_mfma_f32_16x16x32_bf16 v[78:81], v[172:175], v[212:215], v[78:81]
	v_mfma_f32_16x16x32_bf16 v[66:69], v[180:183], v[212:215], v[66:69]
	s_barrier
	s_setprio 0
	s_mov_b32 m0, s87
	s_add_u32 s98, s98, 0x80
	s_addc_u32 s99, s99, 0
	s_add_u32 s100, s100, 0x80
	s_addc_u32 s101, s101, 0
	s_add_u32 s16, s66, 0x100080
	ds_read_b128 v[184:187], v148 offset:49152
	ds_read_b128 v[188:191], v148 offset:50176
	ds_read_b128 v[192:195], v148 offset:51200
	ds_read_b128 v[196:199], v148 offset:52224
	ds_read_b128 v[200:203], v148 offset:53248
	ds_read_b128 v[204:207], v148 offset:54272
	ds_read_b128 v[208:211], v148 offset:55296
	ds_read_b128 v[212:215], v148 offset:56320
	global_load_lds_dwordx4 v134, s[98:99]
	s_mov_b32 m0, s88
	s_addc_u32 s17, s67, 0
	global_load_lds_dwordx4 v130, s[98:99]
	s_mov_b32 m0, s89
	s_nop 0
	global_load_lds_dwordx4 v134, s[16:17]
	s_mov_b32 m0, s56
	s_nop 0
	global_load_lds_dwordx4 v130, s[16:17]
	s_waitcnt vmcnt(6)
	s_waitcnt lgkmcnt(0)
	s_setprio 1
	s_barrier
	v_mfma_f32_16x16x32_bf16 v[62:65], v[152:155], v[184:187], v[62:65]
	v_mfma_f32_16x16x32_bf16 v[50:53], v[160:163], v[184:187], v[50:53]
	v_mfma_f32_16x16x32_bf16 v[42:45], v[152:155], v[192:195], v[42:45]
	v_mfma_f32_16x16x32_bf16 v[34:37], v[160:163], v[192:195], v[34:37]
	v_mfma_f32_16x16x32_bf16 v[26:29], v[152:155], v[200:203], v[26:29]
	v_mfma_f32_16x16x32_bf16 v[18:21], v[160:163], v[200:203], v[18:21]
	v_mfma_f32_16x16x32_bf16 v[10:13], v[152:155], v[208:211], v[10:13]
	v_mfma_f32_16x16x32_bf16 v[2:5], v[160:163], v[208:211], v[2:5]
	v_mfma_f32_16x16x32_bf16 v[62:65], v[156:159], v[188:191], v[62:65]
	v_mfma_f32_16x16x32_bf16 v[50:53], v[164:167], v[188:191], v[50:53]
	v_mfma_f32_16x16x32_bf16 v[42:45], v[156:159], v[196:199], v[42:45]
	v_mfma_f32_16x16x32_bf16 v[34:37], v[164:167], v[196:199], v[34:37]
	v_mfma_f32_16x16x32_bf16 v[26:29], v[156:159], v[204:207], v[26:29]
	v_mfma_f32_16x16x32_bf16 v[18:21], v[164:167], v[204:207], v[18:21]
	v_mfma_f32_16x16x32_bf16 v[10:13], v[156:159], v[212:215], v[10:13]
	v_mfma_f32_16x16x32_bf16 v[2:5], v[164:167], v[212:215], v[2:5]
	s_setprio 0
	s_setprio 1
	v_mfma_f32_16x16x32_bf16 v[70:73], v[168:171], v[184:187], v[70:73]
	v_mfma_f32_16x16x32_bf16 v[54:57], v[176:179], v[184:187], v[54:57]
	v_mfma_f32_16x16x32_bf16 v[46:49], v[168:171], v[192:195], v[46:49]
	v_mfma_f32_16x16x32_bf16 v[38:41], v[176:179], v[192:195], v[38:41]
	v_mfma_f32_16x16x32_bf16 v[30:33], v[168:171], v[200:203], v[30:33]
	v_mfma_f32_16x16x32_bf16 v[22:25], v[176:179], v[200:203], v[22:25]
	v_mfma_f32_16x16x32_bf16 v[14:17], v[168:171], v[208:211], v[14:17]
	v_mfma_f32_16x16x32_bf16 v[6:9], v[176:179], v[208:211], v[6:9]
	v_mfma_f32_16x16x32_bf16 v[70:73], v[172:175], v[188:191], v[70:73]
	v_mfma_f32_16x16x32_bf16 v[54:57], v[180:183], v[188:191], v[54:57]
	v_mfma_f32_16x16x32_bf16 v[46:49], v[172:175], v[196:199], v[46:49]
	v_mfma_f32_16x16x32_bf16 v[38:41], v[180:183], v[196:199], v[38:41]
	v_mfma_f32_16x16x32_bf16 v[30:33], v[172:175], v[204:207], v[30:33]
	v_mfma_f32_16x16x32_bf16 v[22:25], v[180:183], v[204:207], v[22:25]
	v_mfma_f32_16x16x32_bf16 v[14:17], v[172:175], v[212:215], v[14:17]
	v_mfma_f32_16x16x32_bf16 v[6:9], v[180:183], v[212:215], v[6:9]
	s_barrier
	s_setprio 0
	s_add_i32 s15, s15, 2
	s_add_u32 s70, s70, 0x100
	s_addc_u32 s71, s71, 0
	s_add_u32 s57, s57, 0x100
	s_addc_u32 s14, s14, 0
	s_cmp_gt_u32 s15, 61
	s_cbranch_scc0 .LBB0_249
	s_mov_b32 m0, s65
	s_nop 0
	global_load_lds_dwordx4 v136, s[100:101]
	s_mov_b32 m0, s76
	s_nop 0
	global_load_lds_dwordx4 v132, s[100:101]
	s_and_b64 vcc, exec, s[12:13]
	s_cbranch_vccz .LBB0_252
	s_barrier

.LBB0_331:
	ds_read_b128 v[132:135], v207
	ds_read_b128 v[136:139], v207 offset:1024
	ds_read_b128 v[140:143], v207 offset:2048
	ds_read_b128 v[144:147], v207 offset:3072
	ds_read_b128 v[148:151], v208
	ds_read_b128 v[152:155], v208 offset:1024
	ds_read_b128 v[156:159], v208 offset:2048
	ds_read_b128 v[160:163], v208 offset:3072
	s_add_u32 s16, s66, 0x200
	s_addc_u32 s17, s67, 0
	s_cmpk_eq_i32 s15, 0xa8
	s_cselect_b32 s75, s1, s17
	s_cselect_b32 s74, s0, s16
	s_cselect_b32 s71, s65, s14
	s_cselect_b32 s70, s64, s90
	s_cmp_eq_u32 s15, 0
	s_cbranch_scc1 .Lrb2_skip_9715
	s_mov_b32 m0, s58
	s_nop 0
	global_load_lds_dwordx4 v178, s[100:101]
	s_mov_b32 m0, s59
	s_nop 0
	global_load_lds_dwordx4 v182, s[100:101]
.Lrb2_skip_9715:
	s_mov_b32 m0, s86
	ds_read_b128 v[164:167], v209
	ds_read_b128 v[168:171], v209 offset:1024
	ds_read_b128 v[172:175], v209 offset:2048
	ds_read_b128 v[194:197], v209 offset:3072
	ds_read_b128 v[198:201], v209 offset:4096
	ds_read_b128 v[202:205], v209 offset:5120
	ds_read_b128 v[210:213], v209 offset:6144
	ds_read_b128 v[214:217], v209 offset:7168
	global_load_lds_dwordx4 v186, s[66:67]
	s_mov_b32 m0, s87
	s_nop 0
	global_load_lds_dwordx4 v188, s[66:67]
	s_waitcnt vmcnt(8)
	s_waitcnt lgkmcnt(0)
	s_setprio 1
	s_barrier
	v_mfma_f32_16x16x32_bf16 v[122:125], v[132:135], v[164:167], v[122:125]
	v_mfma_f32_16x16x32_bf16 v[118:121], v[140:143], v[164:167], v[118:121]
	v_mfma_f32_16x16x32_bf16 v[110:113], v[132:135], v[172:175], v[110:113]
	v_mfma_f32_16x16x32_bf16 v[106:109], v[140:143], v[172:175], v[106:109]
	v_mfma_f32_16x16x32_bf16 v[94:97], v[132:135], v[198:201], v[94:97]
	v_mfma_f32_16x16x32_bf16 v[90:93], v[140:143], v[198:201], v[90:93]
	v_mfma_f32_16x16x32_bf16 v[78:81], v[132:135], v[210:213], v[78:81]
	v_mfma_f32_16x16x32_bf16 v[74:77], v[140:143], v[210:213], v[74:77]
	v_mfma_f32_16x16x32_bf16 v[122:125], v[136:139], v[168:171], v[122:125]
	v_mfma_f32_16x16x32_bf16 v[118:121], v[144:147], v[168:171], v[118:121]
	v_mfma_f32_16x16x32_bf16 v[110:113], v[136:139], v[194:197], v[110:113]
	v_mfma_f32_16x16x32_bf16 v[106:109], v[144:147], v[194:197], v[106:109]
	v_mfma_f32_16x16x32_bf16 v[94:97], v[136:139], v[202:205], v[94:97]
	v_mfma_f32_16x16x32_bf16 v[90:93], v[144:147], v[202:205], v[90:93]
	v_mfma_f32_16x16x32_bf16 v[78:81], v[136:139], v[214:217], v[78:81]
	v_mfma_f32_16x16x32_bf16 v[74:77], v[144:147], v[214:217], v[74:77]
	s_setprio 0
	s_setprio 1
	v_mfma_f32_16x16x32_bf16 v[126:129], v[148:151], v[164:167], v[126:129]
	v_mfma_f32_16x16x32_bf16 v[114:117], v[156:159], v[164:167], v[114:117]
	v_mfma_f32_16x16x32_bf16 v[102:105], v[148:151], v[172:175], v[102:105]
	v_mfma_f32_16x16x32_bf16 v[98:101], v[156:159], v[172:175], v[98:101]
	v_mfma_f32_16x16x32_bf16 v[86:89], v[148:151], v[198:201], v[86:89]
	v_mfma_f32_16x16x32_bf16 v[82:85], v[156:159], v[198:201], v[82:85]
	v_mfma_f32_16x16x32_bf16 v[70:73], v[148:151], v[210:213], v[70:73]
	v_mfma_f32_16x16x32_bf16 v[66:69], v[156:159], v[210:213], v[66:69]
	v_mfma_f32_16x16x32_bf16 v[126:129], v[152:155], v[168:171], v[126:129]
	v_mfma_f32_16x16x32_bf16 v[114:117], v[160:163], v[168:171], v[114:117]
	v_mfma_f32_16x16x32_bf16 v[102:105], v[152:155], v[194:197], v[102:105]
	v_mfma_f32_16x16x32_bf16 v[98:101], v[160:163], v[194:197], v[98:101]
	v_mfma_f32_16x16x32_bf16 v[86:89], v[152:155], v[202:205], v[86:89]
	v_mfma_f32_16x16x32_bf16 v[82:85], v[160:163], v[202:205], v[82:85]
	v_mfma_f32_16x16x32_bf16 v[70:73], v[152:155], v[214:217], v[70:73]
	v_mfma_f32_16x16x32_bf16 v[66:69], v[160:163], v[214:217], v[66:69]
	s_barrier
	s_setprio 0
	s_mov_b32 m0, s88
	s_mov_b64 s[98:99], s[70:71]
	s_add_u32 s16, s70, 0x2b0000
	ds_read_b128 v[164:167], v209 offset:16384
	ds_read_b128 v[168:171], v209 offset:17408
	ds_read_b128 v[172:175], v209 offset:18432
	ds_read_b128 v[194:197], v209 offset:19456
	ds_read_b128 v[198:201], v209 offset:20480
	ds_read_b128 v[202:205], v209 offset:21504
	ds_read_b128 v[210:213], v209 offset:22528
	ds_read_b128 v[214:217], v209 offset:23552
	global_load_lds_dwordx4 v180, s[70:71]
	s_mov_b32 m0, s84
	s_addc_u32 s17, s71, 0
	global_load_lds_dwordx4 v184, s[70:71]
	s_mov_b32 m0, s85
	s_mov_b64 s[100:101], s[74:75]
	global_load_lds_dwordx4 v180, s[16:17]
	s_mov_b32 m0, s46
	s_nop 0
	global_load_lds_dwordx4 v184, s[16:17]
	s_waitcnt vmcnt(6)
	s_waitcnt lgkmcnt(0)
	s_setprio 1
	s_barrier
	v_mfma_f32_16x16x32_bf16 v[58:61], v[132:135], v[164:167], v[58:61]
	v_mfma_f32_16x16x32_bf16 v[54:57], v[140:143], v[164:167], v[54:57]
	v_mfma_f32_16x16x32_bf16 v[46:49], v[132:135], v[172:175], v[46:49]
	v_mfma_f32_16x16x32_bf16 v[42:45], v[140:143], v[172:175], v[42:45]
	v_mfma_f32_16x16x32_bf16 v[30:33], v[132:135], v[198:201], v[30:33]
	v_mfma_f32_16x16x32_bf16 v[26:29], v[140:143], v[198:201], v[26:29]
	v_mfma_f32_16x16x32_bf16 v[14:17], v[132:135], v[210:213], v[14:17]
	v_mfma_f32_16x16x32_bf16 v[10:13], v[140:143], v[210:213], v[10:13]
	v_mfma_f32_16x16x32_bf16 v[58:61], v[136:139], v[168:171], v[58:61]
	v_mfma_f32_16x16x32_bf16 v[54:57], v[144:147], v[168:171], v[54:57]
	v_mfma_f32_16x16x32_bf16 v[46:49], v[136:139], v[194:197], v[46:49]
	v_mfma_f32_16x16x32_bf16 v[42:45], v[144:147], v[194:197], v[42:45]
	v_mfma_f32_16x16x32_bf16 v[30:33], v[136:139], v[202:205], v[30:33]
	v_mfma_f32_16x16x32_bf16 v[26:29], v[144:147], v[202:205], v[26:29]
	v_mfma_f32_16x16x32_bf16 v[14:17], v[136:139], v[214:217], v[14:17]
	v_mfma_f32_16x16x32_bf16 v[10:13], v[144:147], v[214:217], v[10:13]
	s_setprio 0
	s_setprio 1
	v_mfma_f32_16x16x32_bf16 v[62:65], v[148:151], v[164:167], v[62:65]
	v_mfma_f32_16x16x32_bf16 v[50:53], v[156:159], v[164:167], v[50:53]
	v_mfma_f32_16x16x32_bf16 v[38:41], v[148:151], v[172:175], v[38:41]
	v_mfma_f32_16x16x32_bf16 v[34:37], v[156:159], v[172:175], v[34:37]
	v_mfma_f32_16x16x32_bf16 v[22:25], v[148:151], v[198:201], v[22:25]
	v_mfma_f32_16x16x32_bf16 v[18:21], v[156:159], v[198:201], v[18:21]
	v_mfma_f32_16x16x32_bf16 v[6:9], v[148:151], v[210:213], v[6:9]
	v_mfma_f32_16x16x32_bf16 v[2:5], v[156:159], v[210:213], v[2:5]
	v_mfma_f32_16x16x32_bf16 v[62:65], v[152:155], v[168:171], v[62:65]
	v_mfma_f32_16x16x32_bf16 v[50:53], v[160:163], v[168:171], v[50:53]
	v_mfma_f32_16x16x32_bf16 v[38:41], v[152:155], v[194:197], v[38:41]
	v_mfma_f32_16x16x32_bf16 v[34:37], v[160:163], v[194:197], v[34:37]
	v_mfma_f32_16x16x32_bf16 v[22:25], v[152:155], v[202:205], v[22:25]
	v_mfma_f32_16x16x32_bf16 v[18:21], v[160:163], v[202:205], v[18:21]
	v_mfma_f32_16x16x32_bf16 v[6:9], v[152:155], v[214:217], v[6:9]
	v_mfma_f32_16x16x32_bf16 v[2:5], v[160:163], v[214:217], v[2:5]
	s_barrier
; #define PG8_BAR __builtin_amdgcn_s_barrier()
;     ...
;         for (int t = 2; t < nt; t += 2) PG8_KITER(t);
;         if constexpr (ALIGN_EPI) { if (wr == 0) PG8_BAR; }
	s_setprio 0
	ds_read_b128 v[132:135], v130
	ds_read_b128 v[136:139], v130 offset:1024
	ds_read_b128 v[140:143], v130 offset:2048
	ds_read_b128 v[144:147], v130 offset:3072
	ds_read_b128 v[148:151], v131
	ds_read_b128 v[152:155], v131 offset:1024
	ds_read_b128 v[156:159], v131 offset:2048
	ds_read_b128 v[160:163], v131 offset:3072
	s_add_u32 s16, s74, 0x2b0000
	s_addc_u32 s17, s75, 0
	s_mov_b32 m0, s11
	s_nop 0
	global_load_lds_dwordx4 v178, s[100:101]
	s_mov_b32 m0, s12
	s_nop 0
	global_load_lds_dwordx4 v182, s[100:101]
	s_mov_b32 m0, s13
	ds_read_b128 v[164:167], v209 offset:32768
	ds_read_b128 v[168:171], v209 offset:33792
	ds_read_b128 v[172:175], v209 offset:34816
	ds_read_b128 v[194:197], v209 offset:35840
	ds_read_b128 v[198:201], v209 offset:36864
	ds_read_b128 v[202:205], v209 offset:37888
	ds_read_b128 v[210:213], v209 offset:38912
	ds_read_b128 v[214:217], v209 offset:39936
	global_load_lds_dwordx4 v178, s[16:17]
	s_mov_b32 m0, s29
	s_nop 0
	global_load_lds_dwordx4 v182, s[16:17]
	s_waitcnt vmcnt(8)
	s_waitcnt lgkmcnt(0)
	s_setprio 1
	s_barrier
	v_mfma_f32_16x16x32_bf16 v[122:125], v[132:135], v[164:167], v[122:125]
	v_mfma_f32_16x16x32_bf16 v[118:121], v[140:143], v[164:167], v[118:121]
	v_mfma_f32_16x16x32_bf16 v[110:113], v[132:135], v[172:175], v[110:113]
	v_mfma_f32_16x16x32_bf16 v[106:109], v[140:143], v[172:175], v[106:109]
	v_mfma_f32_16x16x32_bf16 v[94:97], v[132:135], v[198:201], v[94:97]
	v_mfma_f32_16x16x32_bf16 v[90:93], v[140:143], v[198:201], v[90:93]
	v_mfma_f32_16x16x32_bf16 v[78:81], v[132:135], v[210:213], v[78:81]
	v_mfma_f32_16x16x32_bf16 v[74:77], v[140:143], v[210:213], v[74:77]
	v_mfma_f32_16x16x32_bf16 v[122:125], v[136:139], v[168:171], v[122:125]
	v_mfma_f32_16x16x32_bf16 v[118:121], v[144:147], v[168:171], v[118:121]
	v_mfma_f32_16x16x32_bf16 v[110:113], v[136:139], v[194:197], v[110:113]
	v_mfma_f32_16x16x32_bf16 v[106:109], v[144:147], v[194:197], v[106:109]
	v_mfma_f32_16x16x32_bf16 v[94:97], v[136:139], v[202:205], v[94:97]
	v_mfma_f32_16x16x32_bf16 v[90:93], v[144:147], v[202:205], v[90:93]
	v_mfma_f32_16x16x32_bf16 v[78:81], v[136:139], v[214:217], v[78:81]
	v_mfma_f32_16x16x32_bf16 v[74:77], v[144:147], v[214:217], v[74:77]
	s_setprio 0
	s_setprio 1
	v_mfma_f32_16x16x32_bf16 v[126:129], v[148:151], v[164:167], v[126:129]
	v_mfma_f32_16x16x32_bf16 v[114:117], v[156:159], v[164:167], v[114:117]
	v_mfma_f32_16x16x32_bf16 v[102:105], v[148:151], v[172:175], v[102:105]
	v_mfma_f32_16x16x32_bf16 v[98:101], v[156:159], v[172:175], v[98:101]
	v_mfma_f32_16x16x32_bf16 v[86:89], v[148:151], v[198:201], v[86:89]
	v_mfma_f32_16x16x32_bf16 v[82:85], v[156:159], v[198:201], v[82:85]
	v_mfma_f32_16x16x32_bf16 v[70:73], v[148:151], v[210:213], v[70:73]
	v_mfma_f32_16x16x32_bf16 v[66:69], v[156:159], v[210:213], v[66:69]
	v_mfma_f32_16x16x32_bf16 v[126:129], v[152:155], v[168:171], v[126:129]
	v_mfma_f32_16x16x32_bf16 v[114:117], v[160:163], v[168:171], v[114:117]
	v_mfma_f32_16x16x32_bf16 v[102:105], v[152:155], v[194:197], v[102:105]
	v_mfma_f32_16x16x32_bf16 v[98:101], v[160:163], v[194:197], v[98:101]
	v_mfma_f32_16x16x32_bf16 v[86:89], v[152:155], v[202:205], v[86:89]
	v_mfma_f32_16x16x32_bf16 v[82:85], v[160:163], v[202:205], v[82:85]
	v_mfma_f32_16x16x32_bf16 v[70:73], v[152:155], v[214:217], v[70:73]
	v_mfma_f32_16x16x32_bf16 v[66:69], v[160:163], v[214:217], v[66:69]
	s_barrier
	s_setprio 0
	s_mov_b32 m0, s47
	s_add_u32 s98, s98, 0x80
	s_addc_u32 s99, s99, 0
	s_add_u32 s100, s100, 0x80
	s_addc_u32 s101, s101, 0
	s_add_u32 s16, s70, 0x2b0080
	ds_read_b128 v[164:167], v209 offset:49152
	ds_read_b128 v[168:171], v209 offset:50176
	ds_read_b128 v[172:175], v209 offset:51200
	ds_read_b128 v[194:197], v209 offset:52224
	ds_read_b128 v[198:201], v209 offset:53248
	ds_read_b128 v[202:205], v209 offset:54272
	ds_read_b128 v[210:213], v209 offset:55296
	ds_read_b128 v[214:217], v209 offset:56320
	global_load_lds_dwordx4 v180, s[98:99]
	s_mov_b32 m0, s89
	s_addc_u32 s17, s71, 0
	global_load_lds_dwordx4 v184, s[98:99]
	s_mov_b32 m0, s56
	s_nop 0
	global_load_lds_dwordx4 v180, s[16:17]
	s_mov_b32 m0, s57
	s_nop 0
	global_load_lds_dwordx4 v184, s[16:17]
	s_waitcnt vmcnt(6)
	s_waitcnt lgkmcnt(0)
	s_setprio 1
	s_barrier
	v_mfma_f32_16x16x32_bf16 v[58:61], v[132:135], v[164:167], v[58:61]
	v_mfma_f32_16x16x32_bf16 v[54:57], v[140:143], v[164:167], v[54:57]
	v_mfma_f32_16x16x32_bf16 v[46:49], v[132:135], v[172:175], v[46:49]
	v_mfma_f32_16x16x32_bf16 v[42:45], v[140:143], v[172:175], v[42:45]
	v_mfma_f32_16x16x32_bf16 v[30:33], v[132:135], v[198:201], v[30:33]
	v_mfma_f32_16x16x32_bf16 v[26:29], v[140:143], v[198:201], v[26:29]
	v_mfma_f32_16x16x32_bf16 v[14:17], v[132:135], v[210:213], v[14:17]
	v_mfma_f32_16x16x32_bf16 v[10:13], v[140:143], v[210:213], v[10:13]
	v_mfma_f32_16x16x32_bf16 v[58:61], v[136:139], v[168:171], v[58:61]
	v_mfma_f32_16x16x32_bf16 v[54:57], v[144:147], v[168:171], v[54:57]
	v_mfma_f32_16x16x32_bf16 v[46:49], v[136:139], v[194:197], v[46:49]
	v_mfma_f32_16x16x32_bf16 v[42:45], v[144:147], v[194:197], v[42:45]
	v_mfma_f32_16x16x32_bf16 v[30:33], v[136:139], v[202:205], v[30:33]
	v_mfma_f32_16x16x32_bf16 v[26:29], v[144:147], v[202:205], v[26:29]
	v_mfma_f32_16x16x32_bf16 v[14:17], v[136:139], v[214:217], v[14:17]
	v_mfma_f32_16x16x32_bf16 v[10:13], v[144:147], v[214:217], v[10:13]
	s_setprio 0
	s_setprio 1
	v_mfma_f32_16x16x32_bf16 v[62:65], v[148:151], v[164:167], v[62:65]
	v_mfma_f32_16x16x32_bf16 v[50:53], v[156:159], v[164:167], v[50:53]
	v_mfma_f32_16x16x32_bf16 v[38:41], v[148:151], v[172:175], v[38:41]
	v_mfma_f32_16x16x32_bf16 v[34:37], v[156:159], v[172:175], v[34:37]
	v_mfma_f32_16x16x32_bf16 v[22:25], v[148:151], v[198:201], v[22:25]
	v_mfma_f32_16x16x32_bf16 v[18:21], v[156:159], v[198:201], v[18:21]
	v_mfma_f32_16x16x32_bf16 v[6:9], v[148:151], v[210:213], v[6:9]
	v_mfma_f32_16x16x32_bf16 v[2:5], v[156:159], v[210:213], v[2:5]
	v_mfma_f32_16x16x32_bf16 v[62:65], v[152:155], v[168:171], v[62:65]
	v_mfma_f32_16x16x32_bf16 v[50:53], v[160:163], v[168:171], v[50:53]
	v_mfma_f32_16x16x32_bf16 v[38:41], v[152:155], v[194:197], v[38:41]
	v_mfma_f32_16x16x32_bf16 v[34:37], v[160:163], v[194:197], v[34:37]
	v_mfma_f32_16x16x32_bf16 v[22:25], v[152:155], v[202:205], v[22:25]
	v_mfma_f32_16x16x32_bf16 v[18:21], v[160:163], v[202:205], v[18:21]
	v_mfma_f32_16x16x32_bf16 v[6:9], v[152:155], v[214:217], v[6:9]
	v_mfma_f32_16x16x32_bf16 v[2:5], v[160:163], v[214:217], v[2:5]
	s_barrier
	s_setprio 0
	s_add_i32 s15, s15, 2
	s_add_u32 s66, s66, 0x100
	s_addc_u32 s67, s67, 0
	s_add_u32 s90, s90, 0x100
	s_addc_u32 s14, s14, 0
	s_cmpk_gt_u32 s15, 0xa9
	s_cbranch_scc0 .LBB0_331
	s_mov_b32 m0, s58
	s_nop 0
	global_load_lds_dwordx4 v178, s[100:101]
	s_mov_b32 m0, s59
	s_nop 0
	global_load_lds_dwordx4 v182, s[100:101]
	s_and_b64 vcc, exec, s[30:31]
	s_cbranch_vccz .LBB0_334
	s_barrier

.LBB0_415:
	ds_read_b128 v[150:153], v163
	ds_read_b128 v[154:157], v163 offset:1024
	ds_read_b128 v[158:161], v163 offset:2048
	ds_read_b128 v[168:171], v163 offset:3072
	ds_read_b128 v[172:175], v164
	ds_read_b128 v[176:179], v164 offset:1024
	ds_read_b128 v[180:183], v164 offset:2048
	ds_read_b128 v[184:187], v164 offset:3072
	s_add_u32 s6, s80, 0xfff00080
	s_addc_u32 s7, s81, -1
	s_cmp_eq_u32 s15, 60
	s_cselect_b32 s83, s1, s7
	s_cselect_b32 s82, s75, s6
	s_cselect_b32 s7, s18, s14
	s_cselect_b32 s6, vcc_lo, s30
	s_cmp_eq_u32 s15, 0
	s_cbranch_scc1 .Lrb2_skip_11871
	s_mov_b32 m0, s96
	s_nop 0
	global_load_lds_dwordx4 v136, s[100:101]
	s_mov_b32 m0, s97
	s_nop 0
	global_load_lds_dwordx4 v132, s[100:101]
.Lrb2_skip_11871:
	s_mov_b32 m0, s89
	ds_read_b128 v[188:191], v165
	ds_read_b128 v[192:195], v165 offset:1024
	ds_read_b128 v[196:199], v165 offset:2048
	ds_read_b128 v[200:203], v165 offset:3072
	ds_read_b128 v[204:207], v165 offset:4096
	ds_read_b128 v[208:211], v165 offset:5120
	ds_read_b128 v[212:215], v165 offset:6144
	ds_read_b128 v[216:219], v165 offset:7168
	global_load_lds_dwordx4 v140, s[80:81]
	s_mov_b32 m0, s92
	s_nop 0
	global_load_lds_dwordx4 v142, s[80:81]
	s_waitcnt vmcnt(8)
	s_waitcnt lgkmcnt(0)
	s_setprio 1
	s_barrier
	v_mfma_f32_16x16x32_bf16 v[118:121], v[150:153], v[188:191], v[118:121]
	v_mfma_f32_16x16x32_bf16 v[114:117], v[158:161], v[188:191], v[114:117]
	v_mfma_f32_16x16x32_bf16 v[102:105], v[150:153], v[196:199], v[102:105]
	v_mfma_f32_16x16x32_bf16 v[98:101], v[158:161], v[196:199], v[98:101]
	v_mfma_f32_16x16x32_bf16 v[86:89], v[150:153], v[204:207], v[86:89]
	v_mfma_f32_16x16x32_bf16 v[82:85], v[158:161], v[204:207], v[82:85]
	v_mfma_f32_16x16x32_bf16 v[70:73], v[150:153], v[212:215], v[70:73]
	v_mfma_f32_16x16x32_bf16 v[66:69], v[158:161], v[212:215], v[66:69]
	v_mfma_f32_16x16x32_bf16 v[118:121], v[154:157], v[192:195], v[118:121]
	v_mfma_f32_16x16x32_bf16 v[114:117], v[168:171], v[192:195], v[114:117]
	v_mfma_f32_16x16x32_bf16 v[102:105], v[154:157], v[200:203], v[102:105]
	v_mfma_f32_16x16x32_bf16 v[98:101], v[168:171], v[200:203], v[98:101]
	v_mfma_f32_16x16x32_bf16 v[86:89], v[154:157], v[208:211], v[86:89]
	v_mfma_f32_16x16x32_bf16 v[82:85], v[168:171], v[208:211], v[82:85]
	v_mfma_f32_16x16x32_bf16 v[70:73], v[154:157], v[216:219], v[70:73]
	v_mfma_f32_16x16x32_bf16 v[66:69], v[168:171], v[216:219], v[66:69]
	s_setprio 0
	s_setprio 1
	v_mfma_f32_16x16x32_bf16 v[126:129], v[172:175], v[188:191], v[126:129]
	v_mfma_f32_16x16x32_bf16 v[122:125], v[180:183], v[188:191], v[122:125]
	v_mfma_f32_16x16x32_bf16 v[110:113], v[172:175], v[196:199], v[110:113]
	v_mfma_f32_16x16x32_bf16 v[106:109], v[180:183], v[196:199], v[106:109]
	v_mfma_f32_16x16x32_bf16 v[94:97], v[172:175], v[204:207], v[94:97]
	v_mfma_f32_16x16x32_bf16 v[90:93], v[180:183], v[204:207], v[90:93]
	v_mfma_f32_16x16x32_bf16 v[78:81], v[172:175], v[212:215], v[78:81]
	v_mfma_f32_16x16x32_bf16 v[74:77], v[180:183], v[212:215], v[74:77]
	v_mfma_f32_16x16x32_bf16 v[126:129], v[176:179], v[192:195], v[126:129]
	v_mfma_f32_16x16x32_bf16 v[122:125], v[184:187], v[192:195], v[122:125]
	v_mfma_f32_16x16x32_bf16 v[110:113], v[176:179], v[200:203], v[110:113]
	v_mfma_f32_16x16x32_bf16 v[106:109], v[184:187], v[200:203], v[106:109]
	v_mfma_f32_16x16x32_bf16 v[94:97], v[176:179], v[208:211], v[94:97]
	v_mfma_f32_16x16x32_bf16 v[90:93], v[184:187], v[208:211], v[90:93]
	v_mfma_f32_16x16x32_bf16 v[78:81], v[176:179], v[216:219], v[78:81]
	v_mfma_f32_16x16x32_bf16 v[74:77], v[184:187], v[216:219], v[74:77]
	s_barrier
	s_setprio 0
	s_mov_b32 m0, vcc_hi
	s_mov_b64 s[98:99], s[6:7]
	s_add_u32 s16, s6, 0x100000
	ds_read_b128 v[188:191], v165 offset:16384
	ds_read_b128 v[192:195], v165 offset:17408
	ds_read_b128 v[196:199], v165 offset:18432
	ds_read_b128 v[200:203], v165 offset:19456
	ds_read_b128 v[204:207], v165 offset:20480
	ds_read_b128 v[208:211], v165 offset:21504
	ds_read_b128 v[212:215], v165 offset:22528
	ds_read_b128 v[216:219], v165 offset:23552
	global_load_lds_dwordx4 v134, s[6:7]
	s_mov_b32 m0, s84
	s_addc_u32 s17, s7, 0
	global_load_lds_dwordx4 v130, s[6:7]
	s_mov_b32 m0, s85
	s_mov_b64 s[100:101], s[82:83]
	global_load_lds_dwordx4 v134, s[16:17]
	s_mov_b32 m0, s46
	s_nop 0
	global_load_lds_dwordx4 v130, s[16:17]
	s_waitcnt vmcnt(6)
	s_waitcnt lgkmcnt(0)
	s_setprio 1
	s_barrier
	v_mfma_f32_16x16x32_bf16 v[54:57], v[150:153], v[188:191], v[54:57]
	v_mfma_f32_16x16x32_bf16 v[50:53], v[158:161], v[188:191], v[50:53]
	v_mfma_f32_16x16x32_bf16 v[38:41], v[150:153], v[196:199], v[38:41]
	v_mfma_f32_16x16x32_bf16 v[34:37], v[158:161], v[196:199], v[34:37]
	v_mfma_f32_16x16x32_bf16 v[22:25], v[150:153], v[204:207], v[22:25]
	v_mfma_f32_16x16x32_bf16 v[18:21], v[158:161], v[204:207], v[18:21]
	v_mfma_f32_16x16x32_bf16 v[6:9], v[150:153], v[212:215], v[6:9]
	v_mfma_f32_16x16x32_bf16 v[2:5], v[158:161], v[212:215], v[2:5]
	v_mfma_f32_16x16x32_bf16 v[54:57], v[154:157], v[192:195], v[54:57]
	v_mfma_f32_16x16x32_bf16 v[50:53], v[168:171], v[192:195], v[50:53]
	v_mfma_f32_16x16x32_bf16 v[38:41], v[154:157], v[200:203], v[38:41]
	v_mfma_f32_16x16x32_bf16 v[34:37], v[168:171], v[200:203], v[34:37]
	v_mfma_f32_16x16x32_bf16 v[22:25], v[154:157], v[208:211], v[22:25]
	v_mfma_f32_16x16x32_bf16 v[18:21], v[168:171], v[208:211], v[18:21]
	v_mfma_f32_16x16x32_bf16 v[6:9], v[154:157], v[216:219], v[6:9]
	v_mfma_f32_16x16x32_bf16 v[2:5], v[168:171], v[216:219], v[2:5]
	s_setprio 0
	s_setprio 1
	v_mfma_f32_16x16x32_bf16 v[62:65], v[172:175], v[188:191], v[62:65]
	v_mfma_f32_16x16x32_bf16 v[58:61], v[180:183], v[188:191], v[58:61]
	v_mfma_f32_16x16x32_bf16 v[46:49], v[172:175], v[196:199], v[46:49]
	v_mfma_f32_16x16x32_bf16 v[42:45], v[180:183], v[196:199], v[42:45]
	v_mfma_f32_16x16x32_bf16 v[30:33], v[172:175], v[204:207], v[30:33]
	v_mfma_f32_16x16x32_bf16 v[26:29], v[180:183], v[204:207], v[26:29]
	v_mfma_f32_16x16x32_bf16 v[14:17], v[172:175], v[212:215], v[14:17]
	v_mfma_f32_16x16x32_bf16 v[10:13], v[180:183], v[212:215], v[10:13]
	v_mfma_f32_16x16x32_bf16 v[62:65], v[176:179], v[192:195], v[62:65]
	v_mfma_f32_16x16x32_bf16 v[58:61], v[184:187], v[192:195], v[58:61]
	v_mfma_f32_16x16x32_bf16 v[46:49], v[176:179], v[200:203], v[46:49]
	v_mfma_f32_16x16x32_bf16 v[42:45], v[184:187], v[200:203], v[42:45]
	v_mfma_f32_16x16x32_bf16 v[30:33], v[176:179], v[208:211], v[30:33]
	v_mfma_f32_16x16x32_bf16 v[26:29], v[184:187], v[208:211], v[26:29]
	v_mfma_f32_16x16x32_bf16 v[14:17], v[176:179], v[216:219], v[14:17]
	v_mfma_f32_16x16x32_bf16 v[10:13], v[184:187], v[216:219], v[10:13]
	s_barrier
; #define PG8_BAR __builtin_amdgcn_s_barrier()
;     ...
;         for (int t = 2; t < nt; t += 2) PG8_KITER(t);
;         if constexpr (ALIGN_EPI) { if (wr == 0) PG8_BAR; }
	s_setprio 0
	ds_read_b128 v[150:153], v138
	ds_read_b128 v[154:157], v138 offset:1024
	ds_read_b128 v[158:161], v138 offset:2048
	ds_read_b128 v[168:171], v138 offset:3072
	ds_read_b128 v[172:175], v148
	ds_read_b128 v[176:179], v148 offset:1024
	ds_read_b128 v[180:183], v148 offset:2048
	ds_read_b128 v[184:187], v148 offset:3072
	s_add_u32 s16, s82, 0x100000
	s_addc_u32 s17, s83, 0
	s_mov_b32 m0, s86
	s_nop 0
	global_load_lds_dwordx4 v136, s[100:101]
	s_mov_b32 m0, s93
	s_nop 0
	global_load_lds_dwordx4 v132, s[100:101]
	s_mov_b32 m0, s94
	ds_read_b128 v[188:191], v165 offset:32768
	ds_read_b128 v[192:195], v165 offset:33792
	ds_read_b128 v[196:199], v165 offset:34816
	ds_read_b128 v[200:203], v165 offset:35840
	ds_read_b128 v[204:207], v165 offset:36864
	ds_read_b128 v[208:211], v165 offset:37888
	ds_read_b128 v[212:215], v165 offset:38912
	ds_read_b128 v[216:219], v165 offset:39936
	global_load_lds_dwordx4 v136, s[16:17]
	s_mov_b32 m0, s95
	s_nop 0
	global_load_lds_dwordx4 v132, s[16:17]
	s_waitcnt vmcnt(8)
	s_waitcnt lgkmcnt(0)
	s_setprio 1
	s_barrier
	v_mfma_f32_16x16x32_bf16 v[118:121], v[150:153], v[188:191], v[118:121]
	v_mfma_f32_16x16x32_bf16 v[114:117], v[158:161], v[188:191], v[114:117]
	v_mfma_f32_16x16x32_bf16 v[102:105], v[150:153], v[196:199], v[102:105]
	v_mfma_f32_16x16x32_bf16 v[98:101], v[158:161], v[196:199], v[98:101]
	v_mfma_f32_16x16x32_bf16 v[86:89], v[150:153], v[204:207], v[86:89]
	v_mfma_f32_16x16x32_bf16 v[82:85], v[158:161], v[204:207], v[82:85]
	v_mfma_f32_16x16x32_bf16 v[70:73], v[150:153], v[212:215], v[70:73]
	v_mfma_f32_16x16x32_bf16 v[66:69], v[158:161], v[212:215], v[66:69]
	v_mfma_f32_16x16x32_bf16 v[118:121], v[154:157], v[192:195], v[118:121]
	v_mfma_f32_16x16x32_bf16 v[114:117], v[168:171], v[192:195], v[114:117]
	v_mfma_f32_16x16x32_bf16 v[102:105], v[154:157], v[200:203], v[102:105]
	v_mfma_f32_16x16x32_bf16 v[98:101], v[168:171], v[200:203], v[98:101]
	v_mfma_f32_16x16x32_bf16 v[86:89], v[154:157], v[208:211], v[86:89]
	v_mfma_f32_16x16x32_bf16 v[82:85], v[168:171], v[208:211], v[82:85]
	v_mfma_f32_16x16x32_bf16 v[70:73], v[154:157], v[216:219], v[70:73]
	v_mfma_f32_16x16x32_bf16 v[66:69], v[168:171], v[216:219], v[66:69]
	s_setprio 0
	s_setprio 1
	v_mfma_f32_16x16x32_bf16 v[126:129], v[172:175], v[188:191], v[126:129]
	v_mfma_f32_16x16x32_bf16 v[122:125], v[180:183], v[188:191], v[122:125]
	v_mfma_f32_16x16x32_bf16 v[110:113], v[172:175], v[196:199], v[110:113]
	v_mfma_f32_16x16x32_bf16 v[106:109], v[180:183], v[196:199], v[106:109]
	v_mfma_f32_16x16x32_bf16 v[94:97], v[172:175], v[204:207], v[94:97]
	v_mfma_f32_16x16x32_bf16 v[90:93], v[180:183], v[204:207], v[90:93]
	v_mfma_f32_16x16x32_bf16 v[78:81], v[172:175], v[212:215], v[78:81]
	v_mfma_f32_16x16x32_bf16 v[74:77], v[180:183], v[212:215], v[74:77]
	v_mfma_f32_16x16x32_bf16 v[126:129], v[176:179], v[192:195], v[126:129]
	v_mfma_f32_16x16x32_bf16 v[122:125], v[184:187], v[192:195], v[122:125]
	v_mfma_f32_16x16x32_bf16 v[110:113], v[176:179], v[200:203], v[110:113]
	v_mfma_f32_16x16x32_bf16 v[106:109], v[184:187], v[200:203], v[106:109]
	v_mfma_f32_16x16x32_bf16 v[94:97], v[176:179], v[208:211], v[94:97]
	v_mfma_f32_16x16x32_bf16 v[90:93], v[184:187], v[208:211], v[90:93]
	v_mfma_f32_16x16x32_bf16 v[78:81], v[176:179], v[216:219], v[78:81]
	v_mfma_f32_16x16x32_bf16 v[74:77], v[184:187], v[216:219], v[74:77]
	s_barrier
	s_setprio 0
	s_mov_b32 m0, s47
	s_add_u32 s98, s98, 0x80
	s_addc_u32 s99, s99, 0
	s_add_u32 s100, s100, 0x80
	s_addc_u32 s101, s101, 0
	s_add_u32 s6, s6, 0x100080
	ds_read_b128 v[188:191], v165 offset:49152
	ds_read_b128 v[192:195], v165 offset:50176
	ds_read_b128 v[196:199], v165 offset:51200
	ds_read_b128 v[200:203], v165 offset:52224
	ds_read_b128 v[204:207], v165 offset:53248
	ds_read_b128 v[208:211], v165 offset:54272
	ds_read_b128 v[212:215], v165 offset:55296
	ds_read_b128 v[216:219], v165 offset:56320
	global_load_lds_dwordx4 v134, s[98:99]
	s_mov_b32 m0, s91
	s_addc_u32 s7, s7, 0
	global_load_lds_dwordx4 v130, s[98:99]
	s_mov_b32 m0, s56
	s_nop 0
	global_load_lds_dwordx4 v134, s[6:7]
	s_mov_b32 m0, s57
	s_nop 0
	global_load_lds_dwordx4 v130, s[6:7]
	s_waitcnt vmcnt(6)
	s_waitcnt lgkmcnt(0)
	s_setprio 1
	s_barrier
	v_mfma_f32_16x16x32_bf16 v[54:57], v[150:153], v[188:191], v[54:57]
	v_mfma_f32_16x16x32_bf16 v[50:53], v[158:161], v[188:191], v[50:53]
	v_mfma_f32_16x16x32_bf16 v[38:41], v[150:153], v[196:199], v[38:41]
	v_mfma_f32_16x16x32_bf16 v[34:37], v[158:161], v[196:199], v[34:37]
	v_mfma_f32_16x16x32_bf16 v[22:25], v[150:153], v[204:207], v[22:25]
	v_mfma_f32_16x16x32_bf16 v[18:21], v[158:161], v[204:207], v[18:21]
	v_mfma_f32_16x16x32_bf16 v[6:9], v[150:153], v[212:215], v[6:9]
	v_mfma_f32_16x16x32_bf16 v[2:5], v[158:161], v[212:215], v[2:5]
	v_mfma_f32_16x16x32_bf16 v[54:57], v[154:157], v[192:195], v[54:57]
	v_mfma_f32_16x16x32_bf16 v[50:53], v[168:171], v[192:195], v[50:53]
	v_mfma_f32_16x16x32_bf16 v[38:41], v[154:157], v[200:203], v[38:41]
	v_mfma_f32_16x16x32_bf16 v[34:37], v[168:171], v[200:203], v[34:37]
	v_mfma_f32_16x16x32_bf16 v[22:25], v[154:157], v[208:211], v[22:25]
	v_mfma_f32_16x16x32_bf16 v[18:21], v[168:171], v[208:211], v[18:21]
	v_mfma_f32_16x16x32_bf16 v[6:9], v[154:157], v[216:219], v[6:9]
	v_mfma_f32_16x16x32_bf16 v[2:5], v[168:171], v[216:219], v[2:5]
	s_setprio 0
	s_setprio 1
	v_mfma_f32_16x16x32_bf16 v[62:65], v[172:175], v[188:191], v[62:65]
	v_mfma_f32_16x16x32_bf16 v[58:61], v[180:183], v[188:191], v[58:61]
	v_mfma_f32_16x16x32_bf16 v[46:49], v[172:175], v[196:199], v[46:49]
	v_mfma_f32_16x16x32_bf16 v[42:45], v[180:183], v[196:199], v[42:45]
	v_mfma_f32_16x16x32_bf16 v[30:33], v[172:175], v[204:207], v[30:33]
	v_mfma_f32_16x16x32_bf16 v[26:29], v[180:183], v[204:207], v[26:29]
	v_mfma_f32_16x16x32_bf16 v[14:17], v[172:175], v[212:215], v[14:17]
	v_mfma_f32_16x16x32_bf16 v[10:13], v[180:183], v[212:215], v[10:13]
	v_mfma_f32_16x16x32_bf16 v[62:65], v[176:179], v[192:195], v[62:65]
	v_mfma_f32_16x16x32_bf16 v[58:61], v[184:187], v[192:195], v[58:61]
	v_mfma_f32_16x16x32_bf16 v[46:49], v[176:179], v[200:203], v[46:49]
	v_mfma_f32_16x16x32_bf16 v[42:45], v[184:187], v[200:203], v[42:45]
	v_mfma_f32_16x16x32_bf16 v[30:33], v[176:179], v[208:211], v[30:33]
	v_mfma_f32_16x16x32_bf16 v[26:29], v[184:187], v[208:211], v[26:29]
	v_mfma_f32_16x16x32_bf16 v[14:17], v[176:179], v[216:219], v[14:17]
	v_mfma_f32_16x16x32_bf16 v[10:13], v[184:187], v[216:219], v[10:13]
	s_barrier
	s_setprio 0
	s_add_i32 s15, s15, 2
	s_add_u32 s80, s80, 0x100
	s_addc_u32 s81, s81, 0
	s_add_u32 s30, s30, 0x100
	s_addc_u32 s14, s14, 0
	s_cmp_gt_u32 s15, 61
	s_cbranch_scc0 .LBB0_415
	s_mov_b32 m0, s96
	s_nop 0
	global_load_lds_dwordx4 v136, s[100:101]
	s_mov_b32 m0, s97
	s_nop 0
	global_load_lds_dwordx4 v132, s[100:101]
	s_and_b64 vcc, exec, s[64:65]
	s_cbranch_vccz .LBB0_418
	s_barrier

.LBB0_435:
	ds_read_b128 v[146:149], v141
	ds_read_b128 v[150:153], v141 offset:1024
	ds_read_b128 v[154:157], v141 offset:2048
	ds_read_b128 v[158:161], v141 offset:3072
	ds_read_b128 v[162:165], v142
	ds_read_b128 v[166:169], v142 offset:1024
	ds_read_b128 v[170:173], v142 offset:2048
	ds_read_b128 v[174:177], v142 offset:3072
	s_add_u32 s17, s78, 0xfff00080
	s_addc_u32 s20, s79, -1
	s_cmp_eq_u32 s16, 60
	s_cselect_b32 s81, s9, s20
	s_cselect_b32 s80, s67, s17
	s_cselect_b32 s77, s18, s15
	s_cselect_b32 s76, s95, s14
	s_cmp_eq_u32 s16, 0
	s_cbranch_scc1 .Lrb2_skip_14078
	s_mov_b32 m0, s88
	s_nop 0
	global_load_lds_dwordx4 v132, s[100:101]
	s_mov_b32 m0, s89
	s_nop 0
	global_load_lds_dwordx4 v130, s[100:101]
.Lrb2_skip_14078:
	s_mov_b32 m0, s96
	ds_read_b128 v[178:181], v143
	ds_read_b128 v[182:185], v143 offset:1024
	ds_read_b128 v[186:189], v143 offset:2048
	ds_read_b128 v[190:193], v143 offset:3072
	ds_read_b128 v[194:197], v143 offset:4096
	ds_read_b128 v[198:201], v143 offset:5120
	ds_read_b128 v[202:205], v143 offset:6144
	ds_read_b128 v[206:209], v143 offset:7168
	global_load_lds_dwordx4 v136, s[78:79]
	s_mov_b32 m0, s97
	s_nop 0
	global_load_lds_dwordx4 v138, s[78:79]
	s_waitcnt vmcnt(8)
	s_waitcnt lgkmcnt(0)
	s_setprio 1
	s_barrier
	v_mfma_f32_16x16x32_bf16 v[34:37], v[146:149], v[178:181], v[34:37]
	v_mfma_f32_16x16x32_bf16 v[38:41], v[154:157], v[178:181], v[38:41]
	v_mfma_f32_16x16x32_bf16 v[18:21], v[146:149], v[186:189], v[18:21]
	v_mfma_f32_16x16x32_bf16 v[22:25], v[154:157], v[186:189], v[22:25]
	v_mfma_f32_16x16x32_bf16 v[10:13], v[146:149], v[194:197], v[10:13]
	v_mfma_f32_16x16x32_bf16 v[14:17], v[154:157], v[194:197], v[14:17]
	v_mfma_f32_16x16x32_bf16 v[2:5], v[146:149], v[202:205], v[2:5]
	v_mfma_f32_16x16x32_bf16 v[6:9], v[154:157], v[202:205], v[6:9]
	v_mfma_f32_16x16x32_bf16 v[34:37], v[150:153], v[182:185], v[34:37]
	v_mfma_f32_16x16x32_bf16 v[38:41], v[158:161], v[182:185], v[38:41]
	v_mfma_f32_16x16x32_bf16 v[18:21], v[150:153], v[190:193], v[18:21]
	v_mfma_f32_16x16x32_bf16 v[22:25], v[158:161], v[190:193], v[22:25]
	v_mfma_f32_16x16x32_bf16 v[10:13], v[150:153], v[198:201], v[10:13]
	v_mfma_f32_16x16x32_bf16 v[14:17], v[158:161], v[198:201], v[14:17]
	v_mfma_f32_16x16x32_bf16 v[2:5], v[150:153], v[206:209], v[2:5]
	v_mfma_f32_16x16x32_bf16 v[6:9], v[158:161], v[206:209], v[6:9]
	s_setprio 0
	s_setprio 1
	v_mfma_f32_16x16x32_bf16 v[66:69], v[162:165], v[178:181], v[66:69]
	v_mfma_f32_16x16x32_bf16 v[70:73], v[170:173], v[178:181], v[70:73]
	v_mfma_f32_16x16x32_bf16 v[54:57], v[162:165], v[186:189], v[54:57]
	v_mfma_f32_16x16x32_bf16 v[62:65], v[170:173], v[186:189], v[62:65]
	v_mfma_f32_16x16x32_bf16 v[42:45], v[162:165], v[194:197], v[42:45]
	v_mfma_f32_16x16x32_bf16 v[46:49], v[170:173], v[194:197], v[46:49]
	v_mfma_f32_16x16x32_bf16 v[26:29], v[162:165], v[202:205], v[26:29]
	v_mfma_f32_16x16x32_bf16 v[30:33], v[170:173], v[202:205], v[30:33]
	v_mfma_f32_16x16x32_bf16 v[66:69], v[166:169], v[182:185], v[66:69]
	v_mfma_f32_16x16x32_bf16 v[70:73], v[174:177], v[182:185], v[70:73]
	v_mfma_f32_16x16x32_bf16 v[54:57], v[166:169], v[190:193], v[54:57]
	v_mfma_f32_16x16x32_bf16 v[62:65], v[174:177], v[190:193], v[62:65]
	v_mfma_f32_16x16x32_bf16 v[42:45], v[166:169], v[198:201], v[42:45]
	v_mfma_f32_16x16x32_bf16 v[46:49], v[174:177], v[198:201], v[46:49]
	v_mfma_f32_16x16x32_bf16 v[26:29], v[166:169], v[206:209], v[26:29]
	v_mfma_f32_16x16x32_bf16 v[30:33], v[174:177], v[206:209], v[30:33]
	s_barrier
	s_setprio 0
	s_mov_b32 m0, vcc_lo
	s_mov_b64 s[98:99], s[76:77]
	s_add_u32 s20, s76, 0x100000
	ds_read_b128 v[178:181], v143 offset:16384
	ds_read_b128 v[182:185], v143 offset:17408
	ds_read_b128 v[186:189], v143 offset:18432
	ds_read_b128 v[190:193], v143 offset:19456
	ds_read_b128 v[194:197], v143 offset:20480
	ds_read_b128 v[198:201], v143 offset:21504
	ds_read_b128 v[202:205], v143 offset:22528
	ds_read_b128 v[206:209], v143 offset:23552
	global_load_lds_dwordx4 v132, s[76:77]
	s_mov_b32 m0, s84
	s_addc_u32 s21, s77, 0
	global_load_lds_dwordx4 v130, s[76:77]
	s_mov_b32 m0, s85
	s_mov_b64 s[100:101], s[80:81]
	global_load_lds_dwordx4 v132, s[20:21]
	s_mov_b32 m0, s46
	s_nop 0
	global_load_lds_dwordx4 v130, s[20:21]
	s_waitcnt vmcnt(6)
	s_waitcnt lgkmcnt(0)
	s_setprio 1
	s_barrier
	v_mfma_f32_16x16x32_bf16 v[102:105], v[146:149], v[178:181], v[102:105]
	v_mfma_f32_16x16x32_bf16 v[110:113], v[154:157], v[178:181], v[110:113]
	v_mfma_f32_16x16x32_bf16 v[90:93], v[146:149], v[186:189], v[90:93]
	v_mfma_f32_16x16x32_bf16 v[94:97], v[154:157], v[186:189], v[94:97]
	v_mfma_f32_16x16x32_bf16 v[74:77], v[146:149], v[194:197], v[74:77]
	v_mfma_f32_16x16x32_bf16 v[78:81], v[154:157], v[194:197], v[78:81]
	v_mfma_f32_16x16x32_bf16 v[50:53], v[146:149], v[202:205], v[50:53]
	v_mfma_f32_16x16x32_bf16 v[58:61], v[154:157], v[202:205], v[58:61]
	v_mfma_f32_16x16x32_bf16 v[102:105], v[150:153], v[182:185], v[102:105]
	v_mfma_f32_16x16x32_bf16 v[110:113], v[158:161], v[182:185], v[110:113]
	v_mfma_f32_16x16x32_bf16 v[90:93], v[150:153], v[190:193], v[90:93]
	v_mfma_f32_16x16x32_bf16 v[94:97], v[158:161], v[190:193], v[94:97]
	v_mfma_f32_16x16x32_bf16 v[74:77], v[150:153], v[198:201], v[74:77]
	v_mfma_f32_16x16x32_bf16 v[78:81], v[158:161], v[198:201], v[78:81]
	v_mfma_f32_16x16x32_bf16 v[50:53], v[150:153], v[206:209], v[50:53]
	v_mfma_f32_16x16x32_bf16 v[58:61], v[158:161], v[206:209], v[58:61]
	s_setprio 0
	s_setprio 1
	v_mfma_f32_16x16x32_bf16 v[122:125], v[162:165], v[178:181], v[122:125]
	v_mfma_f32_16x16x32_bf16 v[126:129], v[170:173], v[178:181], v[126:129]
	v_mfma_f32_16x16x32_bf16 v[114:117], v[162:165], v[186:189], v[114:117]
	v_mfma_f32_16x16x32_bf16 v[118:121], v[170:173], v[186:189], v[118:121]
	v_mfma_f32_16x16x32_bf16 v[98:101], v[162:165], v[194:197], v[98:101]
	v_mfma_f32_16x16x32_bf16 v[106:109], v[170:173], v[194:197], v[106:109]
	v_mfma_f32_16x16x32_bf16 v[82:85], v[162:165], v[202:205], v[82:85]
	v_mfma_f32_16x16x32_bf16 v[86:89], v[170:173], v[202:205], v[86:89]
	v_mfma_f32_16x16x32_bf16 v[122:125], v[166:169], v[182:185], v[122:125]
	v_mfma_f32_16x16x32_bf16 v[126:129], v[174:177], v[182:185], v[126:129]
	v_mfma_f32_16x16x32_bf16 v[114:117], v[166:169], v[190:193], v[114:117]
	v_mfma_f32_16x16x32_bf16 v[118:121], v[174:177], v[190:193], v[118:121]
	v_mfma_f32_16x16x32_bf16 v[98:101], v[166:169], v[198:201], v[98:101]
	v_mfma_f32_16x16x32_bf16 v[106:109], v[174:177], v[198:201], v[106:109]
	v_mfma_f32_16x16x32_bf16 v[82:85], v[166:169], v[206:209], v[82:85]
	v_mfma_f32_16x16x32_bf16 v[86:89], v[174:177], v[206:209], v[86:89]
	s_barrier
; #define PG8_BAR __builtin_amdgcn_s_barrier()
;     ...
;         for (int t = 2; t < nt; t += 2) PG8_KITER(t);
;         if constexpr (ALIGN_EPI) { if (wr == 0) PG8_BAR; }
	s_setprio 0
	ds_read_b128 v[146:149], v134
	ds_read_b128 v[150:153], v134 offset:1024
	ds_read_b128 v[154:157], v134 offset:2048
	ds_read_b128 v[158:161], v134 offset:3072
	ds_read_b128 v[162:165], v144
	ds_read_b128 v[166:169], v144 offset:1024
	ds_read_b128 v[170:173], v144 offset:2048
	ds_read_b128 v[174:177], v144 offset:3072
	s_add_u32 s20, s80, 0x100000
	s_addc_u32 s21, s81, 0
	s_mov_b32 m0, s59
	s_nop 0
	global_load_lds_dwordx4 v132, s[100:101]
	s_mov_b32 m0, s82
	s_nop 0
	global_load_lds_dwordx4 v130, s[100:101]
	s_mov_b32 m0, s83
	ds_read_b128 v[178:181], v143 offset:32768
	ds_read_b128 v[182:185], v143 offset:33792
	ds_read_b128 v[186:189], v143 offset:34816
	ds_read_b128 v[190:193], v143 offset:35840
	ds_read_b128 v[194:197], v143 offset:36864
	ds_read_b128 v[198:201], v143 offset:37888
	ds_read_b128 v[202:205], v143 offset:38912
	ds_read_b128 v[206:209], v143 offset:39936
	global_load_lds_dwordx4 v132, s[20:21]
	s_mov_b32 m0, s86
	s_nop 0
	global_load_lds_dwordx4 v130, s[20:21]
	s_waitcnt vmcnt(8)
	s_waitcnt lgkmcnt(0)
	s_setprio 1
	s_barrier
	v_mfma_f32_16x16x32_bf16 v[34:37], v[146:149], v[178:181], v[34:37]
	v_mfma_f32_16x16x32_bf16 v[38:41], v[154:157], v[178:181], v[38:41]
	v_mfma_f32_16x16x32_bf16 v[18:21], v[146:149], v[186:189], v[18:21]
	v_mfma_f32_16x16x32_bf16 v[22:25], v[154:157], v[186:189], v[22:25]
	v_mfma_f32_16x16x32_bf16 v[10:13], v[146:149], v[194:197], v[10:13]
	v_mfma_f32_16x16x32_bf16 v[14:17], v[154:157], v[194:197], v[14:17]
	v_mfma_f32_16x16x32_bf16 v[2:5], v[146:149], v[202:205], v[2:5]
	v_mfma_f32_16x16x32_bf16 v[6:9], v[154:157], v[202:205], v[6:9]
	v_mfma_f32_16x16x32_bf16 v[34:37], v[150:153], v[182:185], v[34:37]
	v_mfma_f32_16x16x32_bf16 v[38:41], v[158:161], v[182:185], v[38:41]
	v_mfma_f32_16x16x32_bf16 v[18:21], v[150:153], v[190:193], v[18:21]
	v_mfma_f32_16x16x32_bf16 v[22:25], v[158:161], v[190:193], v[22:25]
	v_mfma_f32_16x16x32_bf16 v[10:13], v[150:153], v[198:201], v[10:13]
	v_mfma_f32_16x16x32_bf16 v[14:17], v[158:161], v[198:201], v[14:17]
	v_mfma_f32_16x16x32_bf16 v[2:5], v[150:153], v[206:209], v[2:5]
	v_mfma_f32_16x16x32_bf16 v[6:9], v[158:161], v[206:209], v[6:9]
	s_setprio 0
	s_setprio 1
	v_mfma_f32_16x16x32_bf16 v[66:69], v[162:165], v[178:181], v[66:69]
	v_mfma_f32_16x16x32_bf16 v[70:73], v[170:173], v[178:181], v[70:73]
	v_mfma_f32_16x16x32_bf16 v[54:57], v[162:165], v[186:189], v[54:57]
	v_mfma_f32_16x16x32_bf16 v[62:65], v[170:173], v[186:189], v[62:65]
	v_mfma_f32_16x16x32_bf16 v[42:45], v[162:165], v[194:197], v[42:45]
	v_mfma_f32_16x16x32_bf16 v[46:49], v[170:173], v[194:197], v[46:49]
	v_mfma_f32_16x16x32_bf16 v[26:29], v[162:165], v[202:205], v[26:29]
	v_mfma_f32_16x16x32_bf16 v[30:33], v[170:173], v[202:205], v[30:33]
	v_mfma_f32_16x16x32_bf16 v[66:69], v[166:169], v[182:185], v[66:69]
	v_mfma_f32_16x16x32_bf16 v[70:73], v[174:177], v[182:185], v[70:73]
	v_mfma_f32_16x16x32_bf16 v[54:57], v[166:169], v[190:193], v[54:57]
	v_mfma_f32_16x16x32_bf16 v[62:65], v[174:177], v[190:193], v[62:65]
	v_mfma_f32_16x16x32_bf16 v[42:45], v[166:169], v[198:201], v[42:45]
	v_mfma_f32_16x16x32_bf16 v[46:49], v[174:177], v[198:201], v[46:49]
	v_mfma_f32_16x16x32_bf16 v[26:29], v[166:169], v[206:209], v[26:29]
	v_mfma_f32_16x16x32_bf16 v[30:33], v[174:177], v[206:209], v[30:33]
	s_barrier
	s_setprio 0
	s_mov_b32 m0, s47
	s_add_u32 s98, s98, 0x80
	s_addc_u32 s99, s99, 0
	s_add_u32 s100, s100, 0x80
	s_addc_u32 s101, s101, 0
	s_add_u32 s20, s76, 0x100080
	ds_read_b128 v[178:181], v143 offset:49152
	ds_read_b128 v[182:185], v143 offset:50176
	ds_read_b128 v[186:189], v143 offset:51200
	ds_read_b128 v[190:193], v143 offset:52224
	ds_read_b128 v[194:197], v143 offset:53248
	ds_read_b128 v[198:201], v143 offset:54272
	ds_read_b128 v[202:205], v143 offset:55296
	ds_read_b128 v[206:209], v143 offset:56320
	global_load_lds_dwordx4 v132, s[98:99]
	s_mov_b32 m0, vcc_hi
	s_addc_u32 s21, s77, 0
	global_load_lds_dwordx4 v130, s[98:99]
	s_mov_b32 m0, s56
	s_nop 0
	global_load_lds_dwordx4 v132, s[20:21]
	s_mov_b32 m0, s57
	s_nop 0
	global_load_lds_dwordx4 v130, s[20:21]
	s_waitcnt vmcnt(6)
	s_waitcnt lgkmcnt(0)
	s_setprio 1
	s_barrier
	v_mfma_f32_16x16x32_bf16 v[102:105], v[146:149], v[178:181], v[102:105]
	v_mfma_f32_16x16x32_bf16 v[110:113], v[154:157], v[178:181], v[110:113]
	v_mfma_f32_16x16x32_bf16 v[90:93], v[146:149], v[186:189], v[90:93]
	v_mfma_f32_16x16x32_bf16 v[94:97], v[154:157], v[186:189], v[94:97]
	v_mfma_f32_16x16x32_bf16 v[74:77], v[146:149], v[194:197], v[74:77]
	v_mfma_f32_16x16x32_bf16 v[78:81], v[154:157], v[194:197], v[78:81]
	v_mfma_f32_16x16x32_bf16 v[50:53], v[146:149], v[202:205], v[50:53]
	v_mfma_f32_16x16x32_bf16 v[58:61], v[154:157], v[202:205], v[58:61]
	v_mfma_f32_16x16x32_bf16 v[102:105], v[150:153], v[182:185], v[102:105]
	v_mfma_f32_16x16x32_bf16 v[110:113], v[158:161], v[182:185], v[110:113]
	v_mfma_f32_16x16x32_bf16 v[90:93], v[150:153], v[190:193], v[90:93]
	v_mfma_f32_16x16x32_bf16 v[94:97], v[158:161], v[190:193], v[94:97]
	v_mfma_f32_16x16x32_bf16 v[74:77], v[150:153], v[198:201], v[74:77]
	v_mfma_f32_16x16x32_bf16 v[78:81], v[158:161], v[198:201], v[78:81]
	v_mfma_f32_16x16x32_bf16 v[50:53], v[150:153], v[206:209], v[50:53]
	v_mfma_f32_16x16x32_bf16 v[58:61], v[158:161], v[206:209], v[58:61]
	s_setprio 0
	s_setprio 1
	v_mfma_f32_16x16x32_bf16 v[122:125], v[162:165], v[178:181], v[122:125]
	v_mfma_f32_16x16x32_bf16 v[126:129], v[170:173], v[178:181], v[126:129]
	v_mfma_f32_16x16x32_bf16 v[114:117], v[162:165], v[186:189], v[114:117]
	v_mfma_f32_16x16x32_bf16 v[118:121], v[170:173], v[186:189], v[118:121]
	v_mfma_f32_16x16x32_bf16 v[98:101], v[162:165], v[194:197], v[98:101]
	v_mfma_f32_16x16x32_bf16 v[106:109], v[170:173], v[194:197], v[106:109]
	v_mfma_f32_16x16x32_bf16 v[82:85], v[162:165], v[202:205], v[82:85]
	v_mfma_f32_16x16x32_bf16 v[86:89], v[170:173], v[202:205], v[86:89]
	v_mfma_f32_16x16x32_bf16 v[122:125], v[166:169], v[182:185], v[122:125]
	v_mfma_f32_16x16x32_bf16 v[126:129], v[174:177], v[182:185], v[126:129]
	v_mfma_f32_16x16x32_bf16 v[114:117], v[166:169], v[190:193], v[114:117]
	v_mfma_f32_16x16x32_bf16 v[118:121], v[174:177], v[190:193], v[118:121]
	v_mfma_f32_16x16x32_bf16 v[98:101], v[166:169], v[198:201], v[98:101]
	v_mfma_f32_16x16x32_bf16 v[106:109], v[174:177], v[198:201], v[106:109]
	v_mfma_f32_16x16x32_bf16 v[82:85], v[166:169], v[206:209], v[82:85]
	v_mfma_f32_16x16x32_bf16 v[86:89], v[174:177], v[206:209], v[86:89]
	s_barrier
	s_setprio 0
	s_add_i32 s16, s16, 2
	s_add_u32 s78, s78, 0x100
	s_addc_u32 s79, s79, 0
	s_add_u32 s14, s14, 0x100
	s_addc_u32 s15, s15, 0
	s_cmp_gt_u32 s16, 61
	s_cbranch_scc0 .LBB0_435
	s_mov_b32 m0, s88
	s_nop 0
	global_load_lds_dwordx4 v132, s[100:101]
	s_mov_b32 m0, s89
	s_nop 0
	global_load_lds_dwordx4 v130, s[100:101]
	s_and_b64 vcc, exec, s[30:31]
	s_cbranch_vccz .LBB0_438
	s_barrier

.LBB0_644:
	ds_read_b128 v[146:149], v1
	ds_read_b128 v[154:157], v1 offset:1024
	ds_read_b128 v[158:161], v1 offset:2048
	ds_read_b128 v[162:165], v1 offset:3072
	ds_read_b128 v[166:169], v150
	ds_read_b128 v[170:173], v150 offset:1024
	ds_read_b128 v[174:177], v150 offset:2048
	ds_read_b128 v[178:181], v150 offset:3072
	s_add_u32 s27, s62, 0xfffc0080
	s_addc_u32 s46, s63, -1
	s_cmp_eq_u32 s26, 12
	s_cselect_b32 s65, s23, s46
	s_cselect_b32 s64, s83, s27
	s_cselect_b32 s55, s0, s15
	s_cselect_b32 s54, s86, s14
	s_cmp_eq_u32 s26, 0
	s_cbranch_scc1 .Lrb2_skip_18937
	s_mov_b32 m0, s66
	s_nop 0
	global_load_lds_dwordx4 v136, s[100:101]
	s_mov_b32 m0, s67
	s_nop 0
	global_load_lds_dwordx4 v132, s[100:101]
.Lrb2_skip_18937:
	s_mov_b32 m0, s69
	ds_read_b128 v[182:185], v151
	ds_read_b128 v[186:189], v151 offset:1024
	ds_read_b128 v[190:193], v151 offset:2048
	ds_read_b128 v[194:197], v151 offset:3072
	ds_read_b128 v[198:201], v151 offset:4096
	ds_read_b128 v[202:205], v151 offset:5120
	ds_read_b128 v[206:209], v151 offset:6144
	ds_read_b128 v[210:213], v151 offset:7168
	global_load_lds_dwordx4 v138, s[62:63]
	s_mov_b32 m0, s70
	s_nop 0
	global_load_lds_dwordx4 v140, s[62:63]
	s_waitcnt vmcnt(8)
	s_waitcnt lgkmcnt(0)
	s_setprio 1
	s_barrier
	v_mfma_f32_16x16x32_bf16 v[122:125], v[146:149], v[182:185], v[122:125]
	v_mfma_f32_16x16x32_bf16 v[114:117], v[158:161], v[182:185], v[114:117]
	v_mfma_f32_16x16x32_bf16 v[106:109], v[146:149], v[190:193], v[106:109]
	v_mfma_f32_16x16x32_bf16 v[98:101], v[158:161], v[190:193], v[98:101]
	v_mfma_f32_16x16x32_bf16 v[90:93], v[146:149], v[198:201], v[90:93]
	v_mfma_f32_16x16x32_bf16 v[82:85], v[158:161], v[198:201], v[82:85]
	v_mfma_f32_16x16x32_bf16 v[58:61], v[146:149], v[206:209], v[58:61]
	v_mfma_f32_16x16x32_bf16 v[50:53], v[158:161], v[206:209], v[50:53]
	v_mfma_f32_16x16x32_bf16 v[122:125], v[154:157], v[186:189], v[122:125]
	v_mfma_f32_16x16x32_bf16 v[114:117], v[162:165], v[186:189], v[114:117]
	v_mfma_f32_16x16x32_bf16 v[106:109], v[154:157], v[194:197], v[106:109]
	v_mfma_f32_16x16x32_bf16 v[98:101], v[162:165], v[194:197], v[98:101]
	v_mfma_f32_16x16x32_bf16 v[90:93], v[154:157], v[202:205], v[90:93]
	v_mfma_f32_16x16x32_bf16 v[82:85], v[162:165], v[202:205], v[82:85]
	v_mfma_f32_16x16x32_bf16 v[58:61], v[154:157], v[210:213], v[58:61]
	v_mfma_f32_16x16x32_bf16 v[50:53], v[162:165], v[210:213], v[50:53]
	s_setprio 0
	s_setprio 1
	v_mfma_f32_16x16x32_bf16 v[126:129], v[166:169], v[182:185], v[126:129]
	v_mfma_f32_16x16x32_bf16 v[118:121], v[174:177], v[182:185], v[118:121]
	v_mfma_f32_16x16x32_bf16 v[110:113], v[166:169], v[190:193], v[110:113]
	v_mfma_f32_16x16x32_bf16 v[102:105], v[174:177], v[190:193], v[102:105]
	v_mfma_f32_16x16x32_bf16 v[94:97], v[166:169], v[198:201], v[94:97]
	v_mfma_f32_16x16x32_bf16 v[86:89], v[174:177], v[198:201], v[86:89]
	v_mfma_f32_16x16x32_bf16 v[62:65], v[166:169], v[206:209], v[62:65]
	v_mfma_f32_16x16x32_bf16 v[54:57], v[174:177], v[206:209], v[54:57]
	v_mfma_f32_16x16x32_bf16 v[126:129], v[170:173], v[186:189], v[126:129]
	v_mfma_f32_16x16x32_bf16 v[118:121], v[178:181], v[186:189], v[118:121]
	v_mfma_f32_16x16x32_bf16 v[110:113], v[170:173], v[194:197], v[110:113]
	v_mfma_f32_16x16x32_bf16 v[102:105], v[178:181], v[194:197], v[102:105]
	v_mfma_f32_16x16x32_bf16 v[94:97], v[170:173], v[202:205], v[94:97]
	v_mfma_f32_16x16x32_bf16 v[86:89], v[178:181], v[202:205], v[86:89]
	v_mfma_f32_16x16x32_bf16 v[62:65], v[170:173], v[210:213], v[62:65]
	v_mfma_f32_16x16x32_bf16 v[54:57], v[178:181], v[210:213], v[54:57]
	s_barrier
	s_setprio 0
	s_mov_b32 m0, s72
	s_mov_b64 s[98:99], s[54:55]
	s_add_u32 s46, s54, 0x40000
	ds_read_b128 v[182:185], v151 offset:16384
	ds_read_b128 v[186:189], v151 offset:17408
	ds_read_b128 v[190:193], v151 offset:18432
	ds_read_b128 v[194:197], v151 offset:19456
	ds_read_b128 v[198:201], v151 offset:20480
	ds_read_b128 v[202:205], v151 offset:21504
	ds_read_b128 v[206:209], v151 offset:22528
	ds_read_b128 v[210:213], v151 offset:23552
	global_load_lds_dwordx4 v134, s[54:55]
	s_mov_b32 m0, s73
	s_addc_u32 s47, s55, 0
	global_load_lds_dwordx4 v130, s[54:55]
	s_mov_b32 m0, s74
	s_mov_b64 s[100:101], s[64:65]
	global_load_lds_dwordx4 v134, s[46:47]
	s_mov_b32 m0, s75
	s_nop 0
	global_load_lds_dwordx4 v130, s[46:47]
	s_waitcnt vmcnt(6)
	s_waitcnt lgkmcnt(0)
	s_setprio 1
	s_barrier
	v_mfma_f32_16x16x32_bf16 v[74:77], v[146:149], v[182:185], v[74:77]
	v_mfma_f32_16x16x32_bf16 v[66:69], v[158:161], v[182:185], v[66:69]
	v_mfma_f32_16x16x32_bf16 v[42:45], v[146:149], v[190:193], v[42:45]
	v_mfma_f32_16x16x32_bf16 v[34:37], v[158:161], v[190:193], v[34:37]
	v_mfma_f32_16x16x32_bf16 v[26:29], v[146:149], v[198:201], v[26:29]
	v_mfma_f32_16x16x32_bf16 v[18:21], v[158:161], v[198:201], v[18:21]
	v_mfma_f32_16x16x32_bf16 v[10:13], v[146:149], v[206:209], v[10:13]
	v_mfma_f32_16x16x32_bf16 v[2:5], v[158:161], v[206:209], v[2:5]
	v_mfma_f32_16x16x32_bf16 v[74:77], v[154:157], v[186:189], v[74:77]
	v_mfma_f32_16x16x32_bf16 v[66:69], v[162:165], v[186:189], v[66:69]
	v_mfma_f32_16x16x32_bf16 v[42:45], v[154:157], v[194:197], v[42:45]
	v_mfma_f32_16x16x32_bf16 v[34:37], v[162:165], v[194:197], v[34:37]
	v_mfma_f32_16x16x32_bf16 v[26:29], v[154:157], v[202:205], v[26:29]
	v_mfma_f32_16x16x32_bf16 v[18:21], v[162:165], v[202:205], v[18:21]
	v_mfma_f32_16x16x32_bf16 v[10:13], v[154:157], v[210:213], v[10:13]
	v_mfma_f32_16x16x32_bf16 v[2:5], v[162:165], v[210:213], v[2:5]
	s_setprio 0
	s_setprio 1
	v_mfma_f32_16x16x32_bf16 v[78:81], v[166:169], v[182:185], v[78:81]
	v_mfma_f32_16x16x32_bf16 v[70:73], v[174:177], v[182:185], v[70:73]
	v_mfma_f32_16x16x32_bf16 v[46:49], v[166:169], v[190:193], v[46:49]
	v_mfma_f32_16x16x32_bf16 v[38:41], v[174:177], v[190:193], v[38:41]
	v_mfma_f32_16x16x32_bf16 v[30:33], v[166:169], v[198:201], v[30:33]
	v_mfma_f32_16x16x32_bf16 v[22:25], v[174:177], v[198:201], v[22:25]
	v_mfma_f32_16x16x32_bf16 v[14:17], v[166:169], v[206:209], v[14:17]
	v_mfma_f32_16x16x32_bf16 v[6:9], v[174:177], v[206:209], v[6:9]
	v_mfma_f32_16x16x32_bf16 v[78:81], v[170:173], v[186:189], v[78:81]
	v_mfma_f32_16x16x32_bf16 v[70:73], v[178:181], v[186:189], v[70:73]
	v_mfma_f32_16x16x32_bf16 v[46:49], v[170:173], v[194:197], v[46:49]
	v_mfma_f32_16x16x32_bf16 v[38:41], v[178:181], v[194:197], v[38:41]
	v_mfma_f32_16x16x32_bf16 v[30:33], v[170:173], v[202:205], v[30:33]
	v_mfma_f32_16x16x32_bf16 v[22:25], v[178:181], v[202:205], v[22:25]
	v_mfma_f32_16x16x32_bf16 v[14:17], v[170:173], v[210:213], v[14:17]
	v_mfma_f32_16x16x32_bf16 v[6:9], v[178:181], v[210:213], v[6:9]
	s_barrier
; #define PG8_BAR __builtin_amdgcn_s_barrier()
;     ...
;         for (int t = 2; t < nt; t += 2) PG8_KITER(t);
;         if constexpr (ALIGN_EPI) { if (wr == 0) PG8_BAR; }
	s_setprio 0
	ds_read_b128 v[146:149], v152
	ds_read_b128 v[154:157], v152 offset:1024
	ds_read_b128 v[158:161], v152 offset:2048
	ds_read_b128 v[162:165], v152 offset:3072
	ds_read_b128 v[166:169], v153
	ds_read_b128 v[170:173], v153 offset:1024
	ds_read_b128 v[174:177], v153 offset:2048
	ds_read_b128 v[178:181], v153 offset:3072
	s_add_u32 s46, s64, 0x40000
	s_addc_u32 s47, s65, 0
	s_mov_b32 m0, s33
	s_nop 0
	global_load_lds_dwordx4 v136, s[100:101]
	s_mov_b32 m0, s41
	s_nop 0
	global_load_lds_dwordx4 v132, s[100:101]
	s_mov_b32 m0, s58
	ds_read_b128 v[182:185], v151 offset:32768
	ds_read_b128 v[186:189], v151 offset:33792
	ds_read_b128 v[190:193], v151 offset:34816
	ds_read_b128 v[194:197], v151 offset:35840
	ds_read_b128 v[198:201], v151 offset:36864
	ds_read_b128 v[202:205], v151 offset:37888
	ds_read_b128 v[206:209], v151 offset:38912
	ds_read_b128 v[210:213], v151 offset:39936
	global_load_lds_dwordx4 v136, s[46:47]
	s_mov_b32 m0, s59
	s_nop 0
	global_load_lds_dwordx4 v132, s[46:47]
	s_waitcnt vmcnt(8)
	s_waitcnt lgkmcnt(0)
	s_setprio 1
	s_barrier
	v_mfma_f32_16x16x32_bf16 v[122:125], v[146:149], v[182:185], v[122:125]
	v_mfma_f32_16x16x32_bf16 v[114:117], v[158:161], v[182:185], v[114:117]
	v_mfma_f32_16x16x32_bf16 v[106:109], v[146:149], v[190:193], v[106:109]
	v_mfma_f32_16x16x32_bf16 v[98:101], v[158:161], v[190:193], v[98:101]
	v_mfma_f32_16x16x32_bf16 v[90:93], v[146:149], v[198:201], v[90:93]
	v_mfma_f32_16x16x32_bf16 v[82:85], v[158:161], v[198:201], v[82:85]
	v_mfma_f32_16x16x32_bf16 v[58:61], v[146:149], v[206:209], v[58:61]
	v_mfma_f32_16x16x32_bf16 v[50:53], v[158:161], v[206:209], v[50:53]
	v_mfma_f32_16x16x32_bf16 v[122:125], v[154:157], v[186:189], v[122:125]
	v_mfma_f32_16x16x32_bf16 v[114:117], v[162:165], v[186:189], v[114:117]
	v_mfma_f32_16x16x32_bf16 v[106:109], v[154:157], v[194:197], v[106:109]
	v_mfma_f32_16x16x32_bf16 v[98:101], v[162:165], v[194:197], v[98:101]
	v_mfma_f32_16x16x32_bf16 v[90:93], v[154:157], v[202:205], v[90:93]
	v_mfma_f32_16x16x32_bf16 v[82:85], v[162:165], v[202:205], v[82:85]
	v_mfma_f32_16x16x32_bf16 v[58:61], v[154:157], v[210:213], v[58:61]
	v_mfma_f32_16x16x32_bf16 v[50:53], v[162:165], v[210:213], v[50:53]
	s_setprio 0
	s_setprio 1
	v_mfma_f32_16x16x32_bf16 v[126:129], v[166:169], v[182:185], v[126:129]
	v_mfma_f32_16x16x32_bf16 v[118:121], v[174:177], v[182:185], v[118:121]
	v_mfma_f32_16x16x32_bf16 v[110:113], v[166:169], v[190:193], v[110:113]
	v_mfma_f32_16x16x32_bf16 v[102:105], v[174:177], v[190:193], v[102:105]
	v_mfma_f32_16x16x32_bf16 v[94:97], v[166:169], v[198:201], v[94:97]
	v_mfma_f32_16x16x32_bf16 v[86:89], v[174:177], v[198:201], v[86:89]
	v_mfma_f32_16x16x32_bf16 v[62:65], v[166:169], v[206:209], v[62:65]
	v_mfma_f32_16x16x32_bf16 v[54:57], v[174:177], v[206:209], v[54:57]
	v_mfma_f32_16x16x32_bf16 v[126:129], v[170:173], v[186:189], v[126:129]
	v_mfma_f32_16x16x32_bf16 v[118:121], v[178:181], v[186:189], v[118:121]
	v_mfma_f32_16x16x32_bf16 v[110:113], v[170:173], v[194:197], v[110:113]
	v_mfma_f32_16x16x32_bf16 v[102:105], v[178:181], v[194:197], v[102:105]
	v_mfma_f32_16x16x32_bf16 v[94:97], v[170:173], v[202:205], v[94:97]
	v_mfma_f32_16x16x32_bf16 v[86:89], v[178:181], v[202:205], v[86:89]
	v_mfma_f32_16x16x32_bf16 v[62:65], v[170:173], v[210:213], v[62:65]
	v_mfma_f32_16x16x32_bf16 v[54:57], v[178:181], v[210:213], v[54:57]
	s_barrier
	s_setprio 0
	s_mov_b32 m0, s76
	s_add_u32 s98, s98, 0x80
	s_addc_u32 s99, s99, 0
	s_add_u32 s100, s100, 0x80
	s_addc_u32 s101, s101, 0
	s_add_u32 s46, s54, 0x40080
	ds_read_b128 v[182:185], v151 offset:49152
	ds_read_b128 v[186:189], v151 offset:50176
	ds_read_b128 v[190:193], v151 offset:51200
	ds_read_b128 v[194:197], v151 offset:52224
	ds_read_b128 v[198:201], v151 offset:53248
	ds_read_b128 v[202:205], v151 offset:54272
	ds_read_b128 v[206:209], v151 offset:55296
	ds_read_b128 v[210:213], v151 offset:56320
	global_load_lds_dwordx4 v134, s[98:99]
	s_mov_b32 m0, s77
	s_addc_u32 s47, s55, 0
	global_load_lds_dwordx4 v130, s[98:99]
	s_mov_b32 m0, s78
	s_nop 0
	global_load_lds_dwordx4 v134, s[46:47]
	s_mov_b32 m0, s79
	s_nop 0
	global_load_lds_dwordx4 v130, s[46:47]
	s_waitcnt vmcnt(6)
	s_waitcnt lgkmcnt(0)
	s_setprio 1
	s_barrier
	v_mfma_f32_16x16x32_bf16 v[74:77], v[146:149], v[182:185], v[74:77]
	v_mfma_f32_16x16x32_bf16 v[66:69], v[158:161], v[182:185], v[66:69]
	v_mfma_f32_16x16x32_bf16 v[42:45], v[146:149], v[190:193], v[42:45]
	v_mfma_f32_16x16x32_bf16 v[34:37], v[158:161], v[190:193], v[34:37]
	v_mfma_f32_16x16x32_bf16 v[26:29], v[146:149], v[198:201], v[26:29]
	v_mfma_f32_16x16x32_bf16 v[18:21], v[158:161], v[198:201], v[18:21]
	v_mfma_f32_16x16x32_bf16 v[10:13], v[146:149], v[206:209], v[10:13]
	v_mfma_f32_16x16x32_bf16 v[2:5], v[158:161], v[206:209], v[2:5]
	v_mfma_f32_16x16x32_bf16 v[74:77], v[154:157], v[186:189], v[74:77]
	v_mfma_f32_16x16x32_bf16 v[66:69], v[162:165], v[186:189], v[66:69]
	v_mfma_f32_16x16x32_bf16 v[42:45], v[154:157], v[194:197], v[42:45]
	v_mfma_f32_16x16x32_bf16 v[34:37], v[162:165], v[194:197], v[34:37]
	v_mfma_f32_16x16x32_bf16 v[26:29], v[154:157], v[202:205], v[26:29]
	v_mfma_f32_16x16x32_bf16 v[18:21], v[162:165], v[202:205], v[18:21]
	v_mfma_f32_16x16x32_bf16 v[10:13], v[154:157], v[210:213], v[10:13]
	v_mfma_f32_16x16x32_bf16 v[2:5], v[162:165], v[210:213], v[2:5]
	s_setprio 0
	s_setprio 1
	v_mfma_f32_16x16x32_bf16 v[78:81], v[166:169], v[182:185], v[78:81]
	v_mfma_f32_16x16x32_bf16 v[70:73], v[174:177], v[182:185], v[70:73]
	v_mfma_f32_16x16x32_bf16 v[46:49], v[166:169], v[190:193], v[46:49]
	v_mfma_f32_16x16x32_bf16 v[38:41], v[174:177], v[190:193], v[38:41]
	v_mfma_f32_16x16x32_bf16 v[30:33], v[166:169], v[198:201], v[30:33]
	v_mfma_f32_16x16x32_bf16 v[22:25], v[174:177], v[198:201], v[22:25]
	v_mfma_f32_16x16x32_bf16 v[14:17], v[166:169], v[206:209], v[14:17]
	v_mfma_f32_16x16x32_bf16 v[6:9], v[174:177], v[206:209], v[6:9]
	v_mfma_f32_16x16x32_bf16 v[78:81], v[170:173], v[186:189], v[78:81]
	v_mfma_f32_16x16x32_bf16 v[70:73], v[178:181], v[186:189], v[70:73]
	v_mfma_f32_16x16x32_bf16 v[46:49], v[170:173], v[194:197], v[46:49]
	v_mfma_f32_16x16x32_bf16 v[38:41], v[178:181], v[194:197], v[38:41]
	v_mfma_f32_16x16x32_bf16 v[30:33], v[170:173], v[202:205], v[30:33]
	v_mfma_f32_16x16x32_bf16 v[22:25], v[178:181], v[202:205], v[22:25]
	v_mfma_f32_16x16x32_bf16 v[14:17], v[170:173], v[210:213], v[14:17]
	v_mfma_f32_16x16x32_bf16 v[6:9], v[178:181], v[210:213], v[6:9]
	s_barrier
	s_setprio 0
	s_add_i32 s26, s26, 2
	s_add_u32 s62, s62, 0x100
	s_addc_u32 s63, s63, 0
	s_add_u32 s14, s14, 0x100
	s_addc_u32 s15, s15, 0
	s_cmp_gt_u32 s26, 13
	s_cbranch_scc0 .LBB0_644
	s_mov_b32 m0, s66
	s_nop 0
	global_load_lds_dwordx4 v136, s[100:101]
	s_mov_b32 m0, s67
	s_nop 0
	global_load_lds_dwordx4 v132, s[100:101]
	s_and_b64 vcc, exec, s[16:17]
	s_cbranch_vccz .LBB0_647
	s_barrier

.LBB0_670:
	ds_read_b128 v[132:135], v158
	ds_read_b128 v[154:157], v158 offset:1024
	ds_read_b128 v[162:165], v158 offset:2048
	ds_read_b128 v[166:169], v158 offset:3072
	ds_read_b128 v[170:173], v159
	ds_read_b128 v[174:177], v159 offset:1024
	ds_read_b128 v[178:181], v159 offset:2048
	ds_read_b128 v[182:185], v159 offset:3072
	s_add_u32 s6, s64, 0xfffe0080
	s_addc_u32 s7, s65, -1
	s_cmp_eq_u32 s26, 4
	s_cselect_b32 s67, s29, s7
	s_cselect_b32 s66, s79, s6
	s_cselect_b32 s7, s0, s15
	s_cselect_b32 s6, s80, s14
	s_cmp_eq_u32 s26, 0
	s_cbranch_scc1 .Lrb2_skip_20202
	s_mov_b32 m0, s69
	s_nop 0
	global_load_lds_dwordx4 v138, s[100:101]
	s_mov_b32 m0, s70
	s_nop 0
	global_load_lds_dwordx4 v142, s[100:101]
.Lrb2_skip_20202:
	s_mov_b32 m0, s81
	ds_read_b128 v[186:189], v160
	ds_read_b128 v[190:193], v160 offset:1024
	ds_read_b128 v[194:197], v160 offset:2048
	ds_read_b128 v[198:201], v160 offset:3072
	ds_read_b128 v[202:205], v160 offset:4096
	ds_read_b128 v[206:209], v160 offset:5120
	ds_read_b128 v[210:213], v160 offset:6144
	ds_read_b128 v[214:217], v160 offset:7168
	global_load_lds_dwordx4 v146, s[64:65]
	s_mov_b32 m0, s82
	s_nop 0
	global_load_lds_dwordx4 v148, s[64:65]
	s_waitcnt vmcnt(8)
	s_waitcnt lgkmcnt(0)
	s_setprio 1
	s_barrier
	v_mfma_f32_16x16x32_bf16 v[118:121], v[132:135], v[186:189], v[118:121]
	v_mfma_f32_16x16x32_bf16 v[114:117], v[162:165], v[186:189], v[114:117]
	v_mfma_f32_16x16x32_bf16 v[110:113], v[132:135], v[194:197], v[110:113]
	v_mfma_f32_16x16x32_bf16 v[98:101], v[162:165], v[194:197], v[98:101]
	v_mfma_f32_16x16x32_bf16 v[94:97], v[132:135], v[202:205], v[94:97]
	v_mfma_f32_16x16x32_bf16 v[90:93], v[162:165], v[202:205], v[90:93]
	v_mfma_f32_16x16x32_bf16 v[78:81], v[132:135], v[210:213], v[78:81]
	v_mfma_f32_16x16x32_bf16 v[70:73], v[162:165], v[210:213], v[70:73]
	v_mfma_f32_16x16x32_bf16 v[118:121], v[154:157], v[190:193], v[118:121]
	v_mfma_f32_16x16x32_bf16 v[114:117], v[166:169], v[190:193], v[114:117]
	v_mfma_f32_16x16x32_bf16 v[110:113], v[154:157], v[198:201], v[110:113]
	v_mfma_f32_16x16x32_bf16 v[98:101], v[166:169], v[198:201], v[98:101]
	v_mfma_f32_16x16x32_bf16 v[94:97], v[154:157], v[206:209], v[94:97]
	v_mfma_f32_16x16x32_bf16 v[90:93], v[166:169], v[206:209], v[90:93]
	v_mfma_f32_16x16x32_bf16 v[78:81], v[154:157], v[214:217], v[78:81]
	v_mfma_f32_16x16x32_bf16 v[70:73], v[166:169], v[214:217], v[70:73]
	s_setprio 0
	s_setprio 1
	v_mfma_f32_16x16x32_bf16 v[126:129], v[170:173], v[186:189], v[126:129]
	v_mfma_f32_16x16x32_bf16 v[122:125], v[178:181], v[186:189], v[122:125]
	v_mfma_f32_16x16x32_bf16 v[106:109], v[170:173], v[194:197], v[106:109]
	v_mfma_f32_16x16x32_bf16 v[102:105], v[178:181], v[194:197], v[102:105]
	v_mfma_f32_16x16x32_bf16 v[86:89], v[170:173], v[202:205], v[86:89]
	v_mfma_f32_16x16x32_bf16 v[82:85], v[178:181], v[202:205], v[82:85]
	v_mfma_f32_16x16x32_bf16 v[62:65], v[170:173], v[210:213], v[62:65]
	v_mfma_f32_16x16x32_bf16 v[58:61], v[178:181], v[210:213], v[58:61]
	v_mfma_f32_16x16x32_bf16 v[126:129], v[174:177], v[190:193], v[126:129]
	v_mfma_f32_16x16x32_bf16 v[122:125], v[182:185], v[190:193], v[122:125]
	v_mfma_f32_16x16x32_bf16 v[106:109], v[174:177], v[198:201], v[106:109]
	v_mfma_f32_16x16x32_bf16 v[102:105], v[182:185], v[198:201], v[102:105]
	v_mfma_f32_16x16x32_bf16 v[86:89], v[174:177], v[206:209], v[86:89]
	v_mfma_f32_16x16x32_bf16 v[82:85], v[182:185], v[206:209], v[82:85]
	v_mfma_f32_16x16x32_bf16 v[62:65], v[174:177], v[214:217], v[62:65]
	v_mfma_f32_16x16x32_bf16 v[58:61], v[182:185], v[214:217], v[58:61]
	s_barrier
	s_setprio 0
	s_mov_b32 m0, s83
	s_mov_b64 s[98:99], s[6:7]
	s_add_u32 s88, s6, 0x20000
	ds_read_b128 v[186:189], v160 offset:16384
	ds_read_b128 v[190:193], v160 offset:17408
	ds_read_b128 v[194:197], v160 offset:18432
	ds_read_b128 v[198:201], v160 offset:19456
	ds_read_b128 v[202:205], v160 offset:20480
	ds_read_b128 v[206:209], v160 offset:21504
	ds_read_b128 v[210:213], v160 offset:22528
	ds_read_b128 v[214:217], v160 offset:23552
	global_load_lds_dwordx4 v140, s[6:7]
	s_mov_b32 m0, s84
	s_addc_u32 s89, s7, 0
	global_load_lds_dwordx4 v144, s[6:7]
	s_mov_b32 m0, s85
	s_mov_b64 s[100:101], s[66:67]
	global_load_lds_dwordx4 v140, s[88:89]
	s_mov_b32 m0, s46
	s_nop 0
	global_load_lds_dwordx4 v144, s[88:89]
	s_waitcnt vmcnt(6)
	s_waitcnt lgkmcnt(0)
	s_setprio 1
	s_barrier
	v_mfma_f32_16x16x32_bf16 v[74:77], v[132:135], v[186:189], v[74:77]
	v_mfma_f32_16x16x32_bf16 v[66:69], v[162:165], v[186:189], v[66:69]
	v_mfma_f32_16x16x32_bf16 v[46:49], v[132:135], v[194:197], v[46:49]
	v_mfma_f32_16x16x32_bf16 v[42:45], v[162:165], v[194:197], v[42:45]
	v_mfma_f32_16x16x32_bf16 v[30:33], v[132:135], v[202:205], v[30:33]
	v_mfma_f32_16x16x32_bf16 v[26:29], v[162:165], v[202:205], v[26:29]
	v_mfma_f32_16x16x32_bf16 v[14:17], v[132:135], v[210:213], v[14:17]
	v_mfma_f32_16x16x32_bf16 v[10:13], v[162:165], v[210:213], v[10:13]
	v_mfma_f32_16x16x32_bf16 v[74:77], v[154:157], v[190:193], v[74:77]
	v_mfma_f32_16x16x32_bf16 v[66:69], v[166:169], v[190:193], v[66:69]
	v_mfma_f32_16x16x32_bf16 v[46:49], v[154:157], v[198:201], v[46:49]
	v_mfma_f32_16x16x32_bf16 v[42:45], v[166:169], v[198:201], v[42:45]
	v_mfma_f32_16x16x32_bf16 v[30:33], v[154:157], v[206:209], v[30:33]
	v_mfma_f32_16x16x32_bf16 v[26:29], v[166:169], v[206:209], v[26:29]
	v_mfma_f32_16x16x32_bf16 v[14:17], v[154:157], v[214:217], v[14:17]
	v_mfma_f32_16x16x32_bf16 v[10:13], v[166:169], v[214:217], v[10:13]
	s_setprio 0
	s_setprio 1
	v_mfma_f32_16x16x32_bf16 v[54:57], v[170:173], v[186:189], v[54:57]
	v_mfma_f32_16x16x32_bf16 v[50:53], v[178:181], v[186:189], v[50:53]
	v_mfma_f32_16x16x32_bf16 v[38:41], v[170:173], v[194:197], v[38:41]
	v_mfma_f32_16x16x32_bf16 v[34:37], v[178:181], v[194:197], v[34:37]
	v_mfma_f32_16x16x32_bf16 v[22:25], v[170:173], v[202:205], v[22:25]
	v_mfma_f32_16x16x32_bf16 v[18:21], v[178:181], v[202:205], v[18:21]
	v_mfma_f32_16x16x32_bf16 v[6:9], v[170:173], v[210:213], v[6:9]
	v_mfma_f32_16x16x32_bf16 v[2:5], v[178:181], v[210:213], v[2:5]
	v_mfma_f32_16x16x32_bf16 v[54:57], v[174:177], v[190:193], v[54:57]
	v_mfma_f32_16x16x32_bf16 v[50:53], v[182:185], v[190:193], v[50:53]
	v_mfma_f32_16x16x32_bf16 v[38:41], v[174:177], v[198:201], v[38:41]
	v_mfma_f32_16x16x32_bf16 v[34:37], v[182:185], v[198:201], v[34:37]
	v_mfma_f32_16x16x32_bf16 v[22:25], v[174:177], v[206:209], v[22:25]
	v_mfma_f32_16x16x32_bf16 v[18:21], v[182:185], v[206:209], v[18:21]
	v_mfma_f32_16x16x32_bf16 v[6:9], v[174:177], v[214:217], v[6:9]
	v_mfma_f32_16x16x32_bf16 v[2:5], v[182:185], v[214:217], v[2:5]
	s_barrier
;     ...
;         for (int t = 2; t < nt; t += 2) PG8_KITER(t);
	s_setprio 0
	ds_read_b128 v[132:135], v130
	ds_read_b128 v[154:157], v130 offset:1024
	ds_read_b128 v[162:165], v130 offset:2048
	ds_read_b128 v[166:169], v130 offset:3072
	ds_read_b128 v[170:173], v131
	ds_read_b128 v[174:177], v131 offset:1024
	ds_read_b128 v[178:181], v131 offset:2048
	ds_read_b128 v[182:185], v131 offset:3072
	s_add_u32 s66, s66, 0x20000
	s_addc_u32 s67, s67, 0
	s_mov_b32 m0, s58
	s_nop 0
	global_load_lds_dwordx4 v138, s[100:101]
	s_mov_b32 m0, s59
	s_nop 0
	global_load_lds_dwordx4 v142, s[100:101]
	s_mov_b32 m0, s63
	ds_read_b128 v[186:189], v160 offset:32768
	ds_read_b128 v[190:193], v160 offset:33792
	ds_read_b128 v[194:197], v160 offset:34816
	ds_read_b128 v[198:201], v160 offset:35840
	ds_read_b128 v[202:205], v160 offset:36864
	ds_read_b128 v[206:209], v160 offset:37888
	ds_read_b128 v[210:213], v160 offset:38912
	ds_read_b128 v[214:217], v160 offset:39936
	global_load_lds_dwordx4 v138, s[66:67]
	s_mov_b32 m0, s68
	s_nop 0
	global_load_lds_dwordx4 v142, s[66:67]
	s_waitcnt vmcnt(8)
	s_waitcnt lgkmcnt(0)
	s_setprio 1
	s_barrier
	v_mfma_f32_16x16x32_bf16 v[118:121], v[132:135], v[186:189], v[118:121]
	v_mfma_f32_16x16x32_bf16 v[114:117], v[162:165], v[186:189], v[114:117]
	v_mfma_f32_16x16x32_bf16 v[110:113], v[132:135], v[194:197], v[110:113]
	v_mfma_f32_16x16x32_bf16 v[98:101], v[162:165], v[194:197], v[98:101]
	v_mfma_f32_16x16x32_bf16 v[94:97], v[132:135], v[202:205], v[94:97]
	v_mfma_f32_16x16x32_bf16 v[90:93], v[162:165], v[202:205], v[90:93]
	v_mfma_f32_16x16x32_bf16 v[78:81], v[132:135], v[210:213], v[78:81]
	v_mfma_f32_16x16x32_bf16 v[70:73], v[162:165], v[210:213], v[70:73]
	v_mfma_f32_16x16x32_bf16 v[118:121], v[154:157], v[190:193], v[118:121]
	v_mfma_f32_16x16x32_bf16 v[114:117], v[166:169], v[190:193], v[114:117]
	v_mfma_f32_16x16x32_bf16 v[110:113], v[154:157], v[198:201], v[110:113]
	v_mfma_f32_16x16x32_bf16 v[98:101], v[166:169], v[198:201], v[98:101]
	v_mfma_f32_16x16x32_bf16 v[94:97], v[154:157], v[206:209], v[94:97]
	v_mfma_f32_16x16x32_bf16 v[90:93], v[166:169], v[206:209], v[90:93]
	v_mfma_f32_16x16x32_bf16 v[78:81], v[154:157], v[214:217], v[78:81]
	v_mfma_f32_16x16x32_bf16 v[70:73], v[166:169], v[214:217], v[70:73]
	s_setprio 0
	s_setprio 1
	v_mfma_f32_16x16x32_bf16 v[126:129], v[170:173], v[186:189], v[126:129]
	v_mfma_f32_16x16x32_bf16 v[122:125], v[178:181], v[186:189], v[122:125]
	v_mfma_f32_16x16x32_bf16 v[106:109], v[170:173], v[194:197], v[106:109]
	v_mfma_f32_16x16x32_bf16 v[102:105], v[178:181], v[194:197], v[102:105]
	v_mfma_f32_16x16x32_bf16 v[86:89], v[170:173], v[202:205], v[86:89]
	v_mfma_f32_16x16x32_bf16 v[82:85], v[178:181], v[202:205], v[82:85]
	v_mfma_f32_16x16x32_bf16 v[62:65], v[170:173], v[210:213], v[62:65]
	v_mfma_f32_16x16x32_bf16 v[58:61], v[178:181], v[210:213], v[58:61]
	v_mfma_f32_16x16x32_bf16 v[126:129], v[174:177], v[190:193], v[126:129]
	v_mfma_f32_16x16x32_bf16 v[122:125], v[182:185], v[190:193], v[122:125]
	v_mfma_f32_16x16x32_bf16 v[106:109], v[174:177], v[198:201], v[106:109]
	v_mfma_f32_16x16x32_bf16 v[102:105], v[182:185], v[198:201], v[102:105]
	v_mfma_f32_16x16x32_bf16 v[86:89], v[174:177], v[206:209], v[86:89]
	v_mfma_f32_16x16x32_bf16 v[82:85], v[182:185], v[206:209], v[82:85]
	v_mfma_f32_16x16x32_bf16 v[62:65], v[174:177], v[214:217], v[62:65]
	v_mfma_f32_16x16x32_bf16 v[58:61], v[182:185], v[214:217], v[58:61]
	s_barrier
	s_setprio 0
	s_mov_b32 m0, s47
	s_add_u32 s98, s98, 0x80
	s_addc_u32 s99, s99, 0
	s_add_u32 s100, s100, 0x80
	s_addc_u32 s101, s101, 0
	s_add_u32 s6, s6, 0x20080
	ds_read_b128 v[186:189], v160 offset:49152
	ds_read_b128 v[190:193], v160 offset:50176
	ds_read_b128 v[194:197], v160 offset:51200
	ds_read_b128 v[198:201], v160 offset:52224
	ds_read_b128 v[202:205], v160 offset:53248
	ds_read_b128 v[206:209], v160 offset:54272
	ds_read_b128 v[210:213], v160 offset:55296
	ds_read_b128 v[214:217], v160 offset:56320
	global_load_lds_dwordx4 v140, s[98:99]
	s_mov_b32 m0, s86
	s_addc_u32 s7, s7, 0
	global_load_lds_dwordx4 v144, s[98:99]
	s_mov_b32 m0, s56
	s_nop 0
	global_load_lds_dwordx4 v140, s[6:7]
	s_mov_b32 m0, s57
	s_nop 0
	global_load_lds_dwordx4 v144, s[6:7]
	s_waitcnt vmcnt(6)
	s_waitcnt lgkmcnt(0)
	s_setprio 1
	s_barrier
	v_mfma_f32_16x16x32_bf16 v[74:77], v[132:135], v[186:189], v[74:77]
	v_mfma_f32_16x16x32_bf16 v[66:69], v[162:165], v[186:189], v[66:69]
	v_mfma_f32_16x16x32_bf16 v[46:49], v[132:135], v[194:197], v[46:49]
	v_mfma_f32_16x16x32_bf16 v[42:45], v[162:165], v[194:197], v[42:45]
	v_mfma_f32_16x16x32_bf16 v[30:33], v[132:135], v[202:205], v[30:33]
	v_mfma_f32_16x16x32_bf16 v[26:29], v[162:165], v[202:205], v[26:29]
	v_mfma_f32_16x16x32_bf16 v[14:17], v[132:135], v[210:213], v[14:17]
	v_mfma_f32_16x16x32_bf16 v[10:13], v[162:165], v[210:213], v[10:13]
	v_mfma_f32_16x16x32_bf16 v[74:77], v[154:157], v[190:193], v[74:77]
	v_mfma_f32_16x16x32_bf16 v[66:69], v[166:169], v[190:193], v[66:69]
	v_mfma_f32_16x16x32_bf16 v[46:49], v[154:157], v[198:201], v[46:49]
	v_mfma_f32_16x16x32_bf16 v[42:45], v[166:169], v[198:201], v[42:45]
	v_mfma_f32_16x16x32_bf16 v[30:33], v[154:157], v[206:209], v[30:33]
	v_mfma_f32_16x16x32_bf16 v[26:29], v[166:169], v[206:209], v[26:29]
	v_mfma_f32_16x16x32_bf16 v[14:17], v[154:157], v[214:217], v[14:17]
	v_mfma_f32_16x16x32_bf16 v[10:13], v[166:169], v[214:217], v[10:13]
	s_setprio 0
	s_setprio 1
	v_mfma_f32_16x16x32_bf16 v[54:57], v[170:173], v[186:189], v[54:57]
	v_mfma_f32_16x16x32_bf16 v[50:53], v[178:181], v[186:189], v[50:53]
	v_mfma_f32_16x16x32_bf16 v[38:41], v[170:173], v[194:197], v[38:41]
	v_mfma_f32_16x16x32_bf16 v[34:37], v[178:181], v[194:197], v[34:37]
	v_mfma_f32_16x16x32_bf16 v[22:25], v[170:173], v[202:205], v[22:25]
	v_mfma_f32_16x16x32_bf16 v[18:21], v[178:181], v[202:205], v[18:21]
	v_mfma_f32_16x16x32_bf16 v[6:9], v[170:173], v[210:213], v[6:9]
	v_mfma_f32_16x16x32_bf16 v[2:5], v[178:181], v[210:213], v[2:5]
	v_mfma_f32_16x16x32_bf16 v[54:57], v[174:177], v[190:193], v[54:57]
	v_mfma_f32_16x16x32_bf16 v[50:53], v[182:185], v[190:193], v[50:53]
	v_mfma_f32_16x16x32_bf16 v[38:41], v[174:177], v[198:201], v[38:41]
	v_mfma_f32_16x16x32_bf16 v[34:37], v[182:185], v[198:201], v[34:37]
	v_mfma_f32_16x16x32_bf16 v[22:25], v[174:177], v[206:209], v[22:25]
	v_mfma_f32_16x16x32_bf16 v[18:21], v[182:185], v[206:209], v[18:21]
	v_mfma_f32_16x16x32_bf16 v[6:9], v[174:177], v[214:217], v[6:9]
	v_mfma_f32_16x16x32_bf16 v[2:5], v[182:185], v[214:217], v[2:5]
	s_barrier
	s_setprio 0
	s_add_i32 s26, s26, 2
	s_add_u32 s64, s64, 0x100
	s_addc_u32 s65, s65, 0
	s_add_u32 s14, s14, 0x100
	s_addc_u32 s15, s15, 0
	s_cmp_gt_u32 s26, 5
	s_cbranch_scc0 .LBB0_670
	s_mov_b32 m0, s69
	s_nop 0
	global_load_lds_dwordx4 v138, s[100:101]
	s_mov_b32 m0, s70
	s_nop 0
	global_load_lds_dwordx4 v142, s[100:101]
	s_and_b64 vcc, exec, s[18:19]
	s_cbranch_vccz .LBB0_673
	s_barrier

.LBB0_716:
	ds_read_b128 v[132:135], v164
	ds_read_b128 v[136:139], v164 offset:1024
	ds_read_b128 v[140:143], v164 offset:2048
	ds_read_b128 v[168:171], v164 offset:3072
	ds_read_b128 v[172:175], v165
	ds_read_b128 v[176:179], v165 offset:1024
	ds_read_b128 v[180:183], v165 offset:2048
	ds_read_b128 v[184:187], v165 offset:3072
	s_add_u32 s27, s62, 0xfff80080
	s_addc_u32 s50, s63, -1
	s_cmp_eq_u32 s26, 4
	s_cselect_b32 s65, s1, s50
	s_cselect_b32 s64, s0, s27
	s_cselect_b32 s51, s29, s15
	s_cselect_b32 s50, s28, s14
	s_cmp_eq_u32 s26, 0
	s_cbranch_scc1 .Lrb2_skip_21903
	s_mov_b32 m0, s69
	s_nop 0
	global_load_lds_dwordx4 v146, s[100:101]
	s_mov_b32 m0, s70
	s_nop 0
	global_load_lds_dwordx4 v150, s[100:101]
.Lrb2_skip_21903:
	s_mov_b32 m0, s23
	ds_read_b128 v[188:191], v166
	ds_read_b128 v[192:195], v166 offset:1024
	ds_read_b128 v[196:199], v166 offset:2048
	ds_read_b128 v[200:203], v166 offset:3072
	ds_read_b128 v[204:207], v166 offset:4096
	ds_read_b128 v[208:211], v166 offset:5120
	ds_read_b128 v[212:215], v166 offset:6144
	ds_read_b128 v[216:219], v166 offset:7168
	global_load_lds_dwordx4 v154, s[62:63]
	s_mov_b32 m0, s77
	s_nop 0
	global_load_lds_dwordx4 v156, s[62:63]
	s_waitcnt vmcnt(8)
	s_waitcnt lgkmcnt(0)
	s_setprio 1
	s_barrier
	v_mfma_f32_16x16x32_bf16 v[102:105], v[132:135], v[188:191], v[102:105]
	v_mfma_f32_16x16x32_bf16 v[98:101], v[140:143], v[188:191], v[98:101]
	v_mfma_f32_16x16x32_bf16 v[94:97], v[132:135], v[196:199], v[94:97]
	v_mfma_f32_16x16x32_bf16 v[90:93], v[140:143], v[196:199], v[90:93]
	v_mfma_f32_16x16x32_bf16 v[86:89], v[132:135], v[204:207], v[86:89]
	v_mfma_f32_16x16x32_bf16 v[82:85], v[140:143], v[204:207], v[82:85]
	v_mfma_f32_16x16x32_bf16 v[78:81], v[132:135], v[212:215], v[78:81]
	v_mfma_f32_16x16x32_bf16 v[62:65], v[140:143], v[212:215], v[62:65]
	v_mfma_f32_16x16x32_bf16 v[102:105], v[136:139], v[192:195], v[102:105]
	v_mfma_f32_16x16x32_bf16 v[98:101], v[168:171], v[192:195], v[98:101]
	v_mfma_f32_16x16x32_bf16 v[94:97], v[136:139], v[200:203], v[94:97]
	v_mfma_f32_16x16x32_bf16 v[90:93], v[168:171], v[200:203], v[90:93]
	v_mfma_f32_16x16x32_bf16 v[86:89], v[136:139], v[208:211], v[86:89]
	v_mfma_f32_16x16x32_bf16 v[82:85], v[168:171], v[208:211], v[82:85]
	v_mfma_f32_16x16x32_bf16 v[78:81], v[136:139], v[216:219], v[78:81]
	v_mfma_f32_16x16x32_bf16 v[62:65], v[168:171], v[216:219], v[62:65]
	s_setprio 0
	s_setprio 1
	v_mfma_f32_16x16x32_bf16 v[126:129], v[172:175], v[188:191], v[126:129]
	v_mfma_f32_16x16x32_bf16 v[122:125], v[180:183], v[188:191], v[122:125]
	v_mfma_f32_16x16x32_bf16 v[118:121], v[172:175], v[196:199], v[118:121]
	v_mfma_f32_16x16x32_bf16 v[114:117], v[180:183], v[196:199], v[114:117]
	v_mfma_f32_16x16x32_bf16 v[110:113], v[172:175], v[204:207], v[110:113]
	v_mfma_f32_16x16x32_bf16 v[106:109], v[180:183], v[204:207], v[106:109]
	v_mfma_f32_16x16x32_bf16 v[54:57], v[172:175], v[212:215], v[54:57]
	v_mfma_f32_16x16x32_bf16 v[50:53], v[180:183], v[212:215], v[50:53]
	v_mfma_f32_16x16x32_bf16 v[126:129], v[176:179], v[192:195], v[126:129]
	v_mfma_f32_16x16x32_bf16 v[122:125], v[184:187], v[192:195], v[122:125]
	v_mfma_f32_16x16x32_bf16 v[118:121], v[176:179], v[200:203], v[118:121]
	v_mfma_f32_16x16x32_bf16 v[114:117], v[184:187], v[200:203], v[114:117]
	v_mfma_f32_16x16x32_bf16 v[110:113], v[176:179], v[208:211], v[110:113]
	v_mfma_f32_16x16x32_bf16 v[106:109], v[184:187], v[208:211], v[106:109]
	v_mfma_f32_16x16x32_bf16 v[54:57], v[176:179], v[216:219], v[54:57]
	v_mfma_f32_16x16x32_bf16 v[50:53], v[184:187], v[216:219], v[50:53]
	s_barrier
	s_setprio 0
	s_mov_b32 m0, s78
	s_mov_b64 s[98:99], s[50:51]
	s_add_u32 s82, s50, 0x80000
	ds_read_b128 v[188:191], v166 offset:16384
	ds_read_b128 v[192:195], v166 offset:17408
	ds_read_b128 v[196:199], v166 offset:18432
	ds_read_b128 v[200:203], v166 offset:19456
	ds_read_b128 v[204:207], v166 offset:20480
	ds_read_b128 v[208:211], v166 offset:21504
	ds_read_b128 v[212:215], v166 offset:22528
	ds_read_b128 v[216:219], v166 offset:23552
	global_load_lds_dwordx4 v148, s[50:51]
	s_mov_b32 m0, s79
	s_addc_u32 s83, s51, 0
	global_load_lds_dwordx4 v152, s[50:51]
	s_mov_b32 m0, s80
	s_mov_b64 s[100:101], s[64:65]
	global_load_lds_dwordx4 v148, s[82:83]
	s_mov_b32 m0, s46
	s_nop 0
	global_load_lds_dwordx4 v152, s[82:83]
	s_waitcnt vmcnt(6)
	s_waitcnt lgkmcnt(0)
	s_setprio 1
	s_barrier
	v_mfma_f32_16x16x32_bf16 v[74:77], v[132:135], v[188:191], v[74:77]
	v_mfma_f32_16x16x32_bf16 v[70:73], v[140:143], v[188:191], v[70:73]
	v_mfma_f32_16x16x32_bf16 v[46:49], v[132:135], v[196:199], v[46:49]
	v_mfma_f32_16x16x32_bf16 v[42:45], v[140:143], v[196:199], v[42:45]
	v_mfma_f32_16x16x32_bf16 v[30:33], v[132:135], v[204:207], v[30:33]
	v_mfma_f32_16x16x32_bf16 v[26:29], v[140:143], v[204:207], v[26:29]
	v_mfma_f32_16x16x32_bf16 v[14:17], v[132:135], v[212:215], v[14:17]
	v_mfma_f32_16x16x32_bf16 v[10:13], v[140:143], v[212:215], v[10:13]
	v_mfma_f32_16x16x32_bf16 v[74:77], v[136:139], v[192:195], v[74:77]
	v_mfma_f32_16x16x32_bf16 v[70:73], v[168:171], v[192:195], v[70:73]
	v_mfma_f32_16x16x32_bf16 v[46:49], v[136:139], v[200:203], v[46:49]
	v_mfma_f32_16x16x32_bf16 v[42:45], v[168:171], v[200:203], v[42:45]
	v_mfma_f32_16x16x32_bf16 v[30:33], v[136:139], v[208:211], v[30:33]
	v_mfma_f32_16x16x32_bf16 v[26:29], v[168:171], v[208:211], v[26:29]
	v_mfma_f32_16x16x32_bf16 v[14:17], v[136:139], v[216:219], v[14:17]
	v_mfma_f32_16x16x32_bf16 v[10:13], v[168:171], v[216:219], v[10:13]
	s_setprio 0
	s_setprio 1
	v_mfma_f32_16x16x32_bf16 v[66:69], v[172:175], v[188:191], v[66:69]
	v_mfma_f32_16x16x32_bf16 v[58:61], v[180:183], v[188:191], v[58:61]
	v_mfma_f32_16x16x32_bf16 v[38:41], v[172:175], v[196:199], v[38:41]
	v_mfma_f32_16x16x32_bf16 v[34:37], v[180:183], v[196:199], v[34:37]
	v_mfma_f32_16x16x32_bf16 v[22:25], v[172:175], v[204:207], v[22:25]
	v_mfma_f32_16x16x32_bf16 v[18:21], v[180:183], v[204:207], v[18:21]
	v_mfma_f32_16x16x32_bf16 v[6:9], v[172:175], v[212:215], v[6:9]
	v_mfma_f32_16x16x32_bf16 v[2:5], v[180:183], v[212:215], v[2:5]
	v_mfma_f32_16x16x32_bf16 v[66:69], v[176:179], v[192:195], v[66:69]
	v_mfma_f32_16x16x32_bf16 v[58:61], v[184:187], v[192:195], v[58:61]
	v_mfma_f32_16x16x32_bf16 v[38:41], v[176:179], v[200:203], v[38:41]
	v_mfma_f32_16x16x32_bf16 v[34:37], v[184:187], v[200:203], v[34:37]
	v_mfma_f32_16x16x32_bf16 v[22:25], v[176:179], v[208:211], v[22:25]
	v_mfma_f32_16x16x32_bf16 v[18:21], v[184:187], v[208:211], v[18:21]
	v_mfma_f32_16x16x32_bf16 v[6:9], v[176:179], v[216:219], v[6:9]
	v_mfma_f32_16x16x32_bf16 v[2:5], v[184:187], v[216:219], v[2:5]
	s_barrier
;     ...
;         for (int t = 2; t < nt; t += 2) PG8_KITER(t);
	s_setprio 0
	ds_read_b128 v[132:135], v130
	ds_read_b128 v[136:139], v130 offset:1024
	ds_read_b128 v[140:143], v130 offset:2048
	ds_read_b128 v[168:171], v130 offset:3072
	ds_read_b128 v[172:175], v131
	ds_read_b128 v[176:179], v131 offset:1024
	ds_read_b128 v[180:183], v131 offset:2048
	ds_read_b128 v[184:187], v131 offset:3072
	s_add_u32 s64, s64, 0x80000
	s_addc_u32 s65, s65, 0
	s_mov_b32 m0, s59
	s_nop 0
	global_load_lds_dwordx4 v146, s[100:101]
	s_mov_b32 m0, s31
	s_nop 0
	global_load_lds_dwordx4 v150, s[100:101]
	s_mov_b32 m0, s66
	ds_read_b128 v[188:191], v166 offset:32768
	ds_read_b128 v[192:195], v166 offset:33792
	ds_read_b128 v[196:199], v166 offset:34816
	ds_read_b128 v[200:203], v166 offset:35840
	ds_read_b128 v[204:207], v166 offset:36864
	ds_read_b128 v[208:211], v166 offset:37888
	ds_read_b128 v[212:215], v166 offset:38912
	ds_read_b128 v[216:219], v166 offset:39936
	global_load_lds_dwordx4 v146, s[64:65]
	s_mov_b32 m0, s67
	s_nop 0
	global_load_lds_dwordx4 v150, s[64:65]
	s_waitcnt vmcnt(8)
	s_waitcnt lgkmcnt(0)
	s_setprio 1
	s_barrier
	v_mfma_f32_16x16x32_bf16 v[102:105], v[132:135], v[188:191], v[102:105]
	v_mfma_f32_16x16x32_bf16 v[98:101], v[140:143], v[188:191], v[98:101]
	v_mfma_f32_16x16x32_bf16 v[94:97], v[132:135], v[196:199], v[94:97]
	v_mfma_f32_16x16x32_bf16 v[90:93], v[140:143], v[196:199], v[90:93]
	v_mfma_f32_16x16x32_bf16 v[86:89], v[132:135], v[204:207], v[86:89]
	v_mfma_f32_16x16x32_bf16 v[82:85], v[140:143], v[204:207], v[82:85]
	v_mfma_f32_16x16x32_bf16 v[78:81], v[132:135], v[212:215], v[78:81]
	v_mfma_f32_16x16x32_bf16 v[62:65], v[140:143], v[212:215], v[62:65]
	v_mfma_f32_16x16x32_bf16 v[102:105], v[136:139], v[192:195], v[102:105]
	v_mfma_f32_16x16x32_bf16 v[98:101], v[168:171], v[192:195], v[98:101]
	v_mfma_f32_16x16x32_bf16 v[94:97], v[136:139], v[200:203], v[94:97]
	v_mfma_f32_16x16x32_bf16 v[90:93], v[168:171], v[200:203], v[90:93]
	v_mfma_f32_16x16x32_bf16 v[86:89], v[136:139], v[208:211], v[86:89]
	v_mfma_f32_16x16x32_bf16 v[82:85], v[168:171], v[208:211], v[82:85]
	v_mfma_f32_16x16x32_bf16 v[78:81], v[136:139], v[216:219], v[78:81]
	v_mfma_f32_16x16x32_bf16 v[62:65], v[168:171], v[216:219], v[62:65]
	s_setprio 0
	s_setprio 1
	v_mfma_f32_16x16x32_bf16 v[126:129], v[172:175], v[188:191], v[126:129]
	v_mfma_f32_16x16x32_bf16 v[122:125], v[180:183], v[188:191], v[122:125]
	v_mfma_f32_16x16x32_bf16 v[118:121], v[172:175], v[196:199], v[118:121]
	v_mfma_f32_16x16x32_bf16 v[114:117], v[180:183], v[196:199], v[114:117]
	v_mfma_f32_16x16x32_bf16 v[110:113], v[172:175], v[204:207], v[110:113]
	v_mfma_f32_16x16x32_bf16 v[106:109], v[180:183], v[204:207], v[106:109]
	v_mfma_f32_16x16x32_bf16 v[54:57], v[172:175], v[212:215], v[54:57]
	v_mfma_f32_16x16x32_bf16 v[50:53], v[180:183], v[212:215], v[50:53]
	v_mfma_f32_16x16x32_bf16 v[126:129], v[176:179], v[192:195], v[126:129]
	v_mfma_f32_16x16x32_bf16 v[122:125], v[184:187], v[192:195], v[122:125]
	v_mfma_f32_16x16x32_bf16 v[118:121], v[176:179], v[200:203], v[118:121]
	v_mfma_f32_16x16x32_bf16 v[114:117], v[184:187], v[200:203], v[114:117]
	v_mfma_f32_16x16x32_bf16 v[110:113], v[176:179], v[208:211], v[110:113]
	v_mfma_f32_16x16x32_bf16 v[106:109], v[184:187], v[208:211], v[106:109]
	v_mfma_f32_16x16x32_bf16 v[54:57], v[176:179], v[216:219], v[54:57]
	v_mfma_f32_16x16x32_bf16 v[50:53], v[184:187], v[216:219], v[50:53]
	s_barrier
	s_setprio 0
	s_mov_b32 m0, s47
	s_add_u32 s98, s98, 0x80
	s_addc_u32 s99, s99, 0
	s_add_u32 s100, s100, 0x80
	s_addc_u32 s101, s101, 0
	s_add_u32 s50, s50, 0x80080
	ds_read_b128 v[188:191], v166 offset:49152
	ds_read_b128 v[192:195], v166 offset:50176
	ds_read_b128 v[196:199], v166 offset:51200
	ds_read_b128 v[200:203], v166 offset:52224
	ds_read_b128 v[204:207], v166 offset:53248
	ds_read_b128 v[208:211], v166 offset:54272
	ds_read_b128 v[212:215], v166 offset:55296
	ds_read_b128 v[216:219], v166 offset:56320
	global_load_lds_dwordx4 v148, s[98:99]
	s_mov_b32 m0, s81
	s_addc_u32 s51, s51, 0
	global_load_lds_dwordx4 v152, s[98:99]
	s_mov_b32 m0, s56
	s_nop 0
	global_load_lds_dwordx4 v148, s[50:51]
	s_mov_b32 m0, s57
	s_nop 0
	global_load_lds_dwordx4 v152, s[50:51]
	s_waitcnt vmcnt(6)
	s_waitcnt lgkmcnt(0)
	s_setprio 1
	s_barrier
	v_mfma_f32_16x16x32_bf16 v[74:77], v[132:135], v[188:191], v[74:77]
	v_mfma_f32_16x16x32_bf16 v[70:73], v[140:143], v[188:191], v[70:73]
	v_mfma_f32_16x16x32_bf16 v[46:49], v[132:135], v[196:199], v[46:49]
	v_mfma_f32_16x16x32_bf16 v[42:45], v[140:143], v[196:199], v[42:45]
	v_mfma_f32_16x16x32_bf16 v[30:33], v[132:135], v[204:207], v[30:33]
	v_mfma_f32_16x16x32_bf16 v[26:29], v[140:143], v[204:207], v[26:29]
	v_mfma_f32_16x16x32_bf16 v[14:17], v[132:135], v[212:215], v[14:17]
	v_mfma_f32_16x16x32_bf16 v[10:13], v[140:143], v[212:215], v[10:13]
	v_mfma_f32_16x16x32_bf16 v[74:77], v[136:139], v[192:195], v[74:77]
	v_mfma_f32_16x16x32_bf16 v[70:73], v[168:171], v[192:195], v[70:73]
	v_mfma_f32_16x16x32_bf16 v[46:49], v[136:139], v[200:203], v[46:49]
	v_mfma_f32_16x16x32_bf16 v[42:45], v[168:171], v[200:203], v[42:45]
	v_mfma_f32_16x16x32_bf16 v[30:33], v[136:139], v[208:211], v[30:33]
	v_mfma_f32_16x16x32_bf16 v[26:29], v[168:171], v[208:211], v[26:29]
	v_mfma_f32_16x16x32_bf16 v[14:17], v[136:139], v[216:219], v[14:17]
	v_mfma_f32_16x16x32_bf16 v[10:13], v[168:171], v[216:219], v[10:13]
	s_setprio 0
	s_setprio 1
	v_mfma_f32_16x16x32_bf16 v[66:69], v[172:175], v[188:191], v[66:69]
	v_mfma_f32_16x16x32_bf16 v[58:61], v[180:183], v[188:191], v[58:61]
	v_mfma_f32_16x16x32_bf16 v[38:41], v[172:175], v[196:199], v[38:41]
	v_mfma_f32_16x16x32_bf16 v[34:37], v[180:183], v[196:199], v[34:37]
	v_mfma_f32_16x16x32_bf16 v[22:25], v[172:175], v[204:207], v[22:25]
	v_mfma_f32_16x16x32_bf16 v[18:21], v[180:183], v[204:207], v[18:21]
	v_mfma_f32_16x16x32_bf16 v[6:9], v[172:175], v[212:215], v[6:9]
	v_mfma_f32_16x16x32_bf16 v[2:5], v[180:183], v[212:215], v[2:5]
	v_mfma_f32_16x16x32_bf16 v[66:69], v[176:179], v[192:195], v[66:69]
	v_mfma_f32_16x16x32_bf16 v[58:61], v[184:187], v[192:195], v[58:61]
	v_mfma_f32_16x16x32_bf16 v[38:41], v[176:179], v[200:203], v[38:41]
	v_mfma_f32_16x16x32_bf16 v[34:37], v[184:187], v[200:203], v[34:37]
	v_mfma_f32_16x16x32_bf16 v[22:25], v[176:179], v[208:211], v[22:25]
	v_mfma_f32_16x16x32_bf16 v[18:21], v[184:187], v[208:211], v[18:21]
	v_mfma_f32_16x16x32_bf16 v[6:9], v[176:179], v[216:219], v[6:9]
	v_mfma_f32_16x16x32_bf16 v[2:5], v[184:187], v[216:219], v[2:5]
	s_barrier
	s_setprio 0
	s_add_i32 s26, s26, 2
	s_add_u32 s62, s62, 0x100
	s_addc_u32 s63, s63, 0
	s_add_u32 s14, s14, 0x100
	s_addc_u32 s15, s15, 0
	s_cmp_gt_u32 s26, 5
	s_cbranch_scc0 .LBB0_716
	s_mov_b32 m0, s69
	s_nop 0
	global_load_lds_dwordx4 v146, s[100:101]
	s_mov_b32 m0, s70
	s_nop 0
	global_load_lds_dwordx4 v150, s[100:101]
	s_and_b64 vcc, exec, s[16:17]
	s_cbranch_vccz .LBB0_719
	s_barrier

.LBB0_930:
	ds_read_b128 v[134:137], v130
	ds_read_b128 v[138:141], v130 offset:1024
	ds_read_b128 v[142:145], v130 offset:2048
	ds_read_b128 v[146:149], v130 offset:3072
	ds_read_b128 v[168:171], v131
	ds_read_b128 v[174:177], v131 offset:1024
	ds_read_b128 v[178:181], v131 offset:2048
	ds_read_b128 v[182:185], v131 offset:3072
	s_add_u32 s27, s62, 0xfff80080
	s_addc_u32 s50, s63, -1
	s_cmp_eq_u32 s26, 28
	s_cselect_b32 s65, s7, s50
	s_cselect_b32 s64, s6, s27
	s_cselect_b32 s51, s49, s15
	s_cselect_b32 s50, s48, s14
	s_cmp_eq_u32 s26, 0
	s_cbranch_scc1 .Lrb2_skip_28568
	s_mov_b32 m0, s77
	s_nop 0
	global_load_lds_dwordx4 v150, s[100:101]
	s_mov_b32 m0, s78
	s_nop 0
	global_load_lds_dwordx4 v154, s[100:101]
.Lrb2_skip_28568:
	s_mov_b32 m0, s0
	ds_read_b128 v[186:189], v172
	ds_read_b128 v[190:193], v172 offset:1024
	ds_read_b128 v[194:197], v172 offset:2048
	ds_read_b128 v[198:201], v172 offset:3072
	ds_read_b128 v[202:205], v172 offset:4096
	ds_read_b128 v[206:209], v172 offset:5120
	ds_read_b128 v[210:213], v172 offset:6144
	ds_read_b128 v[214:217], v172 offset:7168
	global_load_lds_dwordx4 v160, s[62:63]
	s_mov_b32 m0, s11
	s_nop 0
	global_load_lds_dwordx4 v162, s[62:63]
	s_waitcnt vmcnt(8)
	s_waitcnt lgkmcnt(0)
	s_setprio 1
	s_barrier
	v_mfma_f32_16x16x32_bf16 v[126:129], v[134:137], v[186:189], v[126:129]
	v_mfma_f32_16x16x32_bf16 v[122:125], v[142:145], v[186:189], v[122:125]
	v_mfma_f32_16x16x32_bf16 v[118:121], v[134:137], v[194:197], v[118:121]
	v_mfma_f32_16x16x32_bf16 v[114:117], v[142:145], v[194:197], v[114:117]
	v_mfma_f32_16x16x32_bf16 v[110:113], v[134:137], v[202:205], v[110:113]
	v_mfma_f32_16x16x32_bf16 v[106:109], v[142:145], v[202:205], v[106:109]
	v_mfma_f32_16x16x32_bf16 v[102:105], v[134:137], v[210:213], v[102:105]
	v_mfma_f32_16x16x32_bf16 v[98:101], v[142:145], v[210:213], v[98:101]
	v_mfma_f32_16x16x32_bf16 v[126:129], v[138:141], v[190:193], v[126:129]
	v_mfma_f32_16x16x32_bf16 v[122:125], v[146:149], v[190:193], v[122:125]
	v_mfma_f32_16x16x32_bf16 v[118:121], v[138:141], v[198:201], v[118:121]
	v_mfma_f32_16x16x32_bf16 v[114:117], v[146:149], v[198:201], v[114:117]
	v_mfma_f32_16x16x32_bf16 v[110:113], v[138:141], v[206:209], v[110:113]
	v_mfma_f32_16x16x32_bf16 v[106:109], v[146:149], v[206:209], v[106:109]
	v_mfma_f32_16x16x32_bf16 v[102:105], v[138:141], v[214:217], v[102:105]
	v_mfma_f32_16x16x32_bf16 v[98:101], v[146:149], v[214:217], v[98:101]
	s_setprio 0
	s_setprio 1
	v_mfma_f32_16x16x32_bf16 v[94:97], v[168:171], v[186:189], v[94:97]
	v_mfma_f32_16x16x32_bf16 v[90:93], v[178:181], v[186:189], v[90:93]
	v_mfma_f32_16x16x32_bf16 v[86:89], v[168:171], v[194:197], v[86:89]
	v_mfma_f32_16x16x32_bf16 v[82:85], v[178:181], v[194:197], v[82:85]
	v_mfma_f32_16x16x32_bf16 v[78:81], v[168:171], v[202:205], v[78:81]
	v_mfma_f32_16x16x32_bf16 v[74:77], v[178:181], v[202:205], v[74:77]
	v_mfma_f32_16x16x32_bf16 v[70:73], v[168:171], v[210:213], v[70:73]
	v_mfma_f32_16x16x32_bf16 v[66:69], v[178:181], v[210:213], v[66:69]
	v_mfma_f32_16x16x32_bf16 v[94:97], v[174:177], v[190:193], v[94:97]
	v_mfma_f32_16x16x32_bf16 v[90:93], v[182:185], v[190:193], v[90:93]
	v_mfma_f32_16x16x32_bf16 v[86:89], v[174:177], v[198:201], v[86:89]
	v_mfma_f32_16x16x32_bf16 v[82:85], v[182:185], v[198:201], v[82:85]
	v_mfma_f32_16x16x32_bf16 v[78:81], v[174:177], v[206:209], v[78:81]
	v_mfma_f32_16x16x32_bf16 v[74:77], v[182:185], v[206:209], v[74:77]
	v_mfma_f32_16x16x32_bf16 v[70:73], v[174:177], v[214:217], v[70:73]
	v_mfma_f32_16x16x32_bf16 v[66:69], v[182:185], v[214:217], v[66:69]
	s_barrier
	s_setprio 0
	s_mov_b32 m0, s12
	s_mov_b64 s[98:99], s[50:51]
	s_add_u32 s58, s50, 0x80000
	ds_read_b128 v[186:189], v172 offset:16384
	ds_read_b128 v[190:193], v172 offset:17408
	ds_read_b128 v[194:197], v172 offset:18432
	ds_read_b128 v[198:201], v172 offset:19456
	ds_read_b128 v[202:205], v172 offset:20480
	ds_read_b128 v[206:209], v172 offset:21504
	ds_read_b128 v[210:213], v172 offset:22528
	ds_read_b128 v[214:217], v172 offset:23552
	global_load_lds_dwordx4 v152, s[50:51]
	s_mov_b32 m0, s13
	s_addc_u32 s59, s51, 0
	global_load_lds_dwordx4 v156, s[50:51]
	s_mov_b32 m0, s43
	s_mov_b64 s[100:101], s[64:65]
	global_load_lds_dwordx4 v152, s[58:59]
	s_mov_b32 m0, s46
	s_nop 0
	global_load_lds_dwordx4 v156, s[58:59]
	s_waitcnt vmcnt(6)
	s_waitcnt lgkmcnt(0)
	s_setprio 1
	s_barrier
	v_mfma_f32_16x16x32_bf16 v[62:65], v[134:137], v[186:189], v[62:65]
	v_mfma_f32_16x16x32_bf16 v[58:61], v[142:145], v[186:189], v[58:61]
	v_mfma_f32_16x16x32_bf16 v[54:57], v[134:137], v[194:197], v[54:57]
	v_mfma_f32_16x16x32_bf16 v[50:53], v[142:145], v[194:197], v[50:53]
	v_mfma_f32_16x16x32_bf16 v[46:49], v[134:137], v[202:205], v[46:49]
	v_mfma_f32_16x16x32_bf16 v[42:45], v[142:145], v[202:205], v[42:45]
	v_mfma_f32_16x16x32_bf16 v[38:41], v[134:137], v[210:213], v[38:41]
	v_mfma_f32_16x16x32_bf16 v[34:37], v[142:145], v[210:213], v[34:37]
	v_mfma_f32_16x16x32_bf16 v[62:65], v[138:141], v[190:193], v[62:65]
	v_mfma_f32_16x16x32_bf16 v[58:61], v[146:149], v[190:193], v[58:61]
	v_mfma_f32_16x16x32_bf16 v[54:57], v[138:141], v[198:201], v[54:57]
	v_mfma_f32_16x16x32_bf16 v[50:53], v[146:149], v[198:201], v[50:53]
	v_mfma_f32_16x16x32_bf16 v[46:49], v[138:141], v[206:209], v[46:49]
	v_mfma_f32_16x16x32_bf16 v[42:45], v[146:149], v[206:209], v[42:45]
	v_mfma_f32_16x16x32_bf16 v[38:41], v[138:141], v[214:217], v[38:41]
	v_mfma_f32_16x16x32_bf16 v[34:37], v[146:149], v[214:217], v[34:37]
	s_setprio 0
	s_setprio 1
	v_mfma_f32_16x16x32_bf16 v[30:33], v[168:171], v[186:189], v[30:33]
	v_mfma_f32_16x16x32_bf16 v[26:29], v[178:181], v[186:189], v[26:29]
	v_mfma_f32_16x16x32_bf16 v[22:25], v[168:171], v[194:197], v[22:25]
	v_mfma_f32_16x16x32_bf16 v[18:21], v[178:181], v[194:197], v[18:21]
	v_mfma_f32_16x16x32_bf16 v[14:17], v[168:171], v[202:205], v[14:17]
	v_mfma_f32_16x16x32_bf16 v[10:13], v[178:181], v[202:205], v[10:13]
	v_mfma_f32_16x16x32_bf16 v[6:9], v[168:171], v[210:213], v[6:9]
	v_mfma_f32_16x16x32_bf16 v[2:5], v[178:181], v[210:213], v[2:5]
	v_mfma_f32_16x16x32_bf16 v[30:33], v[174:177], v[190:193], v[30:33]
	v_mfma_f32_16x16x32_bf16 v[26:29], v[182:185], v[190:193], v[26:29]
	v_mfma_f32_16x16x32_bf16 v[22:25], v[174:177], v[198:201], v[22:25]
	v_mfma_f32_16x16x32_bf16 v[18:21], v[182:185], v[198:201], v[18:21]
	v_mfma_f32_16x16x32_bf16 v[14:17], v[174:177], v[206:209], v[14:17]
	v_mfma_f32_16x16x32_bf16 v[10:13], v[182:185], v[206:209], v[10:13]
	v_mfma_f32_16x16x32_bf16 v[6:9], v[174:177], v[214:217], v[6:9]
	v_mfma_f32_16x16x32_bf16 v[2:5], v[182:185], v[214:217], v[2:5]
	s_barrier
;     ...
;         for (int t = 2; t < nt; t += 2) PG8_KITER(t);
	s_setprio 0
	ds_read_b128 v[134:137], v132
	ds_read_b128 v[138:141], v132 offset:1024
	ds_read_b128 v[142:145], v132 offset:2048
	ds_read_b128 v[146:149], v132 offset:3072
	ds_read_b128 v[168:171], v133
	ds_read_b128 v[174:177], v133 offset:1024
	ds_read_b128 v[178:181], v133 offset:2048
	ds_read_b128 v[182:185], v133 offset:3072
	s_add_u32 s58, s64, 0x80000
	s_addc_u32 s59, s65, 0
	s_mov_b32 m0, s69
	s_nop 0
	global_load_lds_dwordx4 v150, s[100:101]
	s_mov_b32 m0, s70
	s_nop 0
	global_load_lds_dwordx4 v154, s[100:101]
	s_mov_b32 m0, s71
	ds_read_b128 v[186:189], v172 offset:32768
	ds_read_b128 v[190:193], v172 offset:33792
	ds_read_b128 v[194:197], v172 offset:34816
	ds_read_b128 v[198:201], v172 offset:35840
	ds_read_b128 v[202:205], v172 offset:36864
	ds_read_b128 v[206:209], v172 offset:37888
	ds_read_b128 v[210:213], v172 offset:38912
	ds_read_b128 v[214:217], v172 offset:39936
	global_load_lds_dwordx4 v150, s[58:59]
	s_mov_b32 m0, s72
	s_nop 0
	global_load_lds_dwordx4 v154, s[58:59]
	s_waitcnt vmcnt(8)
	s_waitcnt lgkmcnt(0)
	s_setprio 1
	s_barrier
	v_mfma_f32_16x16x32_bf16 v[126:129], v[134:137], v[186:189], v[126:129]
	v_mfma_f32_16x16x32_bf16 v[122:125], v[142:145], v[186:189], v[122:125]
	v_mfma_f32_16x16x32_bf16 v[118:121], v[134:137], v[194:197], v[118:121]
	v_mfma_f32_16x16x32_bf16 v[114:117], v[142:145], v[194:197], v[114:117]
	v_mfma_f32_16x16x32_bf16 v[110:113], v[134:137], v[202:205], v[110:113]
	v_mfma_f32_16x16x32_bf16 v[106:109], v[142:145], v[202:205], v[106:109]
	v_mfma_f32_16x16x32_bf16 v[102:105], v[134:137], v[210:213], v[102:105]
	v_mfma_f32_16x16x32_bf16 v[98:101], v[142:145], v[210:213], v[98:101]
	v_mfma_f32_16x16x32_bf16 v[126:129], v[138:141], v[190:193], v[126:129]
	v_mfma_f32_16x16x32_bf16 v[122:125], v[146:149], v[190:193], v[122:125]
	v_mfma_f32_16x16x32_bf16 v[118:121], v[138:141], v[198:201], v[118:121]
	v_mfma_f32_16x16x32_bf16 v[114:117], v[146:149], v[198:201], v[114:117]
	v_mfma_f32_16x16x32_bf16 v[110:113], v[138:141], v[206:209], v[110:113]
	v_mfma_f32_16x16x32_bf16 v[106:109], v[146:149], v[206:209], v[106:109]
	v_mfma_f32_16x16x32_bf16 v[102:105], v[138:141], v[214:217], v[102:105]
	v_mfma_f32_16x16x32_bf16 v[98:101], v[146:149], v[214:217], v[98:101]
	s_setprio 0
	s_setprio 1
	v_mfma_f32_16x16x32_bf16 v[94:97], v[168:171], v[186:189], v[94:97]
	v_mfma_f32_16x16x32_bf16 v[90:93], v[178:181], v[186:189], v[90:93]
	v_mfma_f32_16x16x32_bf16 v[86:89], v[168:171], v[194:197], v[86:89]
	v_mfma_f32_16x16x32_bf16 v[82:85], v[178:181], v[194:197], v[82:85]
	v_mfma_f32_16x16x32_bf16 v[78:81], v[168:171], v[202:205], v[78:81]
	v_mfma_f32_16x16x32_bf16 v[74:77], v[178:181], v[202:205], v[74:77]
	v_mfma_f32_16x16x32_bf16 v[70:73], v[168:171], v[210:213], v[70:73]
	v_mfma_f32_16x16x32_bf16 v[66:69], v[178:181], v[210:213], v[66:69]
	v_mfma_f32_16x16x32_bf16 v[94:97], v[174:177], v[190:193], v[94:97]
	v_mfma_f32_16x16x32_bf16 v[90:93], v[182:185], v[190:193], v[90:93]
	v_mfma_f32_16x16x32_bf16 v[86:89], v[174:177], v[198:201], v[86:89]
	v_mfma_f32_16x16x32_bf16 v[82:85], v[182:185], v[198:201], v[82:85]
	v_mfma_f32_16x16x32_bf16 v[78:81], v[174:177], v[206:209], v[78:81]
	v_mfma_f32_16x16x32_bf16 v[74:77], v[182:185], v[206:209], v[74:77]
	v_mfma_f32_16x16x32_bf16 v[70:73], v[174:177], v[214:217], v[70:73]
	v_mfma_f32_16x16x32_bf16 v[66:69], v[182:185], v[214:217], v[66:69]
	s_barrier
	s_setprio 0
	s_mov_b32 m0, s47
	s_add_u32 s98, s98, 0x80
	s_addc_u32 s99, s99, 0
	s_add_u32 s100, s100, 0x80
	s_addc_u32 s101, s101, 0
	s_add_u32 s50, s50, 0x80080
	ds_read_b128 v[186:189], v172 offset:49152
	ds_read_b128 v[190:193], v172 offset:50176
	ds_read_b128 v[194:197], v172 offset:51200
	ds_read_b128 v[198:201], v172 offset:52224
	ds_read_b128 v[202:205], v172 offset:53248
	ds_read_b128 v[206:209], v172 offset:54272
	ds_read_b128 v[210:213], v172 offset:55296
	ds_read_b128 v[214:217], v172 offset:56320
	global_load_lds_dwordx4 v152, s[98:99]
	s_mov_b32 m0, s53
	s_addc_u32 s51, s51, 0
	global_load_lds_dwordx4 v156, s[98:99]
	s_mov_b32 m0, s55
	s_nop 0
	global_load_lds_dwordx4 v152, s[50:51]
	s_mov_b32 m0, s56
	s_nop 0
	global_load_lds_dwordx4 v156, s[50:51]
	s_waitcnt vmcnt(6)
	s_waitcnt lgkmcnt(0)
	s_setprio 1
	s_barrier
	v_mfma_f32_16x16x32_bf16 v[62:65], v[134:137], v[186:189], v[62:65]
	v_mfma_f32_16x16x32_bf16 v[58:61], v[142:145], v[186:189], v[58:61]
	v_mfma_f32_16x16x32_bf16 v[54:57], v[134:137], v[194:197], v[54:57]
	v_mfma_f32_16x16x32_bf16 v[50:53], v[142:145], v[194:197], v[50:53]
	v_mfma_f32_16x16x32_bf16 v[46:49], v[134:137], v[202:205], v[46:49]
	v_mfma_f32_16x16x32_bf16 v[42:45], v[142:145], v[202:205], v[42:45]
	v_mfma_f32_16x16x32_bf16 v[38:41], v[134:137], v[210:213], v[38:41]
	v_mfma_f32_16x16x32_bf16 v[34:37], v[142:145], v[210:213], v[34:37]
	v_mfma_f32_16x16x32_bf16 v[62:65], v[138:141], v[190:193], v[62:65]
	v_mfma_f32_16x16x32_bf16 v[58:61], v[146:149], v[190:193], v[58:61]
	v_mfma_f32_16x16x32_bf16 v[54:57], v[138:141], v[198:201], v[54:57]
	v_mfma_f32_16x16x32_bf16 v[50:53], v[146:149], v[198:201], v[50:53]
	v_mfma_f32_16x16x32_bf16 v[46:49], v[138:141], v[206:209], v[46:49]
	v_mfma_f32_16x16x32_bf16 v[42:45], v[146:149], v[206:209], v[42:45]
	v_mfma_f32_16x16x32_bf16 v[38:41], v[138:141], v[214:217], v[38:41]
	v_mfma_f32_16x16x32_bf16 v[34:37], v[146:149], v[214:217], v[34:37]
	s_setprio 0
	s_setprio 1
	v_mfma_f32_16x16x32_bf16 v[30:33], v[168:171], v[186:189], v[30:33]
	v_mfma_f32_16x16x32_bf16 v[26:29], v[178:181], v[186:189], v[26:29]
	v_mfma_f32_16x16x32_bf16 v[22:25], v[168:171], v[194:197], v[22:25]
	v_mfma_f32_16x16x32_bf16 v[18:21], v[178:181], v[194:197], v[18:21]
	v_mfma_f32_16x16x32_bf16 v[14:17], v[168:171], v[202:205], v[14:17]
	v_mfma_f32_16x16x32_bf16 v[10:13], v[178:181], v[202:205], v[10:13]
	v_mfma_f32_16x16x32_bf16 v[6:9], v[168:171], v[210:213], v[6:9]
	v_mfma_f32_16x16x32_bf16 v[2:5], v[178:181], v[210:213], v[2:5]
	v_mfma_f32_16x16x32_bf16 v[30:33], v[174:177], v[190:193], v[30:33]
	v_mfma_f32_16x16x32_bf16 v[26:29], v[182:185], v[190:193], v[26:29]
	v_mfma_f32_16x16x32_bf16 v[22:25], v[174:177], v[198:201], v[22:25]
	v_mfma_f32_16x16x32_bf16 v[18:21], v[182:185], v[198:201], v[18:21]
	v_mfma_f32_16x16x32_bf16 v[14:17], v[174:177], v[206:209], v[14:17]
	v_mfma_f32_16x16x32_bf16 v[10:13], v[182:185], v[206:209], v[10:13]
	v_mfma_f32_16x16x32_bf16 v[6:9], v[174:177], v[214:217], v[6:9]
	v_mfma_f32_16x16x32_bf16 v[2:5], v[182:185], v[214:217], v[2:5]
	s_barrier
	s_setprio 0
	s_add_i32 s26, s26, 2
	s_add_u32 s62, s62, 0x100
	s_addc_u32 s63, s63, 0
	s_add_u32 s14, s14, 0x100
	s_addc_u32 s15, s15, 0
	s_cmp_gt_u32 s26, 29
	s_cbranch_scc0 .LBB0_930
	s_mov_b32 m0, s77
	s_nop 0
	global_load_lds_dwordx4 v150, s[100:101]
	s_mov_b32 m0, s78
	s_nop 0
	global_load_lds_dwordx4 v154, s[100:101]
	s_and_b64 vcc, exec, s[18:19]
	s_cbranch_vccz .LBB0_933
	s_barrier

.LBB0_1014:
	ds_read_b128 v[132:135], v182
	ds_read_b128 v[136:139], v182 offset:1024
	ds_read_b128 v[140:143], v182 offset:2048
	ds_read_b128 v[144:147], v182 offset:3072
	ds_read_b128 v[148:151], v183
	ds_read_b128 v[170:173], v183 offset:1024
	ds_read_b128 v[174:177], v183 offset:2048
	ds_read_b128 v[178:181], v183 offset:3072
	s_add_u32 s27, s48, 0xfff00080
	s_addc_u32 s42, s49, -1
	s_cmp_eq_u32 s26, 60
	s_cselect_b32 s51, s29, s42
	s_cselect_b32 s50, s41, s27
	s_cselect_b32 s43, s0, s15
	s_cselect_b32 s42, s68, s14
	s_cmp_eq_u32 s26, 0
	s_cbranch_scc1 .Lrb2_skip_31798
	s_mov_b32 m0, s54
	s_nop 0
	global_load_lds_dwordx4 v154, s[100:101]
	s_mov_b32 m0, s55
	s_nop 0
	global_load_lds_dwordx4 v158, s[100:101]
.Lrb2_skip_31798:
	s_mov_b32 m0, s61
	ds_read_b128 v[186:189], v184
	ds_read_b128 v[190:193], v184 offset:1024
	ds_read_b128 v[194:197], v184 offset:2048
	ds_read_b128 v[198:201], v184 offset:3072
	ds_read_b128 v[202:205], v184 offset:4096
	ds_read_b128 v[206:209], v184 offset:5120
	ds_read_b128 v[210:213], v184 offset:6144
	ds_read_b128 v[214:217], v184 offset:7168
	global_load_lds_dwordx4 v162, s[48:49]
	s_mov_b32 m0, s62
	s_nop 0
	global_load_lds_dwordx4 v164, s[48:49]
	s_waitcnt vmcnt(8)
	s_waitcnt lgkmcnt(0)
	s_setprio 1
	s_barrier
	v_mfma_f32_16x16x32_bf16 v[122:125], v[132:135], v[186:189], v[122:125]
	v_mfma_f32_16x16x32_bf16 v[118:121], v[140:143], v[186:189], v[118:121]
	v_mfma_f32_16x16x32_bf16 v[110:113], v[132:135], v[194:197], v[110:113]
	v_mfma_f32_16x16x32_bf16 v[106:109], v[140:143], v[194:197], v[106:109]
	v_mfma_f32_16x16x32_bf16 v[94:97], v[132:135], v[202:205], v[94:97]
	v_mfma_f32_16x16x32_bf16 v[90:93], v[140:143], v[202:205], v[90:93]
	v_mfma_f32_16x16x32_bf16 v[78:81], v[132:135], v[210:213], v[78:81]
	v_mfma_f32_16x16x32_bf16 v[74:77], v[140:143], v[210:213], v[74:77]
	v_mfma_f32_16x16x32_bf16 v[122:125], v[136:139], v[190:193], v[122:125]
	v_mfma_f32_16x16x32_bf16 v[118:121], v[144:147], v[190:193], v[118:121]
	v_mfma_f32_16x16x32_bf16 v[110:113], v[136:139], v[198:201], v[110:113]
	v_mfma_f32_16x16x32_bf16 v[106:109], v[144:147], v[198:201], v[106:109]
	v_mfma_f32_16x16x32_bf16 v[94:97], v[136:139], v[206:209], v[94:97]
	v_mfma_f32_16x16x32_bf16 v[90:93], v[144:147], v[206:209], v[90:93]
	v_mfma_f32_16x16x32_bf16 v[78:81], v[136:139], v[214:217], v[78:81]
	v_mfma_f32_16x16x32_bf16 v[74:77], v[144:147], v[214:217], v[74:77]
	s_setprio 0
	s_setprio 1
	v_mfma_f32_16x16x32_bf16 v[126:129], v[148:151], v[186:189], v[126:129]
	v_mfma_f32_16x16x32_bf16 v[114:117], v[174:177], v[186:189], v[114:117]
	v_mfma_f32_16x16x32_bf16 v[102:105], v[148:151], v[194:197], v[102:105]
	v_mfma_f32_16x16x32_bf16 v[98:101], v[174:177], v[194:197], v[98:101]
	v_mfma_f32_16x16x32_bf16 v[86:89], v[148:151], v[202:205], v[86:89]
	v_mfma_f32_16x16x32_bf16 v[82:85], v[174:177], v[202:205], v[82:85]
	v_mfma_f32_16x16x32_bf16 v[70:73], v[148:151], v[210:213], v[70:73]
	v_mfma_f32_16x16x32_bf16 v[66:69], v[174:177], v[210:213], v[66:69]
	v_mfma_f32_16x16x32_bf16 v[126:129], v[170:173], v[190:193], v[126:129]
	v_mfma_f32_16x16x32_bf16 v[114:117], v[178:181], v[190:193], v[114:117]
	v_mfma_f32_16x16x32_bf16 v[102:105], v[170:173], v[198:201], v[102:105]
	v_mfma_f32_16x16x32_bf16 v[98:101], v[178:181], v[198:201], v[98:101]
	v_mfma_f32_16x16x32_bf16 v[86:89], v[170:173], v[206:209], v[86:89]
	v_mfma_f32_16x16x32_bf16 v[82:85], v[178:181], v[206:209], v[82:85]
	v_mfma_f32_16x16x32_bf16 v[70:73], v[170:173], v[214:217], v[70:73]
	v_mfma_f32_16x16x32_bf16 v[66:69], v[178:181], v[214:217], v[66:69]
	s_barrier
	s_setprio 0
	s_mov_b32 m0, s63
	s_mov_b64 s[98:99], s[42:43]
	s_add_u32 s72, s42, 0x100000
	ds_read_b128 v[186:189], v184 offset:16384
	ds_read_b128 v[190:193], v184 offset:17408
	ds_read_b128 v[194:197], v184 offset:18432
	ds_read_b128 v[198:201], v184 offset:19456
	ds_read_b128 v[202:205], v184 offset:20480
	ds_read_b128 v[206:209], v184 offset:21504
	ds_read_b128 v[210:213], v184 offset:22528
	ds_read_b128 v[214:217], v184 offset:23552
	global_load_lds_dwordx4 v156, s[42:43]
	s_mov_b32 m0, s64
	s_addc_u32 s73, s43, 0
	global_load_lds_dwordx4 v160, s[42:43]
	s_mov_b32 m0, s69
	s_mov_b64 s[100:101], s[50:51]
	global_load_lds_dwordx4 v156, s[72:73]
	s_mov_b32 m0, s46
	s_nop 0
	global_load_lds_dwordx4 v160, s[72:73]
	s_waitcnt vmcnt(6)
	s_waitcnt lgkmcnt(0)
	s_setprio 1
	s_barrier
	v_mfma_f32_16x16x32_bf16 v[58:61], v[132:135], v[186:189], v[58:61]
	v_mfma_f32_16x16x32_bf16 v[54:57], v[140:143], v[186:189], v[54:57]
	v_mfma_f32_16x16x32_bf16 v[46:49], v[132:135], v[194:197], v[46:49]
	v_mfma_f32_16x16x32_bf16 v[42:45], v[140:143], v[194:197], v[42:45]
	v_mfma_f32_16x16x32_bf16 v[30:33], v[132:135], v[202:205], v[30:33]
	v_mfma_f32_16x16x32_bf16 v[26:29], v[140:143], v[202:205], v[26:29]
	v_mfma_f32_16x16x32_bf16 v[14:17], v[132:135], v[210:213], v[14:17]
	v_mfma_f32_16x16x32_bf16 v[10:13], v[140:143], v[210:213], v[10:13]
	v_mfma_f32_16x16x32_bf16 v[58:61], v[136:139], v[190:193], v[58:61]
	v_mfma_f32_16x16x32_bf16 v[54:57], v[144:147], v[190:193], v[54:57]
	v_mfma_f32_16x16x32_bf16 v[46:49], v[136:139], v[198:201], v[46:49]
	v_mfma_f32_16x16x32_bf16 v[42:45], v[144:147], v[198:201], v[42:45]
	v_mfma_f32_16x16x32_bf16 v[30:33], v[136:139], v[206:209], v[30:33]
	v_mfma_f32_16x16x32_bf16 v[26:29], v[144:147], v[206:209], v[26:29]
	v_mfma_f32_16x16x32_bf16 v[14:17], v[136:139], v[214:217], v[14:17]
	v_mfma_f32_16x16x32_bf16 v[10:13], v[144:147], v[214:217], v[10:13]
	s_setprio 0
	s_setprio 1
	v_mfma_f32_16x16x32_bf16 v[62:65], v[148:151], v[186:189], v[62:65]
	v_mfma_f32_16x16x32_bf16 v[50:53], v[174:177], v[186:189], v[50:53]
	v_mfma_f32_16x16x32_bf16 v[38:41], v[148:151], v[194:197], v[38:41]
	v_mfma_f32_16x16x32_bf16 v[34:37], v[174:177], v[194:197], v[34:37]
	v_mfma_f32_16x16x32_bf16 v[22:25], v[148:151], v[202:205], v[22:25]
	v_mfma_f32_16x16x32_bf16 v[18:21], v[174:177], v[202:205], v[18:21]
	v_mfma_f32_16x16x32_bf16 v[6:9], v[148:151], v[210:213], v[6:9]
	v_mfma_f32_16x16x32_bf16 v[2:5], v[174:177], v[210:213], v[2:5]
	v_mfma_f32_16x16x32_bf16 v[62:65], v[170:173], v[190:193], v[62:65]
	v_mfma_f32_16x16x32_bf16 v[50:53], v[178:181], v[190:193], v[50:53]
	v_mfma_f32_16x16x32_bf16 v[38:41], v[170:173], v[198:201], v[38:41]
	v_mfma_f32_16x16x32_bf16 v[34:37], v[178:181], v[198:201], v[34:37]
	v_mfma_f32_16x16x32_bf16 v[22:25], v[170:173], v[206:209], v[22:25]
	v_mfma_f32_16x16x32_bf16 v[18:21], v[178:181], v[206:209], v[18:21]
	v_mfma_f32_16x16x32_bf16 v[6:9], v[170:173], v[214:217], v[6:9]
	v_mfma_f32_16x16x32_bf16 v[2:5], v[178:181], v[214:217], v[2:5]
	s_barrier
;     ...
;         for (int t = 2; t < nt; t += 2) PG8_KITER(t);
	s_setprio 0
	ds_read_b128 v[132:135], v130
	ds_read_b128 v[136:139], v130 offset:1024
	ds_read_b128 v[140:143], v130 offset:2048
	ds_read_b128 v[144:147], v130 offset:3072
	ds_read_b128 v[148:151], v131
	ds_read_b128 v[170:173], v131 offset:1024
	ds_read_b128 v[174:177], v131 offset:2048
	ds_read_b128 v[178:181], v131 offset:3072
	s_add_u32 s50, s50, 0x100000
	s_addc_u32 s51, s51, 0
	s_mov_b32 m0, s13
	s_nop 0
	global_load_lds_dwordx4 v154, s[100:101]
	s_mov_b32 m0, s33
	s_nop 0
	global_load_lds_dwordx4 v158, s[100:101]
	s_mov_b32 m0, s52
	ds_read_b128 v[186:189], v184 offset:32768
	ds_read_b128 v[190:193], v184 offset:33792
	ds_read_b128 v[194:197], v184 offset:34816
	ds_read_b128 v[198:201], v184 offset:35840
	ds_read_b128 v[202:205], v184 offset:36864
	ds_read_b128 v[206:209], v184 offset:37888
	ds_read_b128 v[210:213], v184 offset:38912
	ds_read_b128 v[214:217], v184 offset:39936
	global_load_lds_dwordx4 v154, s[50:51]
	s_mov_b32 m0, s53
	s_nop 0
	global_load_lds_dwordx4 v158, s[50:51]
	s_waitcnt vmcnt(8)
	s_waitcnt lgkmcnt(0)
	s_setprio 1
	s_barrier
	v_mfma_f32_16x16x32_bf16 v[122:125], v[132:135], v[186:189], v[122:125]
	v_mfma_f32_16x16x32_bf16 v[118:121], v[140:143], v[186:189], v[118:121]
	v_mfma_f32_16x16x32_bf16 v[110:113], v[132:135], v[194:197], v[110:113]
	v_mfma_f32_16x16x32_bf16 v[106:109], v[140:143], v[194:197], v[106:109]
	v_mfma_f32_16x16x32_bf16 v[94:97], v[132:135], v[202:205], v[94:97]
	v_mfma_f32_16x16x32_bf16 v[90:93], v[140:143], v[202:205], v[90:93]
	v_mfma_f32_16x16x32_bf16 v[78:81], v[132:135], v[210:213], v[78:81]
	v_mfma_f32_16x16x32_bf16 v[74:77], v[140:143], v[210:213], v[74:77]
	v_mfma_f32_16x16x32_bf16 v[122:125], v[136:139], v[190:193], v[122:125]
	v_mfma_f32_16x16x32_bf16 v[118:121], v[144:147], v[190:193], v[118:121]
	v_mfma_f32_16x16x32_bf16 v[110:113], v[136:139], v[198:201], v[110:113]
	v_mfma_f32_16x16x32_bf16 v[106:109], v[144:147], v[198:201], v[106:109]
	v_mfma_f32_16x16x32_bf16 v[94:97], v[136:139], v[206:209], v[94:97]
	v_mfma_f32_16x16x32_bf16 v[90:93], v[144:147], v[206:209], v[90:93]
	v_mfma_f32_16x16x32_bf16 v[78:81], v[136:139], v[214:217], v[78:81]
	v_mfma_f32_16x16x32_bf16 v[74:77], v[144:147], v[214:217], v[74:77]
	s_setprio 0
	s_setprio 1
	v_mfma_f32_16x16x32_bf16 v[126:129], v[148:151], v[186:189], v[126:129]
	v_mfma_f32_16x16x32_bf16 v[114:117], v[174:177], v[186:189], v[114:117]
	v_mfma_f32_16x16x32_bf16 v[102:105], v[148:151], v[194:197], v[102:105]
	v_mfma_f32_16x16x32_bf16 v[98:101], v[174:177], v[194:197], v[98:101]
	v_mfma_f32_16x16x32_bf16 v[86:89], v[148:151], v[202:205], v[86:89]
	v_mfma_f32_16x16x32_bf16 v[82:85], v[174:177], v[202:205], v[82:85]
	v_mfma_f32_16x16x32_bf16 v[70:73], v[148:151], v[210:213], v[70:73]
	v_mfma_f32_16x16x32_bf16 v[66:69], v[174:177], v[210:213], v[66:69]
	v_mfma_f32_16x16x32_bf16 v[126:129], v[170:173], v[190:193], v[126:129]
	v_mfma_f32_16x16x32_bf16 v[114:117], v[178:181], v[190:193], v[114:117]
	v_mfma_f32_16x16x32_bf16 v[102:105], v[170:173], v[198:201], v[102:105]
	v_mfma_f32_16x16x32_bf16 v[98:101], v[178:181], v[198:201], v[98:101]
	v_mfma_f32_16x16x32_bf16 v[86:89], v[170:173], v[206:209], v[86:89]
	v_mfma_f32_16x16x32_bf16 v[82:85], v[178:181], v[206:209], v[82:85]
	v_mfma_f32_16x16x32_bf16 v[70:73], v[170:173], v[214:217], v[70:73]
	v_mfma_f32_16x16x32_bf16 v[66:69], v[178:181], v[214:217], v[66:69]
	s_barrier
	s_setprio 0
	s_mov_b32 m0, s47
	s_add_u32 s98, s98, 0x80
	s_addc_u32 s99, s99, 0
	s_add_u32 s100, s100, 0x80
	s_addc_u32 s101, s101, 0
	s_add_u32 s42, s42, 0x100080
	ds_read_b128 v[186:189], v184 offset:49152
	ds_read_b128 v[190:193], v184 offset:50176
	ds_read_b128 v[194:197], v184 offset:51200
	ds_read_b128 v[198:201], v184 offset:52224
	ds_read_b128 v[202:205], v184 offset:53248
	ds_read_b128 v[206:209], v184 offset:54272
	ds_read_b128 v[210:213], v184 offset:55296
	ds_read_b128 v[214:217], v184 offset:56320
	global_load_lds_dwordx4 v156, s[98:99]
	s_mov_b32 m0, s70
	s_addc_u32 s43, s43, 0
	global_load_lds_dwordx4 v160, s[98:99]
	s_mov_b32 m0, s56
	s_nop 0
	global_load_lds_dwordx4 v156, s[42:43]
	s_mov_b32 m0, s57
	s_nop 0
	global_load_lds_dwordx4 v160, s[42:43]
	s_waitcnt vmcnt(6)
	s_waitcnt lgkmcnt(0)
	s_setprio 1
	s_barrier
	v_mfma_f32_16x16x32_bf16 v[58:61], v[132:135], v[186:189], v[58:61]
	v_mfma_f32_16x16x32_bf16 v[54:57], v[140:143], v[186:189], v[54:57]
	v_mfma_f32_16x16x32_bf16 v[46:49], v[132:135], v[194:197], v[46:49]
	v_mfma_f32_16x16x32_bf16 v[42:45], v[140:143], v[194:197], v[42:45]
	v_mfma_f32_16x16x32_bf16 v[30:33], v[132:135], v[202:205], v[30:33]
	v_mfma_f32_16x16x32_bf16 v[26:29], v[140:143], v[202:205], v[26:29]
	v_mfma_f32_16x16x32_bf16 v[14:17], v[132:135], v[210:213], v[14:17]
	v_mfma_f32_16x16x32_bf16 v[10:13], v[140:143], v[210:213], v[10:13]
	v_mfma_f32_16x16x32_bf16 v[58:61], v[136:139], v[190:193], v[58:61]
	v_mfma_f32_16x16x32_bf16 v[54:57], v[144:147], v[190:193], v[54:57]
	v_mfma_f32_16x16x32_bf16 v[46:49], v[136:139], v[198:201], v[46:49]
	v_mfma_f32_16x16x32_bf16 v[42:45], v[144:147], v[198:201], v[42:45]
	v_mfma_f32_16x16x32_bf16 v[30:33], v[136:139], v[206:209], v[30:33]
	v_mfma_f32_16x16x32_bf16 v[26:29], v[144:147], v[206:209], v[26:29]
	v_mfma_f32_16x16x32_bf16 v[14:17], v[136:139], v[214:217], v[14:17]
	v_mfma_f32_16x16x32_bf16 v[10:13], v[144:147], v[214:217], v[10:13]
	s_setprio 0
	s_setprio 1
	v_mfma_f32_16x16x32_bf16 v[62:65], v[148:151], v[186:189], v[62:65]
	v_mfma_f32_16x16x32_bf16 v[50:53], v[174:177], v[186:189], v[50:53]
	v_mfma_f32_16x16x32_bf16 v[38:41], v[148:151], v[194:197], v[38:41]
	v_mfma_f32_16x16x32_bf16 v[34:37], v[174:177], v[194:197], v[34:37]
	v_mfma_f32_16x16x32_bf16 v[22:25], v[148:151], v[202:205], v[22:25]
	v_mfma_f32_16x16x32_bf16 v[18:21], v[174:177], v[202:205], v[18:21]
	v_mfma_f32_16x16x32_bf16 v[6:9], v[148:151], v[210:213], v[6:9]
	v_mfma_f32_16x16x32_bf16 v[2:5], v[174:177], v[210:213], v[2:5]
	v_mfma_f32_16x16x32_bf16 v[62:65], v[170:173], v[190:193], v[62:65]
	v_mfma_f32_16x16x32_bf16 v[50:53], v[178:181], v[190:193], v[50:53]
	v_mfma_f32_16x16x32_bf16 v[38:41], v[170:173], v[198:201], v[38:41]
	v_mfma_f32_16x16x32_bf16 v[34:37], v[178:181], v[198:201], v[34:37]
	v_mfma_f32_16x16x32_bf16 v[22:25], v[170:173], v[206:209], v[22:25]
	v_mfma_f32_16x16x32_bf16 v[18:21], v[178:181], v[206:209], v[18:21]
	v_mfma_f32_16x16x32_bf16 v[6:9], v[170:173], v[214:217], v[6:9]
	v_mfma_f32_16x16x32_bf16 v[2:5], v[178:181], v[214:217], v[2:5]
	s_barrier
	s_setprio 0
	s_add_i32 s26, s26, 2
	s_add_u32 s48, s48, 0x100
	s_addc_u32 s49, s49, 0
	s_add_u32 s14, s14, 0x100
	s_addc_u32 s15, s15, 0
	s_cmp_gt_u32 s26, 61
	s_cbranch_scc0 .LBB0_1014
	s_mov_b32 m0, s54
	s_nop 0
	global_load_lds_dwordx4 v154, s[100:101]
	s_mov_b32 m0, s55
	s_nop 0
	global_load_lds_dwordx4 v158, s[100:101]
	s_and_b64 vcc, exec, s[18:19]
	s_cbranch_vccz .LBB0_1017
	s_barrier

.LBB0_1110:
	ds_read_b128 v[152:155], v148
	ds_read_b128 v[156:159], v148 offset:1024
	ds_read_b128 v[160:163], v148 offset:2048
	ds_read_b128 v[164:167], v148 offset:3072
	ds_read_b128 v[168:171], v149
	ds_read_b128 v[172:175], v149 offset:1024
	ds_read_b128 v[176:179], v149 offset:2048
	ds_read_b128 v[180:183], v149 offset:3072
	s_add_u32 s27, s0, 0xfff00080
	s_addc_u32 s52, s1, -1
	s_cmp_eq_u32 s26, 28
	s_cselect_b32 s55, s43, s52
	s_cselect_b32 s54, s42, s27
	s_cselect_b32 s53, s49, s15
	s_cselect_b32 s52, s48, s14
	s_cmp_eq_u32 s26, 0
	s_cbranch_scc1 .Lrb2_skip_34078
	s_mov_b32 m0, s61
	s_nop 0
	global_load_lds_dwordx4 v130, s[100:101]
	s_mov_b32 m0, s62
	s_nop 0
	global_load_lds_dwordx4 v132, s[100:101]
.Lrb2_skip_34078:
	s_mov_b32 m0, s41
	ds_read_b128 v[184:187], v150
	ds_read_b128 v[188:191], v150 offset:1024
	ds_read_b128 v[192:195], v150 offset:2048
	ds_read_b128 v[196:199], v150 offset:3072
	ds_read_b128 v[200:203], v150 offset:4096
	ds_read_b128 v[204:207], v150 offset:5120
	ds_read_b128 v[208:211], v150 offset:6144
	ds_read_b128 v[212:215], v150 offset:7168
	global_load_lds_dwordx4 v136, s[0:1]
	s_mov_b32 m0, s73
	s_nop 0
	global_load_lds_dwordx4 v138, s[0:1]
	s_waitcnt vmcnt(8)
	s_waitcnt lgkmcnt(0)
	s_setprio 1
	s_barrier
	v_mfma_f32_16x16x32_bf16 v[118:121], v[152:155], v[184:187], v[118:121]
	v_mfma_f32_16x16x32_bf16 v[114:117], v[160:163], v[184:187], v[114:117]
	v_mfma_f32_16x16x32_bf16 v[102:105], v[152:155], v[192:195], v[102:105]
	v_mfma_f32_16x16x32_bf16 v[98:101], v[160:163], v[192:195], v[98:101]
	v_mfma_f32_16x16x32_bf16 v[86:89], v[152:155], v[200:203], v[86:89]
	v_mfma_f32_16x16x32_bf16 v[82:85], v[160:163], v[200:203], v[82:85]
	v_mfma_f32_16x16x32_bf16 v[74:77], v[152:155], v[208:211], v[74:77]
	v_mfma_f32_16x16x32_bf16 v[54:57], v[160:163], v[208:211], v[54:57]
	v_mfma_f32_16x16x32_bf16 v[118:121], v[156:159], v[188:191], v[118:121]
	v_mfma_f32_16x16x32_bf16 v[114:117], v[164:167], v[188:191], v[114:117]
	v_mfma_f32_16x16x32_bf16 v[102:105], v[156:159], v[196:199], v[102:105]
	v_mfma_f32_16x16x32_bf16 v[98:101], v[164:167], v[196:199], v[98:101]
	v_mfma_f32_16x16x32_bf16 v[86:89], v[156:159], v[204:207], v[86:89]
	v_mfma_f32_16x16x32_bf16 v[82:85], v[164:167], v[204:207], v[82:85]
	v_mfma_f32_16x16x32_bf16 v[74:77], v[156:159], v[212:215], v[74:77]
	v_mfma_f32_16x16x32_bf16 v[54:57], v[164:167], v[212:215], v[54:57]
	s_setprio 0
	s_setprio 1
	v_mfma_f32_16x16x32_bf16 v[126:129], v[168:171], v[184:187], v[126:129]
	v_mfma_f32_16x16x32_bf16 v[122:125], v[176:179], v[184:187], v[122:125]
	v_mfma_f32_16x16x32_bf16 v[110:113], v[168:171], v[192:195], v[110:113]
	v_mfma_f32_16x16x32_bf16 v[106:109], v[176:179], v[192:195], v[106:109]
	v_mfma_f32_16x16x32_bf16 v[94:97], v[168:171], v[200:203], v[94:97]
	v_mfma_f32_16x16x32_bf16 v[90:93], v[176:179], v[200:203], v[90:93]
	v_mfma_f32_16x16x32_bf16 v[70:73], v[168:171], v[208:211], v[70:73]
	v_mfma_f32_16x16x32_bf16 v[50:53], v[176:179], v[208:211], v[50:53]
	v_mfma_f32_16x16x32_bf16 v[126:129], v[172:175], v[188:191], v[126:129]
	v_mfma_f32_16x16x32_bf16 v[122:125], v[180:183], v[188:191], v[122:125]
	v_mfma_f32_16x16x32_bf16 v[110:113], v[172:175], v[196:199], v[110:113]
	v_mfma_f32_16x16x32_bf16 v[106:109], v[180:183], v[196:199], v[106:109]
	v_mfma_f32_16x16x32_bf16 v[94:97], v[172:175], v[204:207], v[94:97]
	v_mfma_f32_16x16x32_bf16 v[90:93], v[180:183], v[204:207], v[90:93]
	v_mfma_f32_16x16x32_bf16 v[70:73], v[172:175], v[212:215], v[70:73]
	v_mfma_f32_16x16x32_bf16 v[50:53], v[180:183], v[212:215], v[50:53]
	s_barrier
	s_setprio 0
	s_mov_b32 m0, s74
	s_mov_b64 s[98:99], s[52:53]
	s_add_u32 s78, s52, 0x100000
	ds_read_b128 v[184:187], v150 offset:16384
	ds_read_b128 v[188:191], v150 offset:17408
	ds_read_b128 v[192:195], v150 offset:18432
	ds_read_b128 v[196:199], v150 offset:19456
	ds_read_b128 v[200:203], v150 offset:20480
	ds_read_b128 v[204:207], v150 offset:21504
	ds_read_b128 v[208:211], v150 offset:22528
	ds_read_b128 v[212:215], v150 offset:23552
	global_load_lds_dwordx4 v130, s[52:53]
	s_mov_b32 m0, s75
	s_addc_u32 s79, s53, 0
	global_load_lds_dwordx4 v132, s[52:53]
	s_mov_b32 m0, s76
	s_mov_b64 s[100:101], s[54:55]
	global_load_lds_dwordx4 v130, s[78:79]
	s_mov_b32 m0, s46
	s_nop 0
	global_load_lds_dwordx4 v132, s[78:79]
	s_waitcnt vmcnt(6)
	s_waitcnt lgkmcnt(0)
	s_setprio 1
	s_barrier
	v_mfma_f32_16x16x32_bf16 v[66:69], v[152:155], v[184:187], v[66:69]
	v_mfma_f32_16x16x32_bf16 v[62:65], v[160:163], v[184:187], v[62:65]
	v_mfma_f32_16x16x32_bf16 v[42:45], v[152:155], v[192:195], v[42:45]
	v_mfma_f32_16x16x32_bf16 v[38:41], v[160:163], v[192:195], v[38:41]
	v_mfma_f32_16x16x32_bf16 v[26:29], v[152:155], v[200:203], v[26:29]
	v_mfma_f32_16x16x32_bf16 v[22:25], v[160:163], v[200:203], v[22:25]
	v_mfma_f32_16x16x32_bf16 v[6:9], v[152:155], v[208:211], v[6:9]
	v_mfma_f32_16x16x32_bf16 v[2:5], v[160:163], v[208:211], v[2:5]
	v_mfma_f32_16x16x32_bf16 v[66:69], v[156:159], v[188:191], v[66:69]
	v_mfma_f32_16x16x32_bf16 v[62:65], v[164:167], v[188:191], v[62:65]
	v_mfma_f32_16x16x32_bf16 v[42:45], v[156:159], v[196:199], v[42:45]
	v_mfma_f32_16x16x32_bf16 v[38:41], v[164:167], v[196:199], v[38:41]
	v_mfma_f32_16x16x32_bf16 v[26:29], v[156:159], v[204:207], v[26:29]
	v_mfma_f32_16x16x32_bf16 v[22:25], v[164:167], v[204:207], v[22:25]
	v_mfma_f32_16x16x32_bf16 v[6:9], v[156:159], v[212:215], v[6:9]
	v_mfma_f32_16x16x32_bf16 v[2:5], v[164:167], v[212:215], v[2:5]
	s_setprio 0
	s_setprio 1
	v_mfma_f32_16x16x32_bf16 v[78:81], v[168:171], v[184:187], v[78:81]
	v_mfma_f32_16x16x32_bf16 v[58:61], v[176:179], v[184:187], v[58:61]
	v_mfma_f32_16x16x32_bf16 v[46:49], v[168:171], v[192:195], v[46:49]
	v_mfma_f32_16x16x32_bf16 v[34:37], v[176:179], v[192:195], v[34:37]
	v_mfma_f32_16x16x32_bf16 v[30:33], v[168:171], v[200:203], v[30:33]
	v_mfma_f32_16x16x32_bf16 v[18:21], v[176:179], v[200:203], v[18:21]
	v_mfma_f32_16x16x32_bf16 v[14:17], v[168:171], v[208:211], v[14:17]
	v_mfma_f32_16x16x32_bf16 v[10:13], v[176:179], v[208:211], v[10:13]
	v_mfma_f32_16x16x32_bf16 v[78:81], v[172:175], v[188:191], v[78:81]
	v_mfma_f32_16x16x32_bf16 v[58:61], v[180:183], v[188:191], v[58:61]
	v_mfma_f32_16x16x32_bf16 v[46:49], v[172:175], v[196:199], v[46:49]
	v_mfma_f32_16x16x32_bf16 v[34:37], v[180:183], v[196:199], v[34:37]
	v_mfma_f32_16x16x32_bf16 v[30:33], v[172:175], v[204:207], v[30:33]
	v_mfma_f32_16x16x32_bf16 v[18:21], v[180:183], v[204:207], v[18:21]
	v_mfma_f32_16x16x32_bf16 v[14:17], v[172:175], v[212:215], v[14:17]
	v_mfma_f32_16x16x32_bf16 v[10:13], v[180:183], v[212:215], v[10:13]
	s_barrier
;     ...
;         for (int t = 2; t < nt; t += 2) PG8_KITER(t);
	s_setprio 0
	ds_read_b128 v[152:155], v134
	ds_read_b128 v[156:159], v134 offset:1024
	ds_read_b128 v[160:163], v134 offset:2048
	ds_read_b128 v[164:167], v134 offset:3072
	ds_read_b128 v[168:171], v144
	ds_read_b128 v[172:175], v144 offset:1024
	ds_read_b128 v[176:179], v144 offset:2048
	ds_read_b128 v[180:183], v144 offset:3072
	s_add_u32 s54, s54, 0x100000
	s_addc_u32 s55, s55, 0
	s_mov_b32 m0, s33
	s_nop 0
	global_load_lds_dwordx4 v130, s[100:101]
	s_mov_b32 m0, s51
	s_nop 0
	global_load_lds_dwordx4 v132, s[100:101]
	s_mov_b32 m0, s58
	ds_read_b128 v[184:187], v150 offset:32768
	ds_read_b128 v[188:191], v150 offset:33792
	ds_read_b128 v[192:195], v150 offset:34816
	ds_read_b128 v[196:199], v150 offset:35840
	ds_read_b128 v[200:203], v150 offset:36864
	ds_read_b128 v[204:207], v150 offset:37888
	ds_read_b128 v[208:211], v150 offset:38912
	ds_read_b128 v[212:215], v150 offset:39936
	global_load_lds_dwordx4 v130, s[54:55]
	s_mov_b32 m0, s59
	s_nop 0
	global_load_lds_dwordx4 v132, s[54:55]
	s_waitcnt vmcnt(8)
	s_waitcnt lgkmcnt(0)
	s_setprio 1
	s_barrier
	v_mfma_f32_16x16x32_bf16 v[118:121], v[152:155], v[184:187], v[118:121]
	v_mfma_f32_16x16x32_bf16 v[114:117], v[160:163], v[184:187], v[114:117]
	v_mfma_f32_16x16x32_bf16 v[102:105], v[152:155], v[192:195], v[102:105]
	v_mfma_f32_16x16x32_bf16 v[98:101], v[160:163], v[192:195], v[98:101]
	v_mfma_f32_16x16x32_bf16 v[86:89], v[152:155], v[200:203], v[86:89]
	v_mfma_f32_16x16x32_bf16 v[82:85], v[160:163], v[200:203], v[82:85]
	v_mfma_f32_16x16x32_bf16 v[74:77], v[152:155], v[208:211], v[74:77]
	v_mfma_f32_16x16x32_bf16 v[54:57], v[160:163], v[208:211], v[54:57]
	v_mfma_f32_16x16x32_bf16 v[118:121], v[156:159], v[188:191], v[118:121]
	v_mfma_f32_16x16x32_bf16 v[114:117], v[164:167], v[188:191], v[114:117]
	v_mfma_f32_16x16x32_bf16 v[102:105], v[156:159], v[196:199], v[102:105]
	v_mfma_f32_16x16x32_bf16 v[98:101], v[164:167], v[196:199], v[98:101]
	v_mfma_f32_16x16x32_bf16 v[86:89], v[156:159], v[204:207], v[86:89]
	v_mfma_f32_16x16x32_bf16 v[82:85], v[164:167], v[204:207], v[82:85]
	v_mfma_f32_16x16x32_bf16 v[74:77], v[156:159], v[212:215], v[74:77]
	v_mfma_f32_16x16x32_bf16 v[54:57], v[164:167], v[212:215], v[54:57]
	s_setprio 0
	s_setprio 1
	v_mfma_f32_16x16x32_bf16 v[126:129], v[168:171], v[184:187], v[126:129]
	v_mfma_f32_16x16x32_bf16 v[122:125], v[176:179], v[184:187], v[122:125]
	v_mfma_f32_16x16x32_bf16 v[110:113], v[168:171], v[192:195], v[110:113]
	v_mfma_f32_16x16x32_bf16 v[106:109], v[176:179], v[192:195], v[106:109]
	v_mfma_f32_16x16x32_bf16 v[94:97], v[168:171], v[200:203], v[94:97]
	v_mfma_f32_16x16x32_bf16 v[90:93], v[176:179], v[200:203], v[90:93]
	v_mfma_f32_16x16x32_bf16 v[70:73], v[168:171], v[208:211], v[70:73]
	v_mfma_f32_16x16x32_bf16 v[50:53], v[176:179], v[208:211], v[50:53]
	v_mfma_f32_16x16x32_bf16 v[126:129], v[172:175], v[188:191], v[126:129]
	v_mfma_f32_16x16x32_bf16 v[122:125], v[180:183], v[188:191], v[122:125]
	v_mfma_f32_16x16x32_bf16 v[110:113], v[172:175], v[196:199], v[110:113]
	v_mfma_f32_16x16x32_bf16 v[106:109], v[180:183], v[196:199], v[106:109]
	v_mfma_f32_16x16x32_bf16 v[94:97], v[172:175], v[204:207], v[94:97]
	v_mfma_f32_16x16x32_bf16 v[90:93], v[180:183], v[204:207], v[90:93]
	v_mfma_f32_16x16x32_bf16 v[70:73], v[172:175], v[212:215], v[70:73]
	v_mfma_f32_16x16x32_bf16 v[50:53], v[180:183], v[212:215], v[50:53]
	s_barrier
	s_setprio 0
	s_mov_b32 m0, s47
	s_add_u32 s98, s98, 0x80
	s_addc_u32 s99, s99, 0
	s_add_u32 s100, s100, 0x80
	s_addc_u32 s101, s101, 0
	s_add_u32 s52, s52, 0x100080
	ds_read_b128 v[184:187], v150 offset:49152
	ds_read_b128 v[188:191], v150 offset:50176
	ds_read_b128 v[192:195], v150 offset:51200
	ds_read_b128 v[196:199], v150 offset:52224
	ds_read_b128 v[200:203], v150 offset:53248
	ds_read_b128 v[204:207], v150 offset:54272
	ds_read_b128 v[208:211], v150 offset:55296
	ds_read_b128 v[212:215], v150 offset:56320
	global_load_lds_dwordx4 v130, s[98:99]
	s_mov_b32 m0, s77
	s_addc_u32 s53, s53, 0
	global_load_lds_dwordx4 v132, s[98:99]
	s_mov_b32 m0, s56
	s_nop 0
	global_load_lds_dwordx4 v130, s[52:53]
	s_mov_b32 m0, s57
	s_nop 0
	global_load_lds_dwordx4 v132, s[52:53]
	s_waitcnt vmcnt(6)
	s_waitcnt lgkmcnt(0)
	s_setprio 1
	s_barrier
	v_mfma_f32_16x16x32_bf16 v[66:69], v[152:155], v[184:187], v[66:69]
	v_mfma_f32_16x16x32_bf16 v[62:65], v[160:163], v[184:187], v[62:65]
	v_mfma_f32_16x16x32_bf16 v[42:45], v[152:155], v[192:195], v[42:45]
	v_mfma_f32_16x16x32_bf16 v[38:41], v[160:163], v[192:195], v[38:41]
	v_mfma_f32_16x16x32_bf16 v[26:29], v[152:155], v[200:203], v[26:29]
	v_mfma_f32_16x16x32_bf16 v[22:25], v[160:163], v[200:203], v[22:25]
	v_mfma_f32_16x16x32_bf16 v[6:9], v[152:155], v[208:211], v[6:9]
	v_mfma_f32_16x16x32_bf16 v[2:5], v[160:163], v[208:211], v[2:5]
	v_mfma_f32_16x16x32_bf16 v[66:69], v[156:159], v[188:191], v[66:69]
	v_mfma_f32_16x16x32_bf16 v[62:65], v[164:167], v[188:191], v[62:65]
	v_mfma_f32_16x16x32_bf16 v[42:45], v[156:159], v[196:199], v[42:45]
	v_mfma_f32_16x16x32_bf16 v[38:41], v[164:167], v[196:199], v[38:41]
	v_mfma_f32_16x16x32_bf16 v[26:29], v[156:159], v[204:207], v[26:29]
	v_mfma_f32_16x16x32_bf16 v[22:25], v[164:167], v[204:207], v[22:25]
	v_mfma_f32_16x16x32_bf16 v[6:9], v[156:159], v[212:215], v[6:9]
	v_mfma_f32_16x16x32_bf16 v[2:5], v[164:167], v[212:215], v[2:5]
	s_setprio 0
	s_setprio 1
	v_mfma_f32_16x16x32_bf16 v[78:81], v[168:171], v[184:187], v[78:81]
	v_mfma_f32_16x16x32_bf16 v[58:61], v[176:179], v[184:187], v[58:61]
	v_mfma_f32_16x16x32_bf16 v[46:49], v[168:171], v[192:195], v[46:49]
	v_mfma_f32_16x16x32_bf16 v[34:37], v[176:179], v[192:195], v[34:37]
	v_mfma_f32_16x16x32_bf16 v[30:33], v[168:171], v[200:203], v[30:33]
	v_mfma_f32_16x16x32_bf16 v[18:21], v[176:179], v[200:203], v[18:21]
	v_mfma_f32_16x16x32_bf16 v[14:17], v[168:171], v[208:211], v[14:17]
	v_mfma_f32_16x16x32_bf16 v[10:13], v[176:179], v[208:211], v[10:13]
	v_mfma_f32_16x16x32_bf16 v[78:81], v[172:175], v[188:191], v[78:81]
	v_mfma_f32_16x16x32_bf16 v[58:61], v[180:183], v[188:191], v[58:61]
	v_mfma_f32_16x16x32_bf16 v[46:49], v[172:175], v[196:199], v[46:49]
	v_mfma_f32_16x16x32_bf16 v[34:37], v[180:183], v[196:199], v[34:37]
	v_mfma_f32_16x16x32_bf16 v[30:33], v[172:175], v[204:207], v[30:33]
	v_mfma_f32_16x16x32_bf16 v[18:21], v[180:183], v[204:207], v[18:21]
	v_mfma_f32_16x16x32_bf16 v[14:17], v[172:175], v[212:215], v[14:17]
	v_mfma_f32_16x16x32_bf16 v[10:13], v[180:183], v[212:215], v[10:13]
	s_barrier
	s_setprio 0
	s_add_i32 s26, s26, 2
	s_add_u32 s0, s0, 0x100
	s_addc_u32 s1, s1, 0
	s_add_u32 s14, s14, 0x100
	s_addc_u32 s15, s15, 0
	s_cmp_gt_u32 s26, 29
	s_cbranch_scc0 .LBB0_1110
	s_mov_b32 m0, s61
	s_nop 0
	global_load_lds_dwordx4 v130, s[100:101]
	s_mov_b32 m0, s62
	s_nop 0
	global_load_lds_dwordx4 v132, s[100:101]
	s_and_b64 vcc, exec, s[18:19]
	s_cbranch_vccz .LBB0_1113
	s_barrier

.LBB0_1261:
	ds_read_b128 v[132:135], v182
	ds_read_b128 v[136:139], v182 offset:1024
	ds_read_b128 v[140:143], v182 offset:2048
	ds_read_b128 v[144:147], v182 offset:3072
	ds_read_b128 v[148:151], v183
	ds_read_b128 v[170:173], v183 offset:1024
	ds_read_b128 v[174:177], v183 offset:2048
	ds_read_b128 v[178:181], v183 offset:3072
	s_add_u32 s38, s40, 0xfffe0080
	s_addc_u32 s39, s41, -1
	s_cmp_eq_u32 s69, 4
	s_cselect_b32 s43, s23, s39
	s_cselect_b32 s42, s31, s38
	s_cselect_b32 s39, s0, s27
	s_cselect_b32 s38, s66, s26
	s_cmp_eq_u32 s69, 0
	s_cbranch_scc1 .Lrb2_skip_38305
	s_mov_b32 m0, s52
	s_nop 0
	global_load_lds_dwordx4 v154, s[100:101]
	s_mov_b32 m0, s53
	s_nop 0
	global_load_lds_dwordx4 v158, s[100:101]
.Lrb2_skip_38305:
	s_mov_b32 m0, s59
	ds_read_b128 v[186:189], v184
	ds_read_b128 v[190:193], v184 offset:1024
	ds_read_b128 v[194:197], v184 offset:2048
	ds_read_b128 v[198:201], v184 offset:3072
	ds_read_b128 v[202:205], v184 offset:4096
	ds_read_b128 v[206:209], v184 offset:5120
	ds_read_b128 v[210:213], v184 offset:6144
	ds_read_b128 v[214:217], v184 offset:7168
	global_load_lds_dwordx4 v162, s[40:41]
	s_mov_b32 m0, s60
	s_nop 0
	global_load_lds_dwordx4 v164, s[40:41]
	s_waitcnt vmcnt(8)
	s_waitcnt lgkmcnt(0)
	s_setprio 1
	s_barrier
	v_mfma_f32_16x16x32_bf16 v[122:125], v[132:135], v[186:189], v[122:125]
	v_mfma_f32_16x16x32_bf16 v[118:121], v[140:143], v[186:189], v[118:121]
	v_mfma_f32_16x16x32_bf16 v[110:113], v[132:135], v[194:197], v[110:113]
	v_mfma_f32_16x16x32_bf16 v[106:109], v[140:143], v[194:197], v[106:109]
	v_mfma_f32_16x16x32_bf16 v[94:97], v[132:135], v[202:205], v[94:97]
	v_mfma_f32_16x16x32_bf16 v[90:93], v[140:143], v[202:205], v[90:93]
	v_mfma_f32_16x16x32_bf16 v[78:81], v[132:135], v[210:213], v[78:81]
	v_mfma_f32_16x16x32_bf16 v[74:77], v[140:143], v[210:213], v[74:77]
	v_mfma_f32_16x16x32_bf16 v[122:125], v[136:139], v[190:193], v[122:125]
	v_mfma_f32_16x16x32_bf16 v[118:121], v[144:147], v[190:193], v[118:121]
	v_mfma_f32_16x16x32_bf16 v[110:113], v[136:139], v[198:201], v[110:113]
	v_mfma_f32_16x16x32_bf16 v[106:109], v[144:147], v[198:201], v[106:109]
	v_mfma_f32_16x16x32_bf16 v[94:97], v[136:139], v[206:209], v[94:97]
	v_mfma_f32_16x16x32_bf16 v[90:93], v[144:147], v[206:209], v[90:93]
	v_mfma_f32_16x16x32_bf16 v[78:81], v[136:139], v[214:217], v[78:81]
	v_mfma_f32_16x16x32_bf16 v[74:77], v[144:147], v[214:217], v[74:77]
	s_setprio 0
	s_setprio 1
	v_mfma_f32_16x16x32_bf16 v[126:129], v[148:151], v[186:189], v[126:129]
	v_mfma_f32_16x16x32_bf16 v[114:117], v[174:177], v[186:189], v[114:117]
	v_mfma_f32_16x16x32_bf16 v[102:105], v[148:151], v[194:197], v[102:105]
	v_mfma_f32_16x16x32_bf16 v[98:101], v[174:177], v[194:197], v[98:101]
	v_mfma_f32_16x16x32_bf16 v[86:89], v[148:151], v[202:205], v[86:89]
	v_mfma_f32_16x16x32_bf16 v[82:85], v[174:177], v[202:205], v[82:85]
	v_mfma_f32_16x16x32_bf16 v[70:73], v[148:151], v[210:213], v[70:73]
	v_mfma_f32_16x16x32_bf16 v[66:69], v[174:177], v[210:213], v[66:69]
	v_mfma_f32_16x16x32_bf16 v[126:129], v[170:173], v[190:193], v[126:129]
	v_mfma_f32_16x16x32_bf16 v[114:117], v[178:181], v[190:193], v[114:117]
	v_mfma_f32_16x16x32_bf16 v[102:105], v[170:173], v[198:201], v[102:105]
	v_mfma_f32_16x16x32_bf16 v[98:101], v[178:181], v[198:201], v[98:101]
	v_mfma_f32_16x16x32_bf16 v[86:89], v[170:173], v[206:209], v[86:89]
	v_mfma_f32_16x16x32_bf16 v[82:85], v[178:181], v[206:209], v[82:85]
	v_mfma_f32_16x16x32_bf16 v[70:73], v[170:173], v[214:217], v[70:73]
	v_mfma_f32_16x16x32_bf16 v[66:69], v[178:181], v[214:217], v[66:69]
	s_barrier
	s_setprio 0
	s_mov_b32 m0, s61
	s_mov_b64 s[98:99], s[38:39]
	s_add_u32 s70, s38, 0x20000
	ds_read_b128 v[186:189], v184 offset:16384
	ds_read_b128 v[190:193], v184 offset:17408
	ds_read_b128 v[194:197], v184 offset:18432
	ds_read_b128 v[198:201], v184 offset:19456
	ds_read_b128 v[202:205], v184 offset:20480
	ds_read_b128 v[206:209], v184 offset:21504
	ds_read_b128 v[210:213], v184 offset:22528
	ds_read_b128 v[214:217], v184 offset:23552
	global_load_lds_dwordx4 v156, s[38:39]
	s_mov_b32 m0, s62
	s_addc_u32 s71, s39, 0
	global_load_lds_dwordx4 v160, s[38:39]
	s_mov_b32 m0, s67
	s_mov_b64 s[100:101], s[42:43]
	global_load_lds_dwordx4 v156, s[70:71]
	s_mov_b32 m0, s46
	s_nop 0
	global_load_lds_dwordx4 v160, s[70:71]
	s_waitcnt vmcnt(6)
	s_waitcnt lgkmcnt(0)
	s_setprio 1
	s_barrier
	v_mfma_f32_16x16x32_bf16 v[58:61], v[132:135], v[186:189], v[58:61]
	v_mfma_f32_16x16x32_bf16 v[54:57], v[140:143], v[186:189], v[54:57]
	v_mfma_f32_16x16x32_bf16 v[46:49], v[132:135], v[194:197], v[46:49]
	v_mfma_f32_16x16x32_bf16 v[42:45], v[140:143], v[194:197], v[42:45]
	v_mfma_f32_16x16x32_bf16 v[30:33], v[132:135], v[202:205], v[30:33]
	v_mfma_f32_16x16x32_bf16 v[26:29], v[140:143], v[202:205], v[26:29]
	v_mfma_f32_16x16x32_bf16 v[14:17], v[132:135], v[210:213], v[14:17]
	v_mfma_f32_16x16x32_bf16 v[10:13], v[140:143], v[210:213], v[10:13]
	v_mfma_f32_16x16x32_bf16 v[58:61], v[136:139], v[190:193], v[58:61]
	v_mfma_f32_16x16x32_bf16 v[54:57], v[144:147], v[190:193], v[54:57]
	v_mfma_f32_16x16x32_bf16 v[46:49], v[136:139], v[198:201], v[46:49]
	v_mfma_f32_16x16x32_bf16 v[42:45], v[144:147], v[198:201], v[42:45]
	v_mfma_f32_16x16x32_bf16 v[30:33], v[136:139], v[206:209], v[30:33]
	v_mfma_f32_16x16x32_bf16 v[26:29], v[144:147], v[206:209], v[26:29]
	v_mfma_f32_16x16x32_bf16 v[14:17], v[136:139], v[214:217], v[14:17]
	v_mfma_f32_16x16x32_bf16 v[10:13], v[144:147], v[214:217], v[10:13]
	s_setprio 0
	s_setprio 1
	v_mfma_f32_16x16x32_bf16 v[62:65], v[148:151], v[186:189], v[62:65]
	v_mfma_f32_16x16x32_bf16 v[50:53], v[174:177], v[186:189], v[50:53]
	v_mfma_f32_16x16x32_bf16 v[38:41], v[148:151], v[194:197], v[38:41]
	v_mfma_f32_16x16x32_bf16 v[34:37], v[174:177], v[194:197], v[34:37]
	v_mfma_f32_16x16x32_bf16 v[22:25], v[148:151], v[202:205], v[22:25]
	v_mfma_f32_16x16x32_bf16 v[18:21], v[174:177], v[202:205], v[18:21]
	v_mfma_f32_16x16x32_bf16 v[6:9], v[148:151], v[210:213], v[6:9]
	v_mfma_f32_16x16x32_bf16 v[2:5], v[174:177], v[210:213], v[2:5]
	v_mfma_f32_16x16x32_bf16 v[62:65], v[170:173], v[190:193], v[62:65]
	v_mfma_f32_16x16x32_bf16 v[50:53], v[178:181], v[190:193], v[50:53]
	v_mfma_f32_16x16x32_bf16 v[38:41], v[170:173], v[198:201], v[38:41]
	v_mfma_f32_16x16x32_bf16 v[34:37], v[178:181], v[198:201], v[34:37]
	v_mfma_f32_16x16x32_bf16 v[22:25], v[170:173], v[206:209], v[22:25]
	v_mfma_f32_16x16x32_bf16 v[18:21], v[178:181], v[206:209], v[18:21]
	v_mfma_f32_16x16x32_bf16 v[6:9], v[170:173], v[214:217], v[6:9]
	v_mfma_f32_16x16x32_bf16 v[2:5], v[178:181], v[214:217], v[2:5]
	s_barrier
;     ...
;         for (int t = 2; t < nt; t += 2) PG8_KITER(t);
	s_setprio 0
	ds_read_b128 v[132:135], v130
	ds_read_b128 v[136:139], v130 offset:1024
	ds_read_b128 v[140:143], v130 offset:2048
	ds_read_b128 v[144:147], v130 offset:3072
	ds_read_b128 v[148:151], v131
	ds_read_b128 v[170:173], v131 offset:1024
	ds_read_b128 v[174:177], v131 offset:2048
	ds_read_b128 v[178:181], v131 offset:3072
	s_add_u32 s42, s42, 0x20000
	s_addc_u32 s43, s43, 0
	s_mov_b32 m0, s48
	s_nop 0
	global_load_lds_dwordx4 v154, s[100:101]
	s_mov_b32 m0, s49
	s_nop 0
	global_load_lds_dwordx4 v158, s[100:101]
	s_mov_b32 m0, s50
	ds_read_b128 v[186:189], v184 offset:32768
	ds_read_b128 v[190:193], v184 offset:33792
	ds_read_b128 v[194:197], v184 offset:34816
	ds_read_b128 v[198:201], v184 offset:35840
	ds_read_b128 v[202:205], v184 offset:36864
	ds_read_b128 v[206:209], v184 offset:37888
	ds_read_b128 v[210:213], v184 offset:38912
	ds_read_b128 v[214:217], v184 offset:39936
	global_load_lds_dwordx4 v154, s[42:43]
	s_mov_b32 m0, s51
	s_nop 0
	global_load_lds_dwordx4 v158, s[42:43]
	s_waitcnt vmcnt(8)
	s_waitcnt lgkmcnt(0)
	s_setprio 1
	s_barrier
	v_mfma_f32_16x16x32_bf16 v[122:125], v[132:135], v[186:189], v[122:125]
	v_mfma_f32_16x16x32_bf16 v[118:121], v[140:143], v[186:189], v[118:121]
	v_mfma_f32_16x16x32_bf16 v[110:113], v[132:135], v[194:197], v[110:113]
	v_mfma_f32_16x16x32_bf16 v[106:109], v[140:143], v[194:197], v[106:109]
	v_mfma_f32_16x16x32_bf16 v[94:97], v[132:135], v[202:205], v[94:97]
	v_mfma_f32_16x16x32_bf16 v[90:93], v[140:143], v[202:205], v[90:93]
	v_mfma_f32_16x16x32_bf16 v[78:81], v[132:135], v[210:213], v[78:81]
	v_mfma_f32_16x16x32_bf16 v[74:77], v[140:143], v[210:213], v[74:77]
	v_mfma_f32_16x16x32_bf16 v[122:125], v[136:139], v[190:193], v[122:125]
	v_mfma_f32_16x16x32_bf16 v[118:121], v[144:147], v[190:193], v[118:121]
	v_mfma_f32_16x16x32_bf16 v[110:113], v[136:139], v[198:201], v[110:113]
	v_mfma_f32_16x16x32_bf16 v[106:109], v[144:147], v[198:201], v[106:109]
	v_mfma_f32_16x16x32_bf16 v[94:97], v[136:139], v[206:209], v[94:97]
	v_mfma_f32_16x16x32_bf16 v[90:93], v[144:147], v[206:209], v[90:93]
	v_mfma_f32_16x16x32_bf16 v[78:81], v[136:139], v[214:217], v[78:81]
	v_mfma_f32_16x16x32_bf16 v[74:77], v[144:147], v[214:217], v[74:77]
	s_setprio 0
	s_setprio 1
	v_mfma_f32_16x16x32_bf16 v[126:129], v[148:151], v[186:189], v[126:129]
	v_mfma_f32_16x16x32_bf16 v[114:117], v[174:177], v[186:189], v[114:117]
	v_mfma_f32_16x16x32_bf16 v[102:105], v[148:151], v[194:197], v[102:105]
	v_mfma_f32_16x16x32_bf16 v[98:101], v[174:177], v[194:197], v[98:101]
	v_mfma_f32_16x16x32_bf16 v[86:89], v[148:151], v[202:205], v[86:89]
	v_mfma_f32_16x16x32_bf16 v[82:85], v[174:177], v[202:205], v[82:85]
	v_mfma_f32_16x16x32_bf16 v[70:73], v[148:151], v[210:213], v[70:73]
	v_mfma_f32_16x16x32_bf16 v[66:69], v[174:177], v[210:213], v[66:69]
	v_mfma_f32_16x16x32_bf16 v[126:129], v[170:173], v[190:193], v[126:129]
	v_mfma_f32_16x16x32_bf16 v[114:117], v[178:181], v[190:193], v[114:117]
	v_mfma_f32_16x16x32_bf16 v[102:105], v[170:173], v[198:201], v[102:105]
	v_mfma_f32_16x16x32_bf16 v[98:101], v[178:181], v[198:201], v[98:101]
	v_mfma_f32_16x16x32_bf16 v[86:89], v[170:173], v[206:209], v[86:89]
	v_mfma_f32_16x16x32_bf16 v[82:85], v[178:181], v[206:209], v[82:85]
	v_mfma_f32_16x16x32_bf16 v[70:73], v[170:173], v[214:217], v[70:73]
	v_mfma_f32_16x16x32_bf16 v[66:69], v[178:181], v[214:217], v[66:69]
	s_barrier
	s_setprio 0
	s_mov_b32 m0, s47
	s_add_u32 s98, s98, 0x80
	s_addc_u32 s99, s99, 0
	s_add_u32 s100, s100, 0x80
	s_addc_u32 s101, s101, 0
	s_add_u32 s38, s38, 0x20080
	ds_read_b128 v[186:189], v184 offset:49152
	ds_read_b128 v[190:193], v184 offset:50176
	ds_read_b128 v[194:197], v184 offset:51200
	ds_read_b128 v[198:201], v184 offset:52224
	ds_read_b128 v[202:205], v184 offset:53248
	ds_read_b128 v[206:209], v184 offset:54272
	ds_read_b128 v[210:213], v184 offset:55296
	ds_read_b128 v[214:217], v184 offset:56320
	global_load_lds_dwordx4 v156, s[98:99]
	s_mov_b32 m0, s68
	s_addc_u32 s39, s39, 0
	global_load_lds_dwordx4 v160, s[98:99]
	s_mov_b32 m0, s56
	s_nop 0
	global_load_lds_dwordx4 v156, s[38:39]
	s_mov_b32 m0, s57
	s_nop 0
	global_load_lds_dwordx4 v160, s[38:39]
	s_waitcnt vmcnt(6)
	s_waitcnt lgkmcnt(0)
	s_setprio 1
	s_barrier
	v_mfma_f32_16x16x32_bf16 v[58:61], v[132:135], v[186:189], v[58:61]
	v_mfma_f32_16x16x32_bf16 v[54:57], v[140:143], v[186:189], v[54:57]
	v_mfma_f32_16x16x32_bf16 v[46:49], v[132:135], v[194:197], v[46:49]
	v_mfma_f32_16x16x32_bf16 v[42:45], v[140:143], v[194:197], v[42:45]
	v_mfma_f32_16x16x32_bf16 v[30:33], v[132:135], v[202:205], v[30:33]
	v_mfma_f32_16x16x32_bf16 v[26:29], v[140:143], v[202:205], v[26:29]
	v_mfma_f32_16x16x32_bf16 v[14:17], v[132:135], v[210:213], v[14:17]
	v_mfma_f32_16x16x32_bf16 v[10:13], v[140:143], v[210:213], v[10:13]
	v_mfma_f32_16x16x32_bf16 v[58:61], v[136:139], v[190:193], v[58:61]
	v_mfma_f32_16x16x32_bf16 v[54:57], v[144:147], v[190:193], v[54:57]
	v_mfma_f32_16x16x32_bf16 v[46:49], v[136:139], v[198:201], v[46:49]
	v_mfma_f32_16x16x32_bf16 v[42:45], v[144:147], v[198:201], v[42:45]
	v_mfma_f32_16x16x32_bf16 v[30:33], v[136:139], v[206:209], v[30:33]
	v_mfma_f32_16x16x32_bf16 v[26:29], v[144:147], v[206:209], v[26:29]
	v_mfma_f32_16x16x32_bf16 v[14:17], v[136:139], v[214:217], v[14:17]
	v_mfma_f32_16x16x32_bf16 v[10:13], v[144:147], v[214:217], v[10:13]
	s_setprio 0
	s_setprio 1
	v_mfma_f32_16x16x32_bf16 v[62:65], v[148:151], v[186:189], v[62:65]
	v_mfma_f32_16x16x32_bf16 v[50:53], v[174:177], v[186:189], v[50:53]
	v_mfma_f32_16x16x32_bf16 v[38:41], v[148:151], v[194:197], v[38:41]
	v_mfma_f32_16x16x32_bf16 v[34:37], v[174:177], v[194:197], v[34:37]
	v_mfma_f32_16x16x32_bf16 v[22:25], v[148:151], v[202:205], v[22:25]
	v_mfma_f32_16x16x32_bf16 v[18:21], v[174:177], v[202:205], v[18:21]
	v_mfma_f32_16x16x32_bf16 v[6:9], v[148:151], v[210:213], v[6:9]
	v_mfma_f32_16x16x32_bf16 v[2:5], v[174:177], v[210:213], v[2:5]
	v_mfma_f32_16x16x32_bf16 v[62:65], v[170:173], v[190:193], v[62:65]
	v_mfma_f32_16x16x32_bf16 v[50:53], v[178:181], v[190:193], v[50:53]
	v_mfma_f32_16x16x32_bf16 v[38:41], v[170:173], v[198:201], v[38:41]
	v_mfma_f32_16x16x32_bf16 v[34:37], v[178:181], v[198:201], v[34:37]
	v_mfma_f32_16x16x32_bf16 v[22:25], v[170:173], v[206:209], v[22:25]
	v_mfma_f32_16x16x32_bf16 v[18:21], v[178:181], v[206:209], v[18:21]
	v_mfma_f32_16x16x32_bf16 v[6:9], v[170:173], v[214:217], v[6:9]
	v_mfma_f32_16x16x32_bf16 v[2:5], v[178:181], v[214:217], v[2:5]
	s_barrier
	s_setprio 0
	s_add_i32 s69, s69, 2
	s_add_u32 s40, s40, 0x100
	s_addc_u32 s41, s41, 0
	s_add_u32 s26, s26, 0x100
	s_addc_u32 s27, s27, 0
	s_cmp_gt_u32 s69, 5
	s_cbranch_scc0 .LBB0_1261
	s_mov_b32 m0, s52
	s_nop 0
	global_load_lds_dwordx4 v154, s[100:101]
	s_mov_b32 m0, s53
	s_nop 0
	global_load_lds_dwordx4 v158, s[100:101]
	s_and_b64 vcc, exec, s[16:17]
	s_cbranch_vccz .LBB0_1264
	s_barrier

.LBB0_1345:
	ds_read_b128 v[156:159], v150
	ds_read_b128 v[160:163], v150 offset:1024
	ds_read_b128 v[164:167], v150 offset:2048
	ds_read_b128 v[168:171], v150 offset:3072
	ds_read_b128 v[172:175], v151
	ds_read_b128 v[176:179], v151 offset:1024
	ds_read_b128 v[180:183], v151 offset:2048
	ds_read_b128 v[184:187], v151 offset:3072
	s_add_u32 s38, s40, 0xfff00080
	s_addc_u32 s39, s41, -1
	s_cmp_eq_u32 s68, 60
	s_cselect_b32 s43, s1, s39
	s_cselect_b32 s42, s25, s38
	s_cselect_b32 s39, s8, s27
	s_cselect_b32 s38, s67, s26
	s_cmp_eq_u32 s68, 0
	s_cbranch_scc1 .Lrb2_skip_40588
	s_mov_b32 m0, s50
	s_nop 0
	global_load_lds_dwordx4 v136, s[100:101]
	s_mov_b32 m0, s51
	s_nop 0
	global_load_lds_dwordx4 v132, s[100:101]
.Lrb2_skip_40588:
	s_mov_b32 m0, s53
	ds_read_b128 v[188:191], v152
	ds_read_b128 v[192:195], v152 offset:1024
	ds_read_b128 v[196:199], v152 offset:2048
	ds_read_b128 v[200:203], v152 offset:3072
	ds_read_b128 v[204:207], v152 offset:4096
	ds_read_b128 v[208:211], v152 offset:5120
	ds_read_b128 v[212:215], v152 offset:6144
	ds_read_b128 v[216:219], v152 offset:7168
	global_load_lds_dwordx4 v0, s[40:41]
	s_mov_b32 m0, s54
	s_nop 0
	global_load_lds_dwordx4 v140, s[40:41]
	s_waitcnt vmcnt(8)
	s_waitcnt lgkmcnt(0)
	s_setprio 1
	s_barrier
	v_mfma_f32_16x16x32_bf16 v[118:121], v[156:159], v[188:191], v[118:121]
	v_mfma_f32_16x16x32_bf16 v[114:117], v[164:167], v[188:191], v[114:117]
	v_mfma_f32_16x16x32_bf16 v[102:105], v[156:159], v[196:199], v[102:105]
	v_mfma_f32_16x16x32_bf16 v[98:101], v[164:167], v[196:199], v[98:101]
	v_mfma_f32_16x16x32_bf16 v[86:89], v[156:159], v[204:207], v[86:89]
	v_mfma_f32_16x16x32_bf16 v[82:85], v[164:167], v[204:207], v[82:85]
	v_mfma_f32_16x16x32_bf16 v[66:69], v[156:159], v[212:215], v[66:69]
	v_mfma_f32_16x16x32_bf16 v[62:65], v[164:167], v[212:215], v[62:65]
	v_mfma_f32_16x16x32_bf16 v[118:121], v[160:163], v[192:195], v[118:121]
	v_mfma_f32_16x16x32_bf16 v[114:117], v[168:171], v[192:195], v[114:117]
	v_mfma_f32_16x16x32_bf16 v[102:105], v[160:163], v[200:203], v[102:105]
	v_mfma_f32_16x16x32_bf16 v[98:101], v[168:171], v[200:203], v[98:101]
	v_mfma_f32_16x16x32_bf16 v[86:89], v[160:163], v[208:211], v[86:89]
	v_mfma_f32_16x16x32_bf16 v[82:85], v[168:171], v[208:211], v[82:85]
	v_mfma_f32_16x16x32_bf16 v[66:69], v[160:163], v[216:219], v[66:69]
	v_mfma_f32_16x16x32_bf16 v[62:65], v[168:171], v[216:219], v[62:65]
	s_setprio 0
	s_setprio 1
	v_mfma_f32_16x16x32_bf16 v[126:129], v[172:175], v[188:191], v[126:129]
	v_mfma_f32_16x16x32_bf16 v[122:125], v[180:183], v[188:191], v[122:125]
	v_mfma_f32_16x16x32_bf16 v[110:113], v[172:175], v[196:199], v[110:113]
	v_mfma_f32_16x16x32_bf16 v[106:109], v[180:183], v[196:199], v[106:109]
	v_mfma_f32_16x16x32_bf16 v[94:97], v[172:175], v[204:207], v[94:97]
	v_mfma_f32_16x16x32_bf16 v[90:93], v[180:183], v[204:207], v[90:93]
	v_mfma_f32_16x16x32_bf16 v[78:81], v[172:175], v[212:215], v[78:81]
	v_mfma_f32_16x16x32_bf16 v[74:77], v[180:183], v[212:215], v[74:77]
	v_mfma_f32_16x16x32_bf16 v[126:129], v[176:179], v[192:195], v[126:129]
	v_mfma_f32_16x16x32_bf16 v[122:125], v[184:187], v[192:195], v[122:125]
	v_mfma_f32_16x16x32_bf16 v[110:113], v[176:179], v[200:203], v[110:113]
	v_mfma_f32_16x16x32_bf16 v[106:109], v[184:187], v[200:203], v[106:109]
	v_mfma_f32_16x16x32_bf16 v[94:97], v[176:179], v[208:211], v[94:97]
	v_mfma_f32_16x16x32_bf16 v[90:93], v[184:187], v[208:211], v[90:93]
	v_mfma_f32_16x16x32_bf16 v[78:81], v[176:179], v[216:219], v[78:81]
	v_mfma_f32_16x16x32_bf16 v[74:77], v[184:187], v[216:219], v[74:77]
	s_barrier
	s_setprio 0
	s_mov_b32 m0, s59
	s_mov_b64 s[98:99], s[38:39]
	s_add_u32 s70, s38, 0x100000
	ds_read_b128 v[188:191], v152 offset:16384
	ds_read_b128 v[192:195], v152 offset:17408
	ds_read_b128 v[196:199], v152 offset:18432
	ds_read_b128 v[200:203], v152 offset:19456
	ds_read_b128 v[204:207], v152 offset:20480
	ds_read_b128 v[208:211], v152 offset:21504
	ds_read_b128 v[212:215], v152 offset:22528
	ds_read_b128 v[216:219], v152 offset:23552
	global_load_lds_dwordx4 v134, s[38:39]
	s_mov_b32 m0, s60
	s_addc_u32 s71, s39, 0
	global_load_lds_dwordx4 v130, s[38:39]
	s_mov_b32 m0, s61
	s_mov_b64 s[100:101], s[42:43]
	global_load_lds_dwordx4 v134, s[70:71]
	s_mov_b32 m0, s62
	s_nop 0
	global_load_lds_dwordx4 v130, s[70:71]
	s_waitcnt vmcnt(6)
	s_waitcnt lgkmcnt(0)
	s_setprio 1
	s_barrier
	v_mfma_f32_16x16x32_bf16 v[54:57], v[156:159], v[188:191], v[54:57]
	v_mfma_f32_16x16x32_bf16 v[50:53], v[164:167], v[188:191], v[50:53]
	v_mfma_f32_16x16x32_bf16 v[38:41], v[156:159], v[196:199], v[38:41]
	v_mfma_f32_16x16x32_bf16 v[34:37], v[164:167], v[196:199], v[34:37]
	v_mfma_f32_16x16x32_bf16 v[22:25], v[156:159], v[204:207], v[22:25]
	v_mfma_f32_16x16x32_bf16 v[18:21], v[164:167], v[204:207], v[18:21]
	v_mfma_f32_16x16x32_bf16 v[6:9], v[156:159], v[212:215], v[6:9]
	v_mfma_f32_16x16x32_bf16 v[2:5], v[164:167], v[212:215], v[2:5]
	v_mfma_f32_16x16x32_bf16 v[54:57], v[160:163], v[192:195], v[54:57]
	v_mfma_f32_16x16x32_bf16 v[50:53], v[168:171], v[192:195], v[50:53]
	v_mfma_f32_16x16x32_bf16 v[38:41], v[160:163], v[200:203], v[38:41]
	v_mfma_f32_16x16x32_bf16 v[34:37], v[168:171], v[200:203], v[34:37]
	v_mfma_f32_16x16x32_bf16 v[22:25], v[160:163], v[208:211], v[22:25]
	v_mfma_f32_16x16x32_bf16 v[18:21], v[168:171], v[208:211], v[18:21]
	v_mfma_f32_16x16x32_bf16 v[6:9], v[160:163], v[216:219], v[6:9]
	v_mfma_f32_16x16x32_bf16 v[2:5], v[168:171], v[216:219], v[2:5]
	s_setprio 0
	s_setprio 1
	v_mfma_f32_16x16x32_bf16 v[70:73], v[172:175], v[188:191], v[70:73]
	v_mfma_f32_16x16x32_bf16 v[58:61], v[180:183], v[188:191], v[58:61]
	v_mfma_f32_16x16x32_bf16 v[46:49], v[172:175], v[196:199], v[46:49]
	v_mfma_f32_16x16x32_bf16 v[42:45], v[180:183], v[196:199], v[42:45]
	v_mfma_f32_16x16x32_bf16 v[30:33], v[172:175], v[204:207], v[30:33]
	v_mfma_f32_16x16x32_bf16 v[26:29], v[180:183], v[204:207], v[26:29]
	v_mfma_f32_16x16x32_bf16 v[14:17], v[172:175], v[212:215], v[14:17]
	v_mfma_f32_16x16x32_bf16 v[10:13], v[180:183], v[212:215], v[10:13]
	v_mfma_f32_16x16x32_bf16 v[70:73], v[176:179], v[192:195], v[70:73]
	v_mfma_f32_16x16x32_bf16 v[58:61], v[184:187], v[192:195], v[58:61]
	v_mfma_f32_16x16x32_bf16 v[46:49], v[176:179], v[200:203], v[46:49]
	v_mfma_f32_16x16x32_bf16 v[42:45], v[184:187], v[200:203], v[42:45]
	v_mfma_f32_16x16x32_bf16 v[30:33], v[176:179], v[208:211], v[30:33]
	v_mfma_f32_16x16x32_bf16 v[26:29], v[184:187], v[208:211], v[26:29]
	v_mfma_f32_16x16x32_bf16 v[14:17], v[176:179], v[216:219], v[14:17]
	v_mfma_f32_16x16x32_bf16 v[10:13], v[184:187], v[216:219], v[10:13]
	s_barrier
;     ...
;         for (int t = 2; t < nt; t += 2) PG8_KITER(t);
	s_setprio 0
	ds_read_b128 v[156:159], v154
	ds_read_b128 v[160:163], v154 offset:1024
	ds_read_b128 v[164:167], v154 offset:2048
	ds_read_b128 v[168:171], v154 offset:3072
	ds_read_b128 v[172:175], v146
	ds_read_b128 v[176:179], v146 offset:1024
	ds_read_b128 v[180:183], v146 offset:2048
	ds_read_b128 v[184:187], v146 offset:3072
	s_add_u32 s42, s42, 0x100000
	s_addc_u32 s43, s43, 0
	s_mov_b32 m0, s13
	s_nop 0
	global_load_lds_dwordx4 v136, s[100:101]
	s_mov_b32 m0, s33
	s_nop 0
	global_load_lds_dwordx4 v132, s[100:101]
	s_mov_b32 m0, s48
	ds_read_b128 v[188:191], v152 offset:32768
	ds_read_b128 v[192:195], v152 offset:33792
	ds_read_b128 v[196:199], v152 offset:34816
	ds_read_b128 v[200:203], v152 offset:35840
	ds_read_b128 v[204:207], v152 offset:36864
	ds_read_b128 v[208:211], v152 offset:37888
	ds_read_b128 v[212:215], v152 offset:38912
	ds_read_b128 v[216:219], v152 offset:39936
	global_load_lds_dwordx4 v136, s[42:43]
	s_mov_b32 m0, s49
	s_nop 0
	global_load_lds_dwordx4 v132, s[42:43]
	s_waitcnt vmcnt(8)
	s_waitcnt lgkmcnt(0)
	s_setprio 1
	s_barrier
	v_mfma_f32_16x16x32_bf16 v[118:121], v[156:159], v[188:191], v[118:121]
	v_mfma_f32_16x16x32_bf16 v[114:117], v[164:167], v[188:191], v[114:117]
	v_mfma_f32_16x16x32_bf16 v[102:105], v[156:159], v[196:199], v[102:105]
	v_mfma_f32_16x16x32_bf16 v[98:101], v[164:167], v[196:199], v[98:101]
	v_mfma_f32_16x16x32_bf16 v[86:89], v[156:159], v[204:207], v[86:89]
	v_mfma_f32_16x16x32_bf16 v[82:85], v[164:167], v[204:207], v[82:85]
	v_mfma_f32_16x16x32_bf16 v[66:69], v[156:159], v[212:215], v[66:69]
	v_mfma_f32_16x16x32_bf16 v[62:65], v[164:167], v[212:215], v[62:65]
	v_mfma_f32_16x16x32_bf16 v[118:121], v[160:163], v[192:195], v[118:121]
	v_mfma_f32_16x16x32_bf16 v[114:117], v[168:171], v[192:195], v[114:117]
	v_mfma_f32_16x16x32_bf16 v[102:105], v[160:163], v[200:203], v[102:105]
	v_mfma_f32_16x16x32_bf16 v[98:101], v[168:171], v[200:203], v[98:101]
	v_mfma_f32_16x16x32_bf16 v[86:89], v[160:163], v[208:211], v[86:89]
	v_mfma_f32_16x16x32_bf16 v[82:85], v[168:171], v[208:211], v[82:85]
	v_mfma_f32_16x16x32_bf16 v[66:69], v[160:163], v[216:219], v[66:69]
	v_mfma_f32_16x16x32_bf16 v[62:65], v[168:171], v[216:219], v[62:65]
	s_setprio 0
	s_setprio 1
	v_mfma_f32_16x16x32_bf16 v[126:129], v[172:175], v[188:191], v[126:129]
	v_mfma_f32_16x16x32_bf16 v[122:125], v[180:183], v[188:191], v[122:125]
	v_mfma_f32_16x16x32_bf16 v[110:113], v[172:175], v[196:199], v[110:113]
	v_mfma_f32_16x16x32_bf16 v[106:109], v[180:183], v[196:199], v[106:109]
	v_mfma_f32_16x16x32_bf16 v[94:97], v[172:175], v[204:207], v[94:97]
	v_mfma_f32_16x16x32_bf16 v[90:93], v[180:183], v[204:207], v[90:93]
	v_mfma_f32_16x16x32_bf16 v[78:81], v[172:175], v[212:215], v[78:81]
	v_mfma_f32_16x16x32_bf16 v[74:77], v[180:183], v[212:215], v[74:77]
	v_mfma_f32_16x16x32_bf16 v[126:129], v[176:179], v[192:195], v[126:129]
	v_mfma_f32_16x16x32_bf16 v[122:125], v[184:187], v[192:195], v[122:125]
	v_mfma_f32_16x16x32_bf16 v[110:113], v[176:179], v[200:203], v[110:113]
	v_mfma_f32_16x16x32_bf16 v[106:109], v[184:187], v[200:203], v[106:109]
	v_mfma_f32_16x16x32_bf16 v[94:97], v[176:179], v[208:211], v[94:97]
	v_mfma_f32_16x16x32_bf16 v[90:93], v[184:187], v[208:211], v[90:93]
	v_mfma_f32_16x16x32_bf16 v[78:81], v[176:179], v[216:219], v[78:81]
	v_mfma_f32_16x16x32_bf16 v[74:77], v[184:187], v[216:219], v[74:77]
	s_barrier
	s_setprio 0
	s_mov_b32 m0, s46
	s_add_u32 s98, s98, 0x80
	s_addc_u32 s99, s99, 0
	s_add_u32 s100, s100, 0x80
	s_addc_u32 s101, s101, 0
	s_add_u32 s38, s38, 0x100080
	ds_read_b128 v[188:191], v152 offset:49152
	ds_read_b128 v[192:195], v152 offset:50176
	ds_read_b128 v[196:199], v152 offset:51200
	ds_read_b128 v[200:203], v152 offset:52224
	ds_read_b128 v[204:207], v152 offset:53248
	ds_read_b128 v[208:211], v152 offset:54272
	ds_read_b128 v[212:215], v152 offset:55296
	ds_read_b128 v[216:219], v152 offset:56320
	global_load_lds_dwordx4 v134, s[98:99]
	s_mov_b32 m0, s47
	s_addc_u32 s39, s39, 0
	global_load_lds_dwordx4 v130, s[98:99]
	s_mov_b32 m0, s56
	s_nop 0
	global_load_lds_dwordx4 v134, s[38:39]
	s_mov_b32 m0, s57
	s_nop 0
	global_load_lds_dwordx4 v130, s[38:39]
	s_waitcnt vmcnt(6)
	s_waitcnt lgkmcnt(0)
	s_setprio 1
	s_barrier
	v_mfma_f32_16x16x32_bf16 v[54:57], v[156:159], v[188:191], v[54:57]
	v_mfma_f32_16x16x32_bf16 v[50:53], v[164:167], v[188:191], v[50:53]
	v_mfma_f32_16x16x32_bf16 v[38:41], v[156:159], v[196:199], v[38:41]
	v_mfma_f32_16x16x32_bf16 v[34:37], v[164:167], v[196:199], v[34:37]
	v_mfma_f32_16x16x32_bf16 v[22:25], v[156:159], v[204:207], v[22:25]
	v_mfma_f32_16x16x32_bf16 v[18:21], v[164:167], v[204:207], v[18:21]
	v_mfma_f32_16x16x32_bf16 v[6:9], v[156:159], v[212:215], v[6:9]
	v_mfma_f32_16x16x32_bf16 v[2:5], v[164:167], v[212:215], v[2:5]
	v_mfma_f32_16x16x32_bf16 v[54:57], v[160:163], v[192:195], v[54:57]
	v_mfma_f32_16x16x32_bf16 v[50:53], v[168:171], v[192:195], v[50:53]
	v_mfma_f32_16x16x32_bf16 v[38:41], v[160:163], v[200:203], v[38:41]
	v_mfma_f32_16x16x32_bf16 v[34:37], v[168:171], v[200:203], v[34:37]
	v_mfma_f32_16x16x32_bf16 v[22:25], v[160:163], v[208:211], v[22:25]
	v_mfma_f32_16x16x32_bf16 v[18:21], v[168:171], v[208:211], v[18:21]
	v_mfma_f32_16x16x32_bf16 v[6:9], v[160:163], v[216:219], v[6:9]
	v_mfma_f32_16x16x32_bf16 v[2:5], v[168:171], v[216:219], v[2:5]
	s_setprio 0
	s_setprio 1
	v_mfma_f32_16x16x32_bf16 v[70:73], v[172:175], v[188:191], v[70:73]
	v_mfma_f32_16x16x32_bf16 v[58:61], v[180:183], v[188:191], v[58:61]
	v_mfma_f32_16x16x32_bf16 v[46:49], v[172:175], v[196:199], v[46:49]
	v_mfma_f32_16x16x32_bf16 v[42:45], v[180:183], v[196:199], v[42:45]
	v_mfma_f32_16x16x32_bf16 v[30:33], v[172:175], v[204:207], v[30:33]
	v_mfma_f32_16x16x32_bf16 v[26:29], v[180:183], v[204:207], v[26:29]
	v_mfma_f32_16x16x32_bf16 v[14:17], v[172:175], v[212:215], v[14:17]
	v_mfma_f32_16x16x32_bf16 v[10:13], v[180:183], v[212:215], v[10:13]
	v_mfma_f32_16x16x32_bf16 v[70:73], v[176:179], v[192:195], v[70:73]
	v_mfma_f32_16x16x32_bf16 v[58:61], v[184:187], v[192:195], v[58:61]
	v_mfma_f32_16x16x32_bf16 v[46:49], v[176:179], v[200:203], v[46:49]
	v_mfma_f32_16x16x32_bf16 v[42:45], v[184:187], v[200:203], v[42:45]
	v_mfma_f32_16x16x32_bf16 v[30:33], v[176:179], v[208:211], v[30:33]
	v_mfma_f32_16x16x32_bf16 v[26:29], v[184:187], v[208:211], v[26:29]
	v_mfma_f32_16x16x32_bf16 v[14:17], v[176:179], v[216:219], v[14:17]
	v_mfma_f32_16x16x32_bf16 v[10:13], v[184:187], v[216:219], v[10:13]
	s_barrier
	s_setprio 0
	s_add_i32 s68, s68, 2
	s_add_u32 s40, s40, 0x100
	s_addc_u32 s41, s41, 0
	s_add_u32 s26, s26, 0x100
	s_addc_u32 s27, s27, 0
	s_cmp_gt_u32 s68, 61
	s_cbranch_scc0 .LBB0_1345
	s_mov_b32 m0, s50
	s_nop 0
	global_load_lds_dwordx4 v136, s[100:101]
	s_mov_b32 m0, s51
	s_nop 0
	global_load_lds_dwordx4 v132, s[100:101]
	s_and_b64 vcc, exec, s[18:19]
	s_cbranch_vccz .LBB0_1348
	s_barrier

.LBB0_1425:
	ds_read_b128 v[148:151], v152
	ds_read_b128 v[156:159], v152 offset:1024
	ds_read_b128 v[160:163], v152 offset:2048
	ds_read_b128 v[164:167], v152 offset:3072
	ds_read_b128 v[168:171], v153
	ds_read_b128 v[172:175], v153 offset:1024
	ds_read_b128 v[176:179], v153 offset:2048
	ds_read_b128 v[180:183], v153 offset:3072
	s_add_u32 s20, s18, 0x200
	s_addc_u32 s21, s19, 0
	s_cmpk_eq_i32 s57, 0xa8
	s_cselect_b32 s23, s5, s21
	s_cselect_b32 s22, s4, s20
	s_cselect_b32 s21, s17, s27
	s_cselect_b32 s20, s16, s26
	s_cmp_eq_u32 s57, 0
	s_cbranch_scc1 .Lrb2_skip_42710
	s_mov_b32 m0, s34
	s_nop 0
	global_load_lds_dwordx4 v130, s[100:101]
	s_mov_b32 m0, s35
	s_nop 0
	global_load_lds_dwordx4 v134, s[100:101]
.Lrb2_skip_42710:
	s_mov_b32 m0, s49
	ds_read_b128 v[184:187], v154
	ds_read_b128 v[188:191], v154 offset:1024
	ds_read_b128 v[192:195], v154 offset:2048
	ds_read_b128 v[196:199], v154 offset:3072
	ds_read_b128 v[200:203], v154 offset:4096
	ds_read_b128 v[204:207], v154 offset:5120
	ds_read_b128 v[208:211], v154 offset:6144
	ds_read_b128 v[212:215], v154 offset:7168
	global_load_lds_dwordx4 v138, s[18:19]
	s_mov_b32 m0, s50
	s_nop 0
	global_load_lds_dwordx4 v140, s[18:19]
	s_waitcnt vmcnt(8)
	s_waitcnt lgkmcnt(0)
	s_setprio 1
	s_barrier
	v_mfma_f32_16x16x32_bf16 v[126:129], v[148:151], v[184:187], v[126:129]
	v_mfma_f32_16x16x32_bf16 v[122:125], v[160:163], v[184:187], v[122:125]
	v_mfma_f32_16x16x32_bf16 v[110:113], v[148:151], v[192:195], v[110:113]
	v_mfma_f32_16x16x32_bf16 v[106:109], v[160:163], v[192:195], v[106:109]
	v_mfma_f32_16x16x32_bf16 v[94:97], v[148:151], v[200:203], v[94:97]
	v_mfma_f32_16x16x32_bf16 v[90:93], v[160:163], v[200:203], v[90:93]
	v_mfma_f32_16x16x32_bf16 v[78:81], v[148:151], v[208:211], v[78:81]
	v_mfma_f32_16x16x32_bf16 v[74:77], v[160:163], v[208:211], v[74:77]
	v_mfma_f32_16x16x32_bf16 v[126:129], v[156:159], v[188:191], v[126:129]
	v_mfma_f32_16x16x32_bf16 v[122:125], v[164:167], v[188:191], v[122:125]
	v_mfma_f32_16x16x32_bf16 v[110:113], v[156:159], v[196:199], v[110:113]
	v_mfma_f32_16x16x32_bf16 v[106:109], v[164:167], v[196:199], v[106:109]
	v_mfma_f32_16x16x32_bf16 v[94:97], v[156:159], v[204:207], v[94:97]
	v_mfma_f32_16x16x32_bf16 v[90:93], v[164:167], v[204:207], v[90:93]
	v_mfma_f32_16x16x32_bf16 v[78:81], v[156:159], v[212:215], v[78:81]
	v_mfma_f32_16x16x32_bf16 v[74:77], v[164:167], v[212:215], v[74:77]
	s_setprio 0
	s_setprio 1
	v_mfma_f32_16x16x32_bf16 v[118:121], v[168:171], v[184:187], v[118:121]
	v_mfma_f32_16x16x32_bf16 v[114:117], v[176:179], v[184:187], v[114:117]
	v_mfma_f32_16x16x32_bf16 v[102:105], v[168:171], v[192:195], v[102:105]
	v_mfma_f32_16x16x32_bf16 v[98:101], v[176:179], v[192:195], v[98:101]
	v_mfma_f32_16x16x32_bf16 v[86:89], v[168:171], v[200:203], v[86:89]
	v_mfma_f32_16x16x32_bf16 v[82:85], v[176:179], v[200:203], v[82:85]
	v_mfma_f32_16x16x32_bf16 v[70:73], v[168:171], v[208:211], v[70:73]
	v_mfma_f32_16x16x32_bf16 v[66:69], v[176:179], v[208:211], v[66:69]
	v_mfma_f32_16x16x32_bf16 v[118:121], v[172:175], v[188:191], v[118:121]
	v_mfma_f32_16x16x32_bf16 v[114:117], v[180:183], v[188:191], v[114:117]
	v_mfma_f32_16x16x32_bf16 v[102:105], v[172:175], v[196:199], v[102:105]
	v_mfma_f32_16x16x32_bf16 v[98:101], v[180:183], v[196:199], v[98:101]
	v_mfma_f32_16x16x32_bf16 v[86:89], v[172:175], v[204:207], v[86:89]
	v_mfma_f32_16x16x32_bf16 v[82:85], v[180:183], v[204:207], v[82:85]
	v_mfma_f32_16x16x32_bf16 v[70:73], v[172:175], v[212:215], v[70:73]
	v_mfma_f32_16x16x32_bf16 v[66:69], v[180:183], v[212:215], v[66:69]
	s_barrier
	s_setprio 0
	s_mov_b32 m0, s51
	s_mov_b64 s[98:99], s[20:21]
	s_add_u32 s58, s20, 0x2b0000
	ds_read_b128 v[184:187], v154 offset:16384
	ds_read_b128 v[188:191], v154 offset:17408
	ds_read_b128 v[192:195], v154 offset:18432
	ds_read_b128 v[196:199], v154 offset:19456
	ds_read_b128 v[200:203], v154 offset:20480
	ds_read_b128 v[204:207], v154 offset:21504
	ds_read_b128 v[208:211], v154 offset:22528
	ds_read_b128 v[212:215], v154 offset:23552
	global_load_lds_dwordx4 v132, s[20:21]
	s_mov_b32 m0, s52
	s_addc_u32 s59, s21, 0
	global_load_lds_dwordx4 v136, s[20:21]
	s_mov_b32 m0, s46
	s_mov_b64 s[100:101], s[22:23]
	global_load_lds_dwordx4 v132, s[58:59]
	s_mov_b32 m0, s47
	s_nop 0
	global_load_lds_dwordx4 v136, s[58:59]
	s_waitcnt vmcnt(6)
	s_waitcnt lgkmcnt(0)
	s_setprio 1
	s_barrier
	v_mfma_f32_16x16x32_bf16 v[62:65], v[148:151], v[184:187], v[62:65]
	v_mfma_f32_16x16x32_bf16 v[58:61], v[160:163], v[184:187], v[58:61]
	v_mfma_f32_16x16x32_bf16 v[46:49], v[148:151], v[192:195], v[46:49]
	v_mfma_f32_16x16x32_bf16 v[42:45], v[160:163], v[192:195], v[42:45]
	v_mfma_f32_16x16x32_bf16 v[30:33], v[148:151], v[200:203], v[30:33]
	v_mfma_f32_16x16x32_bf16 v[26:29], v[160:163], v[200:203], v[26:29]
	v_mfma_f32_16x16x32_bf16 v[14:17], v[148:151], v[208:211], v[14:17]
	v_mfma_f32_16x16x32_bf16 v[10:13], v[160:163], v[208:211], v[10:13]
	v_mfma_f32_16x16x32_bf16 v[62:65], v[156:159], v[188:191], v[62:65]
	v_mfma_f32_16x16x32_bf16 v[58:61], v[164:167], v[188:191], v[58:61]
	v_mfma_f32_16x16x32_bf16 v[46:49], v[156:159], v[196:199], v[46:49]
	v_mfma_f32_16x16x32_bf16 v[42:45], v[164:167], v[196:199], v[42:45]
	v_mfma_f32_16x16x32_bf16 v[30:33], v[156:159], v[204:207], v[30:33]
	v_mfma_f32_16x16x32_bf16 v[26:29], v[164:167], v[204:207], v[26:29]
	v_mfma_f32_16x16x32_bf16 v[14:17], v[156:159], v[212:215], v[14:17]
	v_mfma_f32_16x16x32_bf16 v[10:13], v[164:167], v[212:215], v[10:13]
	s_setprio 0
	s_setprio 1
	v_mfma_f32_16x16x32_bf16 v[54:57], v[168:171], v[184:187], v[54:57]
	v_mfma_f32_16x16x32_bf16 v[50:53], v[176:179], v[184:187], v[50:53]
	v_mfma_f32_16x16x32_bf16 v[38:41], v[168:171], v[192:195], v[38:41]
	v_mfma_f32_16x16x32_bf16 v[34:37], v[176:179], v[192:195], v[34:37]
	v_mfma_f32_16x16x32_bf16 v[22:25], v[168:171], v[200:203], v[22:25]
	v_mfma_f32_16x16x32_bf16 v[18:21], v[176:179], v[200:203], v[18:21]
	v_mfma_f32_16x16x32_bf16 v[6:9], v[168:171], v[208:211], v[6:9]
	v_mfma_f32_16x16x32_bf16 v[2:5], v[176:179], v[208:211], v[2:5]
	v_mfma_f32_16x16x32_bf16 v[54:57], v[172:175], v[188:191], v[54:57]
	v_mfma_f32_16x16x32_bf16 v[50:53], v[180:183], v[188:191], v[50:53]
	v_mfma_f32_16x16x32_bf16 v[38:41], v[172:175], v[196:199], v[38:41]
	v_mfma_f32_16x16x32_bf16 v[34:37], v[180:183], v[196:199], v[34:37]
	v_mfma_f32_16x16x32_bf16 v[22:25], v[172:175], v[204:207], v[22:25]
	v_mfma_f32_16x16x32_bf16 v[18:21], v[180:183], v[204:207], v[18:21]
	v_mfma_f32_16x16x32_bf16 v[6:9], v[172:175], v[212:215], v[6:9]
	v_mfma_f32_16x16x32_bf16 v[2:5], v[180:183], v[212:215], v[2:5]
	s_barrier
;     ...
;         for (int t = 2; t < nt; t += 2) PG8_KITER(t);
	s_setprio 0
	ds_read_b128 v[148:151], v146
	ds_read_b128 v[156:159], v146 offset:1024
	ds_read_b128 v[160:163], v146 offset:2048
	ds_read_b128 v[164:167], v146 offset:3072
	ds_read_b128 v[168:171], v147
	ds_read_b128 v[172:175], v147 offset:1024
	ds_read_b128 v[176:179], v147 offset:2048
	ds_read_b128 v[180:183], v147 offset:3072
	s_add_u32 s22, s22, 0x2b0000
	s_addc_u32 s23, s23, 0
	s_mov_b32 m0, s28
	s_nop 0
	global_load_lds_dwordx4 v130, s[100:101]
	s_mov_b32 m0, s29
	s_nop 0
	global_load_lds_dwordx4 v134, s[100:101]
	s_mov_b32 m0, s30
	ds_read_b128 v[184:187], v154 offset:32768
	ds_read_b128 v[188:191], v154 offset:33792
	ds_read_b128 v[192:195], v154 offset:34816
	ds_read_b128 v[196:199], v154 offset:35840
	ds_read_b128 v[200:203], v154 offset:36864
	ds_read_b128 v[204:207], v154 offset:37888
	ds_read_b128 v[208:211], v154 offset:38912
	ds_read_b128 v[212:215], v154 offset:39936
	global_load_lds_dwordx4 v130, s[22:23]
	s_mov_b32 m0, s31
	s_nop 0
	global_load_lds_dwordx4 v134, s[22:23]
	s_waitcnt vmcnt(8)
	s_waitcnt lgkmcnt(0)
	s_setprio 1
	s_barrier
	v_mfma_f32_16x16x32_bf16 v[126:129], v[148:151], v[184:187], v[126:129]
	v_mfma_f32_16x16x32_bf16 v[122:125], v[160:163], v[184:187], v[122:125]
	v_mfma_f32_16x16x32_bf16 v[110:113], v[148:151], v[192:195], v[110:113]
	v_mfma_f32_16x16x32_bf16 v[106:109], v[160:163], v[192:195], v[106:109]
	v_mfma_f32_16x16x32_bf16 v[94:97], v[148:151], v[200:203], v[94:97]
	v_mfma_f32_16x16x32_bf16 v[90:93], v[160:163], v[200:203], v[90:93]
	v_mfma_f32_16x16x32_bf16 v[78:81], v[148:151], v[208:211], v[78:81]
	v_mfma_f32_16x16x32_bf16 v[74:77], v[160:163], v[208:211], v[74:77]
	v_mfma_f32_16x16x32_bf16 v[126:129], v[156:159], v[188:191], v[126:129]
	v_mfma_f32_16x16x32_bf16 v[122:125], v[164:167], v[188:191], v[122:125]
	v_mfma_f32_16x16x32_bf16 v[110:113], v[156:159], v[196:199], v[110:113]
	v_mfma_f32_16x16x32_bf16 v[106:109], v[164:167], v[196:199], v[106:109]
	v_mfma_f32_16x16x32_bf16 v[94:97], v[156:159], v[204:207], v[94:97]
	v_mfma_f32_16x16x32_bf16 v[90:93], v[164:167], v[204:207], v[90:93]
	v_mfma_f32_16x16x32_bf16 v[78:81], v[156:159], v[212:215], v[78:81]
	v_mfma_f32_16x16x32_bf16 v[74:77], v[164:167], v[212:215], v[74:77]
	s_setprio 0
	s_setprio 1
	v_mfma_f32_16x16x32_bf16 v[118:121], v[168:171], v[184:187], v[118:121]
	v_mfma_f32_16x16x32_bf16 v[114:117], v[176:179], v[184:187], v[114:117]
	v_mfma_f32_16x16x32_bf16 v[102:105], v[168:171], v[192:195], v[102:105]
	v_mfma_f32_16x16x32_bf16 v[98:101], v[176:179], v[192:195], v[98:101]
	v_mfma_f32_16x16x32_bf16 v[86:89], v[168:171], v[200:203], v[86:89]
	v_mfma_f32_16x16x32_bf16 v[82:85], v[176:179], v[200:203], v[82:85]
	v_mfma_f32_16x16x32_bf16 v[70:73], v[168:171], v[208:211], v[70:73]
	v_mfma_f32_16x16x32_bf16 v[66:69], v[176:179], v[208:211], v[66:69]
	v_mfma_f32_16x16x32_bf16 v[118:121], v[172:175], v[188:191], v[118:121]
	v_mfma_f32_16x16x32_bf16 v[114:117], v[180:183], v[188:191], v[114:117]
	v_mfma_f32_16x16x32_bf16 v[102:105], v[172:175], v[196:199], v[102:105]
	v_mfma_f32_16x16x32_bf16 v[98:101], v[180:183], v[196:199], v[98:101]
	v_mfma_f32_16x16x32_bf16 v[86:89], v[172:175], v[204:207], v[86:89]
	v_mfma_f32_16x16x32_bf16 v[82:85], v[180:183], v[204:207], v[82:85]
	v_mfma_f32_16x16x32_bf16 v[70:73], v[172:175], v[212:215], v[70:73]
	v_mfma_f32_16x16x32_bf16 v[66:69], v[180:183], v[212:215], v[66:69]
	s_barrier
	s_setprio 0
	s_mov_b32 m0, s53
	s_add_u32 s98, s98, 0x80
	s_addc_u32 s99, s99, 0
	s_add_u32 s100, s100, 0x80
	s_addc_u32 s101, s101, 0
	s_add_u32 s20, s20, 0x2b0080
	ds_read_b128 v[184:187], v154 offset:49152
	ds_read_b128 v[188:191], v154 offset:50176
	ds_read_b128 v[192:195], v154 offset:51200
	ds_read_b128 v[196:199], v154 offset:52224
	ds_read_b128 v[200:203], v154 offset:53248
	ds_read_b128 v[204:207], v154 offset:54272
	ds_read_b128 v[208:211], v154 offset:55296
	ds_read_b128 v[212:215], v154 offset:56320
	global_load_lds_dwordx4 v132, s[98:99]
	s_mov_b32 m0, s54
	s_addc_u32 s21, s21, 0
	global_load_lds_dwordx4 v136, s[98:99]
	s_mov_b32 m0, s55
	s_nop 0
	global_load_lds_dwordx4 v132, s[20:21]
	s_mov_b32 m0, s56
	s_nop 0
	global_load_lds_dwordx4 v136, s[20:21]
	s_waitcnt vmcnt(6)
	s_waitcnt lgkmcnt(0)
	s_setprio 1
	s_barrier
	v_mfma_f32_16x16x32_bf16 v[62:65], v[148:151], v[184:187], v[62:65]
	v_mfma_f32_16x16x32_bf16 v[58:61], v[160:163], v[184:187], v[58:61]
	v_mfma_f32_16x16x32_bf16 v[46:49], v[148:151], v[192:195], v[46:49]
	v_mfma_f32_16x16x32_bf16 v[42:45], v[160:163], v[192:195], v[42:45]
	v_mfma_f32_16x16x32_bf16 v[30:33], v[148:151], v[200:203], v[30:33]
	v_mfma_f32_16x16x32_bf16 v[26:29], v[160:163], v[200:203], v[26:29]
	v_mfma_f32_16x16x32_bf16 v[14:17], v[148:151], v[208:211], v[14:17]
	v_mfma_f32_16x16x32_bf16 v[10:13], v[160:163], v[208:211], v[10:13]
	v_mfma_f32_16x16x32_bf16 v[62:65], v[156:159], v[188:191], v[62:65]
	v_mfma_f32_16x16x32_bf16 v[58:61], v[164:167], v[188:191], v[58:61]
	v_mfma_f32_16x16x32_bf16 v[46:49], v[156:159], v[196:199], v[46:49]
	v_mfma_f32_16x16x32_bf16 v[42:45], v[164:167], v[196:199], v[42:45]
	v_mfma_f32_16x16x32_bf16 v[30:33], v[156:159], v[204:207], v[30:33]
	v_mfma_f32_16x16x32_bf16 v[26:29], v[164:167], v[204:207], v[26:29]
	v_mfma_f32_16x16x32_bf16 v[14:17], v[156:159], v[212:215], v[14:17]
	v_mfma_f32_16x16x32_bf16 v[10:13], v[164:167], v[212:215], v[10:13]
	s_setprio 0
	s_setprio 1
	v_mfma_f32_16x16x32_bf16 v[54:57], v[168:171], v[184:187], v[54:57]
	v_mfma_f32_16x16x32_bf16 v[50:53], v[176:179], v[184:187], v[50:53]
	v_mfma_f32_16x16x32_bf16 v[38:41], v[168:171], v[192:195], v[38:41]
	v_mfma_f32_16x16x32_bf16 v[34:37], v[176:179], v[192:195], v[34:37]
	v_mfma_f32_16x16x32_bf16 v[22:25], v[168:171], v[200:203], v[22:25]
	v_mfma_f32_16x16x32_bf16 v[18:21], v[176:179], v[200:203], v[18:21]
	v_mfma_f32_16x16x32_bf16 v[6:9], v[168:171], v[208:211], v[6:9]
	v_mfma_f32_16x16x32_bf16 v[2:5], v[176:179], v[208:211], v[2:5]
	v_mfma_f32_16x16x32_bf16 v[54:57], v[172:175], v[188:191], v[54:57]
	v_mfma_f32_16x16x32_bf16 v[50:53], v[180:183], v[188:191], v[50:53]
	v_mfma_f32_16x16x32_bf16 v[38:41], v[172:175], v[196:199], v[38:41]
	v_mfma_f32_16x16x32_bf16 v[34:37], v[180:183], v[196:199], v[34:37]
	v_mfma_f32_16x16x32_bf16 v[22:25], v[172:175], v[204:207], v[22:25]
	v_mfma_f32_16x16x32_bf16 v[18:21], v[180:183], v[204:207], v[18:21]
	v_mfma_f32_16x16x32_bf16 v[6:9], v[172:175], v[212:215], v[6:9]
	v_mfma_f32_16x16x32_bf16 v[2:5], v[180:183], v[212:215], v[2:5]
	s_barrier
	s_setprio 0
	s_add_i32 s57, s57, 2
	s_add_u32 s18, s18, 0x100
	s_addc_u32 s19, s19, 0
	s_add_u32 s26, s26, 0x100
	s_addc_u32 s27, s27, 0
	s_cmpk_gt_u32 s57, 0xa9
	s_cbranch_scc0 .LBB0_1425
	s_mov_b32 m0, s34
	s_nop 0
	global_load_lds_dwordx4 v130, s[100:101]
	s_mov_b32 m0, s35
	s_nop 0
	global_load_lds_dwordx4 v134, s[100:101]
	s_and_b64 vcc, exec, s[10:11]
	s_cbranch_vccz .LBB0_1428
	s_barrier
